# k22 + K-loop R phases: v0 copy moves removed (LDS-DMA takes the offset VGPR directly)
# speedup vs baseline: 1.0063x; 1.0039x over previous
.LBB0_444:
	s_add_u32 s48, s46, 0x20080
	s_addc_u32 s49, s47, 0
	s_add_u32 s25, s50, 0x100
	s_addc_u32 s64, s51, 0
	s_mov_b32 s65, -2
	s_add_u32 s46, s48, 0xfffe0080
	s_addc_u32 s47, s49, -1
	s_add_i32 s84, 0, 0x10000
	s_cmp_eq_u32 s65, 4
	s_cselect_b32 s47, s15, s47
	s_cselect_b32 s46, s14, s46
	v_add_u32_e32 v0, s84, v147
	s_cselect_b32 s51, s17, s64
	s_cselect_b32 s50, s16, s25
	s_add_i32 s86, 0, 0x14000
	ds_read_b128 v[150:153], v0
	ds_read_b128 v[154:157], v0 offset:1024
	ds_read_b128 v[158:161], v0 offset:2048
	ds_read_b128 v[162:165], v0 offset:3072
	v_add_u32_e32 v0, s86, v147
	ds_read_b128 v[166:169], v0
	ds_read_b128 v[170:173], v0 offset:1024
	ds_read_b128 v[174:177], v0 offset:2048
	ds_read_b128 v[178:181], v0 offset:3072
	ds_read_b128 v[182:185], v148
	ds_read_b128 v[186:189], v148 offset:1024
	ds_read_b128 v[190:193], v148 offset:2048
	ds_read_b128 v[194:197], v148 offset:3072
	ds_read_b128 v[198:201], v148 offset:4096
	ds_read_b128 v[202:205], v148 offset:5120
	ds_read_b128 v[206:209], v148 offset:6144
	ds_read_b128 v[210:213], v148 offset:7168
	s_add_i32 m0, s59, 0xc000
	s_nop 0
	global_load_lds_dwordx4 v132, s[48:49]
	s_add_i32 m0, s59, 0xe000
	s_nop 0
	global_load_lds_dwordx4 v133, s[48:49]
	s_waitcnt vmcnt(8)
	s_waitcnt lgkmcnt(0)
	s_barrier
	s_setprio 1
	s_waitcnt lgkmcnt(0)
	v_mfma_i32_16x16x64_i8 v[126:129], v[150:153], v[182:185], 0
	v_mfma_i32_16x16x64_i8 v[122:125], v[158:161], v[182:185], 0
	v_mfma_i32_16x16x64_i8 v[110:113], v[150:153], v[190:193], 0
	v_mfma_i32_16x16x64_i8 v[106:109], v[158:161], v[190:193], 0
	v_mfma_i32_16x16x64_i8 v[94:97], v[150:153], v[198:201], 0
	v_mfma_i32_16x16x64_i8 v[90:93], v[158:161], v[198:201], 0
	v_mfma_i32_16x16x64_i8 v[78:81], v[150:153], v[206:209], 0
	v_mfma_i32_16x16x64_i8 v[74:77], v[158:161], v[206:209], 0
	v_mfma_i32_16x16x64_i8 v[126:129], v[154:157], v[186:189], v[126:129]
	v_mfma_i32_16x16x64_i8 v[122:125], v[162:165], v[186:189], v[122:125]
	v_mfma_i32_16x16x64_i8 v[110:113], v[154:157], v[194:197], v[110:113]
	v_mfma_i32_16x16x64_i8 v[106:109], v[162:165], v[194:197], v[106:109]
	v_mfma_i32_16x16x64_i8 v[94:97], v[154:157], v[202:205], v[94:97]
	v_mfma_i32_16x16x64_i8 v[90:93], v[162:165], v[202:205], v[90:93]
	v_mfma_i32_16x16x64_i8 v[78:81], v[154:157], v[210:213], v[78:81]
	v_mfma_i32_16x16x64_i8 v[74:77], v[162:165], v[210:213], v[74:77]
	s_setprio 0
	s_setprio 1
	v_mfma_i32_16x16x64_i8 v[118:121], v[166:169], v[182:185], 0
	v_mfma_i32_16x16x64_i8 v[114:117], v[174:177], v[182:185], 0
	v_mfma_i32_16x16x64_i8 v[102:105], v[166:169], v[190:193], 0
	v_mfma_i32_16x16x64_i8 v[98:101], v[174:177], v[190:193], 0
	v_mfma_i32_16x16x64_i8 v[86:89], v[166:169], v[198:201], 0
	v_mfma_i32_16x16x64_i8 v[82:85], v[174:177], v[198:201], 0
	v_mfma_i32_16x16x64_i8 v[70:73], v[166:169], v[206:209], 0
	v_mfma_i32_16x16x64_i8 v[66:69], v[174:177], v[206:209], 0
	v_mfma_i32_16x16x64_i8 v[118:121], v[170:173], v[186:189], v[118:121]
	v_mfma_i32_16x16x64_i8 v[114:117], v[178:181], v[186:189], v[114:117]
	v_mfma_i32_16x16x64_i8 v[102:105], v[170:173], v[194:197], v[102:105]
	v_mfma_i32_16x16x64_i8 v[98:101], v[178:181], v[194:197], v[98:101]
	v_mfma_i32_16x16x64_i8 v[86:89], v[170:173], v[202:205], v[86:89]
	v_mfma_i32_16x16x64_i8 v[82:85], v[178:181], v[202:205], v[82:85]
	v_mfma_i32_16x16x64_i8 v[70:73], v[170:173], v[210:213], v[70:73]
	v_mfma_i32_16x16x64_i8 v[66:69], v[178:181], v[210:213], v[66:69]
	s_setprio 0
	s_barrier
	s_add_i32 s84, s84, s40
	ds_read_b128 v[182:185], v148 offset:16384
	ds_read_b128 v[186:189], v148 offset:17408
	ds_read_b128 v[190:193], v148 offset:18432
	ds_read_b128 v[194:197], v148 offset:19456
	ds_read_b128 v[198:201], v148 offset:20480
	ds_read_b128 v[202:205], v148 offset:21504
	ds_read_b128 v[206:209], v148 offset:22528
	ds_read_b128 v[210:213], v148 offset:23552
	s_mov_b32 m0, s84
	s_nop 0
	global_load_lds_dwordx4 v143, s[50:51]
	s_add_i32 m0, s84, 0x2000
	s_add_u32 s84, s50, 0x20000
	global_load_lds_dwordx4 v144, s[50:51]
	s_addc_u32 s85, s51, 0
	s_add_i32 s86, s86, s40
	s_mov_b32 m0, s86
	s_nop 0
	global_load_lds_dwordx4 v143, s[84:85]
	s_add_i32 m0, s86, 0x2000
	s_nop 0
	global_load_lds_dwordx4 v144, s[84:85]
	s_mov_b32 m0, s59
	s_nop 0
	global_load_lds_dwordx4 v132, s[46:47]
	s_mov_b32 m0, s60
	s_nop 0
	global_load_lds_dwordx4 v133, s[46:47]
	s_waitcnt vmcnt(8)
	s_waitcnt lgkmcnt(0)
	s_barrier
	s_setprio 1
	s_waitcnt lgkmcnt(0)
	v_mfma_i32_16x16x64_i8 v[62:65], v[150:153], v[182:185], 0
	v_mfma_i32_16x16x64_i8 v[58:61], v[158:161], v[182:185], 0
	v_mfma_i32_16x16x64_i8 v[46:49], v[150:153], v[190:193], 0
	v_mfma_i32_16x16x64_i8 v[42:45], v[158:161], v[190:193], 0
	v_mfma_i32_16x16x64_i8 v[30:33], v[150:153], v[198:201], 0
	v_mfma_i32_16x16x64_i8 v[26:29], v[158:161], v[198:201], 0
	v_mfma_i32_16x16x64_i8 v[14:17], v[150:153], v[206:209], 0
	v_mfma_i32_16x16x64_i8 v[10:13], v[158:161], v[206:209], 0
	v_mfma_i32_16x16x64_i8 v[62:65], v[154:157], v[186:189], v[62:65]
	v_mfma_i32_16x16x64_i8 v[58:61], v[162:165], v[186:189], v[58:61]
	v_mfma_i32_16x16x64_i8 v[46:49], v[154:157], v[194:197], v[46:49]
	v_mfma_i32_16x16x64_i8 v[42:45], v[162:165], v[194:197], v[42:45]
	v_mfma_i32_16x16x64_i8 v[30:33], v[154:157], v[202:205], v[30:33]
	v_mfma_i32_16x16x64_i8 v[26:29], v[162:165], v[202:205], v[26:29]
	v_mfma_i32_16x16x64_i8 v[14:17], v[154:157], v[210:213], v[14:17]
	v_mfma_i32_16x16x64_i8 v[10:13], v[162:165], v[210:213], v[10:13]
	s_setprio 0
	s_setprio 1
	v_mfma_i32_16x16x64_i8 v[54:57], v[166:169], v[182:185], 0
	v_mfma_i32_16x16x64_i8 v[50:53], v[174:177], v[182:185], 0
	v_mfma_i32_16x16x64_i8 v[38:41], v[166:169], v[190:193], 0
	v_mfma_i32_16x16x64_i8 v[34:37], v[174:177], v[190:193], 0
	v_mfma_i32_16x16x64_i8 v[22:25], v[166:169], v[198:201], 0
	v_mfma_i32_16x16x64_i8 v[18:21], v[174:177], v[198:201], 0
	v_mfma_i32_16x16x64_i8 v[6:9], v[166:169], v[206:209], 0
	v_mfma_i32_16x16x64_i8 v[2:5], v[174:177], v[206:209], 0
	v_mfma_i32_16x16x64_i8 v[54:57], v[170:173], v[186:189], v[54:57]
	v_mfma_i32_16x16x64_i8 v[50:53], v[178:181], v[186:189], v[50:53]
	v_mfma_i32_16x16x64_i8 v[38:41], v[170:173], v[194:197], v[38:41]
	v_mfma_i32_16x16x64_i8 v[34:37], v[178:181], v[194:197], v[34:37]
	v_mfma_i32_16x16x64_i8 v[22:25], v[170:173], v[202:205], v[22:25]
	v_mfma_i32_16x16x64_i8 v[18:21], v[178:181], v[202:205], v[18:21]
	v_mfma_i32_16x16x64_i8 v[6:9], v[170:173], v[210:213], v[6:9]
	v_mfma_i32_16x16x64_i8 v[2:5], v[178:181], v[210:213], v[2:5]
	s_setprio 0
	s_barrier
	s_add_i32 s86, 0, 0x18000
	v_add_u32_e32 v0, s86, v147
	s_add_i32 s87, 0, 0x1c000
	ds_read_b128 v[150:153], v0
	ds_read_b128 v[154:157], v0 offset:1024
	ds_read_b128 v[158:161], v0 offset:2048
	ds_read_b128 v[162:165], v0 offset:3072
	v_add_u32_e32 v0, s87, v147
	ds_read_b128 v[166:169], v0
	ds_read_b128 v[170:173], v0 offset:1024
	ds_read_b128 v[174:177], v0 offset:2048
	ds_read_b128 v[178:181], v0 offset:3072
	s_add_u32 s84, s46, 0x20000
	s_mov_b32 m0, s61
	ds_read_b128 v[182:185], v148 offset:32768
	ds_read_b128 v[186:189], v148 offset:33792
	ds_read_b128 v[190:193], v148 offset:34816
	ds_read_b128 v[194:197], v148 offset:35840
	ds_read_b128 v[198:201], v148 offset:36864
	ds_read_b128 v[202:205], v148 offset:37888
	ds_read_b128 v[206:209], v148 offset:38912
	ds_read_b128 v[210:213], v148 offset:39936
	s_addc_u32 s85, s47, 0
	s_nop 0
	global_load_lds_dwordx4 v132, s[84:85]
	s_mov_b32 m0, s66
	s_nop 0
	global_load_lds_dwordx4 v133, s[84:85]
	s_waitcnt vmcnt(8)
	s_waitcnt lgkmcnt(0)
	s_barrier
	s_setprio 1
	s_waitcnt lgkmcnt(0)
	v_mfma_i32_16x16x64_i8 v[126:129], v[150:153], v[182:185], v[126:129]
	v_mfma_i32_16x16x64_i8 v[122:125], v[158:161], v[182:185], v[122:125]
	v_mfma_i32_16x16x64_i8 v[110:113], v[150:153], v[190:193], v[110:113]
	v_mfma_i32_16x16x64_i8 v[106:109], v[158:161], v[190:193], v[106:109]
	v_mfma_i32_16x16x64_i8 v[94:97], v[150:153], v[198:201], v[94:97]
	v_mfma_i32_16x16x64_i8 v[90:93], v[158:161], v[198:201], v[90:93]
	v_mfma_i32_16x16x64_i8 v[78:81], v[150:153], v[206:209], v[78:81]
	v_mfma_i32_16x16x64_i8 v[74:77], v[158:161], v[206:209], v[74:77]
	v_mfma_i32_16x16x64_i8 v[126:129], v[154:157], v[186:189], v[126:129]
	v_mfma_i32_16x16x64_i8 v[122:125], v[162:165], v[186:189], v[122:125]
	v_mfma_i32_16x16x64_i8 v[110:113], v[154:157], v[194:197], v[110:113]
	v_mfma_i32_16x16x64_i8 v[106:109], v[162:165], v[194:197], v[106:109]
	v_mfma_i32_16x16x64_i8 v[94:97], v[154:157], v[202:205], v[94:97]
	v_mfma_i32_16x16x64_i8 v[90:93], v[162:165], v[202:205], v[90:93]
	v_mfma_i32_16x16x64_i8 v[78:81], v[154:157], v[210:213], v[78:81]
	v_mfma_i32_16x16x64_i8 v[74:77], v[162:165], v[210:213], v[74:77]
	s_setprio 0
	s_setprio 1
	v_mfma_i32_16x16x64_i8 v[118:121], v[166:169], v[182:185], v[118:121]
	v_mfma_i32_16x16x64_i8 v[114:117], v[174:177], v[182:185], v[114:117]
	v_mfma_i32_16x16x64_i8 v[102:105], v[166:169], v[190:193], v[102:105]
	v_mfma_i32_16x16x64_i8 v[98:101], v[174:177], v[190:193], v[98:101]
	v_mfma_i32_16x16x64_i8 v[86:89], v[166:169], v[198:201], v[86:89]
	v_mfma_i32_16x16x64_i8 v[82:85], v[174:177], v[198:201], v[82:85]
	v_mfma_i32_16x16x64_i8 v[70:73], v[166:169], v[206:209], v[70:73]
	v_mfma_i32_16x16x64_i8 v[66:69], v[174:177], v[206:209], v[66:69]
	v_mfma_i32_16x16x64_i8 v[118:121], v[170:173], v[186:189], v[118:121]
	v_mfma_i32_16x16x64_i8 v[114:117], v[178:181], v[186:189], v[114:117]
	v_mfma_i32_16x16x64_i8 v[102:105], v[170:173], v[194:197], v[102:105]
	v_mfma_i32_16x16x64_i8 v[98:101], v[178:181], v[194:197], v[98:101]
	v_mfma_i32_16x16x64_i8 v[86:89], v[170:173], v[202:205], v[86:89]
	v_mfma_i32_16x16x64_i8 v[82:85], v[178:181], v[202:205], v[82:85]
	v_mfma_i32_16x16x64_i8 v[70:73], v[170:173], v[210:213], v[70:73]
	v_mfma_i32_16x16x64_i8 v[66:69], v[178:181], v[210:213], v[66:69]
	s_setprio 0
	s_barrier
	ds_read_b128 v[182:185], v148 offset:49152
	ds_read_b128 v[186:189], v148 offset:50176
	ds_read_b128 v[190:193], v148 offset:51200
	ds_read_b128 v[194:197], v148 offset:52224
	ds_read_b128 v[198:201], v148 offset:53248
	ds_read_b128 v[202:205], v148 offset:54272
	ds_read_b128 v[206:209], v148 offset:55296
	ds_read_b128 v[210:213], v148 offset:56320
	s_add_i32 s84, s86, s40
	s_add_u32 s100, s50, s38
	s_addc_u32 s101, s51, s39
	s_mov_b32 m0, s84
	s_nop 0
	global_load_lds_dwordx4 v143, s[100:101]
	s_add_i32 m0, s84, 0x2000
	s_nop 0
	s_add_u32 s50, s50, 0x20080
	s_addc_u32 s51, s51, 0
	s_add_i32 s84, s87, s40
	global_load_lds_dwordx4 v144, s[100:101]
	s_mov_b32 m0, s84
	s_nop 0
	global_load_lds_dwordx4 v143, s[50:51]
	s_add_i32 m0, s84, 0x2000
	s_nop 0
	global_load_lds_dwordx4 v144, s[50:51]
	s_mov_b32 m0, s75
	s_add_u32 s100, s46, s38
	s_addc_u32 s101, s47, s39
	v_mov_b32_e32 v0, v133
	global_load_lds_dwordx4 v132, s[100:101]
	s_mov_b32 m0, s78
	s_nop 0
	global_load_lds_dwordx4 v133, s[100:101]
	s_waitcnt vmcnt(8)
	s_waitcnt lgkmcnt(0)
	s_barrier
	s_setprio 1
	s_waitcnt lgkmcnt(0)
	v_mfma_i32_16x16x64_i8 v[62:65], v[150:153], v[182:185], v[62:65]
	v_mfma_i32_16x16x64_i8 v[58:61], v[158:161], v[182:185], v[58:61]
	v_mfma_i32_16x16x64_i8 v[46:49], v[150:153], v[190:193], v[46:49]
	v_mfma_i32_16x16x64_i8 v[42:45], v[158:161], v[190:193], v[42:45]
	v_mfma_i32_16x16x64_i8 v[30:33], v[150:153], v[198:201], v[30:33]
	v_mfma_i32_16x16x64_i8 v[26:29], v[158:161], v[198:201], v[26:29]
	v_mfma_i32_16x16x64_i8 v[14:17], v[150:153], v[206:209], v[14:17]
	v_mfma_i32_16x16x64_i8 v[10:13], v[158:161], v[206:209], v[10:13]
	v_mfma_i32_16x16x64_i8 v[62:65], v[154:157], v[186:189], v[62:65]
	v_mfma_i32_16x16x64_i8 v[58:61], v[162:165], v[186:189], v[58:61]
	v_mfma_i32_16x16x64_i8 v[46:49], v[154:157], v[194:197], v[46:49]
	v_mfma_i32_16x16x64_i8 v[42:45], v[162:165], v[194:197], v[42:45]
	v_mfma_i32_16x16x64_i8 v[30:33], v[154:157], v[202:205], v[30:33]
	v_mfma_i32_16x16x64_i8 v[26:29], v[162:165], v[202:205], v[26:29]
	v_mfma_i32_16x16x64_i8 v[14:17], v[154:157], v[210:213], v[14:17]
	v_mfma_i32_16x16x64_i8 v[10:13], v[162:165], v[210:213], v[10:13]
	s_setprio 0
	s_setprio 1
	v_mfma_i32_16x16x64_i8 v[54:57], v[166:169], v[182:185], v[54:57]
	v_mfma_i32_16x16x64_i8 v[50:53], v[174:177], v[182:185], v[50:53]
	v_mfma_i32_16x16x64_i8 v[38:41], v[166:169], v[190:193], v[38:41]
	v_mfma_i32_16x16x64_i8 v[34:37], v[174:177], v[190:193], v[34:37]
	v_mfma_i32_16x16x64_i8 v[22:25], v[166:169], v[198:201], v[22:25]
	v_mfma_i32_16x16x64_i8 v[18:21], v[174:177], v[198:201], v[18:21]
	v_mfma_i32_16x16x64_i8 v[6:9], v[166:169], v[206:209], v[6:9]
	v_mfma_i32_16x16x64_i8 v[2:5], v[174:177], v[206:209], v[2:5]
	v_mfma_i32_16x16x64_i8 v[54:57], v[170:173], v[186:189], v[54:57]
	v_mfma_i32_16x16x64_i8 v[50:53], v[178:181], v[186:189], v[50:53]
	v_mfma_i32_16x16x64_i8 v[38:41], v[170:173], v[194:197], v[38:41]
	v_mfma_i32_16x16x64_i8 v[34:37], v[178:181], v[194:197], v[34:37]
	v_mfma_i32_16x16x64_i8 v[22:25], v[170:173], v[202:205], v[22:25]
	v_mfma_i32_16x16x64_i8 v[18:21], v[178:181], v[202:205], v[18:21]
	v_mfma_i32_16x16x64_i8 v[6:9], v[170:173], v[210:213], v[6:9]
	v_mfma_i32_16x16x64_i8 v[2:5], v[178:181], v[210:213], v[2:5]
	s_setprio 0
	s_barrier
	s_add_i32 s65, s65, 2
	s_add_u32 s48, s48, 0x100
	s_addc_u32 s49, s49, 0
	s_add_u32 s25, s25, 0x100
	s_addc_u32 s64, s64, 0
	s_cmp_gt_u32 s65, 5
	s_cbranch_scc0 .LBB0_445
	s_branch .Lpeel_exit_445
.LBB0_445:
	s_add_u32 s46, s48, 0xfffe0080
	s_addc_u32 s47, s49, -1
	s_add_i32 s84, 0, 0x10000
	s_cmp_eq_u32 s65, 4
	s_cselect_b32 s47, s15, s47
	s_cselect_b32 s46, s14, s46
	v_add_u32_e32 v0, s84, v147
	s_cselect_b32 s51, s17, s64
	s_cselect_b32 s50, s16, s25
	s_add_i32 s86, 0, 0x14000
	ds_read_b128 v[150:153], v0
	ds_read_b128 v[154:157], v0 offset:1024
	ds_read_b128 v[158:161], v0 offset:2048
	ds_read_b128 v[162:165], v0 offset:3072
	v_add_u32_e32 v0, s86, v147
	ds_read_b128 v[166:169], v0
	ds_read_b128 v[170:173], v0 offset:1024
	ds_read_b128 v[174:177], v0 offset:2048
	ds_read_b128 v[178:181], v0 offset:3072
	ds_read_b128 v[182:185], v148
	ds_read_b128 v[186:189], v148 offset:1024
	ds_read_b128 v[190:193], v148 offset:2048
	ds_read_b128 v[194:197], v148 offset:3072
	ds_read_b128 v[198:201], v148 offset:4096
	ds_read_b128 v[202:205], v148 offset:5120
	ds_read_b128 v[206:209], v148 offset:6144
	ds_read_b128 v[210:213], v148 offset:7168
	s_add_i32 m0, s59, 0xc000
	s_nop 0
	global_load_lds_dwordx4 v132, s[48:49]
	s_add_i32 m0, s59, 0xe000
	s_nop 0
	global_load_lds_dwordx4 v133, s[48:49]
	s_waitcnt vmcnt(8)
	s_waitcnt lgkmcnt(0)
	s_barrier
	s_setprio 1
	s_waitcnt lgkmcnt(0)
	v_mfma_i32_16x16x64_i8 v[126:129], v[150:153], v[182:185], v[126:129]
	v_mfma_i32_16x16x64_i8 v[122:125], v[158:161], v[182:185], v[122:125]
	v_mfma_i32_16x16x64_i8 v[110:113], v[150:153], v[190:193], v[110:113]
	v_mfma_i32_16x16x64_i8 v[106:109], v[158:161], v[190:193], v[106:109]
	v_mfma_i32_16x16x64_i8 v[94:97], v[150:153], v[198:201], v[94:97]
	v_mfma_i32_16x16x64_i8 v[90:93], v[158:161], v[198:201], v[90:93]
	v_mfma_i32_16x16x64_i8 v[78:81], v[150:153], v[206:209], v[78:81]
	v_mfma_i32_16x16x64_i8 v[74:77], v[158:161], v[206:209], v[74:77]
	v_mfma_i32_16x16x64_i8 v[126:129], v[154:157], v[186:189], v[126:129]
	v_mfma_i32_16x16x64_i8 v[122:125], v[162:165], v[186:189], v[122:125]
	v_mfma_i32_16x16x64_i8 v[110:113], v[154:157], v[194:197], v[110:113]
	v_mfma_i32_16x16x64_i8 v[106:109], v[162:165], v[194:197], v[106:109]
	v_mfma_i32_16x16x64_i8 v[94:97], v[154:157], v[202:205], v[94:97]
	v_mfma_i32_16x16x64_i8 v[90:93], v[162:165], v[202:205], v[90:93]
	v_mfma_i32_16x16x64_i8 v[78:81], v[154:157], v[210:213], v[78:81]
	v_mfma_i32_16x16x64_i8 v[74:77], v[162:165], v[210:213], v[74:77]
	s_setprio 0
	s_setprio 1
	v_mfma_i32_16x16x64_i8 v[118:121], v[166:169], v[182:185], v[118:121]
	v_mfma_i32_16x16x64_i8 v[114:117], v[174:177], v[182:185], v[114:117]
	v_mfma_i32_16x16x64_i8 v[102:105], v[166:169], v[190:193], v[102:105]
	v_mfma_i32_16x16x64_i8 v[98:101], v[174:177], v[190:193], v[98:101]
	v_mfma_i32_16x16x64_i8 v[86:89], v[166:169], v[198:201], v[86:89]
	v_mfma_i32_16x16x64_i8 v[82:85], v[174:177], v[198:201], v[82:85]
	v_mfma_i32_16x16x64_i8 v[70:73], v[166:169], v[206:209], v[70:73]
	v_mfma_i32_16x16x64_i8 v[66:69], v[174:177], v[206:209], v[66:69]
	v_mfma_i32_16x16x64_i8 v[118:121], v[170:173], v[186:189], v[118:121]
	v_mfma_i32_16x16x64_i8 v[114:117], v[178:181], v[186:189], v[114:117]
	v_mfma_i32_16x16x64_i8 v[102:105], v[170:173], v[194:197], v[102:105]
	v_mfma_i32_16x16x64_i8 v[98:101], v[178:181], v[194:197], v[98:101]
	v_mfma_i32_16x16x64_i8 v[86:89], v[170:173], v[202:205], v[86:89]
	v_mfma_i32_16x16x64_i8 v[82:85], v[178:181], v[202:205], v[82:85]
	v_mfma_i32_16x16x64_i8 v[70:73], v[170:173], v[210:213], v[70:73]
	v_mfma_i32_16x16x64_i8 v[66:69], v[178:181], v[210:213], v[66:69]
	s_setprio 0
	s_barrier
	s_add_i32 s84, s84, s40
	ds_read_b128 v[182:185], v148 offset:16384
	ds_read_b128 v[186:189], v148 offset:17408
	ds_read_b128 v[190:193], v148 offset:18432
	ds_read_b128 v[194:197], v148 offset:19456
	ds_read_b128 v[198:201], v148 offset:20480
	ds_read_b128 v[202:205], v148 offset:21504
	ds_read_b128 v[206:209], v148 offset:22528
	ds_read_b128 v[210:213], v148 offset:23552
	s_mov_b32 m0, s84
	s_nop 0
	global_load_lds_dwordx4 v143, s[50:51]
	s_add_i32 m0, s84, 0x2000
	s_add_u32 s84, s50, 0x20000
	global_load_lds_dwordx4 v144, s[50:51]
	s_addc_u32 s85, s51, 0
	s_add_i32 s86, s86, s40
	s_mov_b32 m0, s86
	s_nop 0
	global_load_lds_dwordx4 v143, s[84:85]
	s_add_i32 m0, s86, 0x2000
	s_nop 0
	global_load_lds_dwordx4 v144, s[84:85]
	s_mov_b32 m0, s59
	s_nop 0
	global_load_lds_dwordx4 v132, s[46:47]
	s_mov_b32 m0, s60
	s_nop 0
	global_load_lds_dwordx4 v133, s[46:47]
	s_waitcnt vmcnt(8)
	s_waitcnt lgkmcnt(0)
	s_barrier
	s_setprio 1
	s_waitcnt lgkmcnt(0)
	v_mfma_i32_16x16x64_i8 v[62:65], v[150:153], v[182:185], v[62:65]
	v_mfma_i32_16x16x64_i8 v[58:61], v[158:161], v[182:185], v[58:61]
	v_mfma_i32_16x16x64_i8 v[46:49], v[150:153], v[190:193], v[46:49]
	v_mfma_i32_16x16x64_i8 v[42:45], v[158:161], v[190:193], v[42:45]
	v_mfma_i32_16x16x64_i8 v[30:33], v[150:153], v[198:201], v[30:33]
	v_mfma_i32_16x16x64_i8 v[26:29], v[158:161], v[198:201], v[26:29]
	v_mfma_i32_16x16x64_i8 v[14:17], v[150:153], v[206:209], v[14:17]
	v_mfma_i32_16x16x64_i8 v[10:13], v[158:161], v[206:209], v[10:13]
	v_mfma_i32_16x16x64_i8 v[62:65], v[154:157], v[186:189], v[62:65]
	v_mfma_i32_16x16x64_i8 v[58:61], v[162:165], v[186:189], v[58:61]
	v_mfma_i32_16x16x64_i8 v[46:49], v[154:157], v[194:197], v[46:49]
	v_mfma_i32_16x16x64_i8 v[42:45], v[162:165], v[194:197], v[42:45]
	v_mfma_i32_16x16x64_i8 v[30:33], v[154:157], v[202:205], v[30:33]
	v_mfma_i32_16x16x64_i8 v[26:29], v[162:165], v[202:205], v[26:29]
	v_mfma_i32_16x16x64_i8 v[14:17], v[154:157], v[210:213], v[14:17]
	v_mfma_i32_16x16x64_i8 v[10:13], v[162:165], v[210:213], v[10:13]
	s_setprio 0
	s_setprio 1
	v_mfma_i32_16x16x64_i8 v[54:57], v[166:169], v[182:185], v[54:57]
	v_mfma_i32_16x16x64_i8 v[50:53], v[174:177], v[182:185], v[50:53]
	v_mfma_i32_16x16x64_i8 v[38:41], v[166:169], v[190:193], v[38:41]
	v_mfma_i32_16x16x64_i8 v[34:37], v[174:177], v[190:193], v[34:37]
	v_mfma_i32_16x16x64_i8 v[22:25], v[166:169], v[198:201], v[22:25]
	v_mfma_i32_16x16x64_i8 v[18:21], v[174:177], v[198:201], v[18:21]
	v_mfma_i32_16x16x64_i8 v[6:9], v[166:169], v[206:209], v[6:9]
	v_mfma_i32_16x16x64_i8 v[2:5], v[174:177], v[206:209], v[2:5]
	v_mfma_i32_16x16x64_i8 v[54:57], v[170:173], v[186:189], v[54:57]
	v_mfma_i32_16x16x64_i8 v[50:53], v[178:181], v[186:189], v[50:53]
	v_mfma_i32_16x16x64_i8 v[38:41], v[170:173], v[194:197], v[38:41]
	v_mfma_i32_16x16x64_i8 v[34:37], v[178:181], v[194:197], v[34:37]
	v_mfma_i32_16x16x64_i8 v[22:25], v[170:173], v[202:205], v[22:25]
	v_mfma_i32_16x16x64_i8 v[18:21], v[178:181], v[202:205], v[18:21]
	v_mfma_i32_16x16x64_i8 v[6:9], v[170:173], v[210:213], v[6:9]
	v_mfma_i32_16x16x64_i8 v[2:5], v[178:181], v[210:213], v[2:5]
	s_setprio 0
	s_barrier
	s_add_i32 s86, 0, 0x18000
	v_add_u32_e32 v0, s86, v147
	s_add_i32 s87, 0, 0x1c000
	ds_read_b128 v[150:153], v0
	ds_read_b128 v[154:157], v0 offset:1024
	ds_read_b128 v[158:161], v0 offset:2048
	ds_read_b128 v[162:165], v0 offset:3072
	v_add_u32_e32 v0, s87, v147
	ds_read_b128 v[166:169], v0
	ds_read_b128 v[170:173], v0 offset:1024
	ds_read_b128 v[174:177], v0 offset:2048
	ds_read_b128 v[178:181], v0 offset:3072
	s_add_u32 s84, s46, 0x20000
	s_mov_b32 m0, s61
	ds_read_b128 v[182:185], v148 offset:32768
	ds_read_b128 v[186:189], v148 offset:33792
	ds_read_b128 v[190:193], v148 offset:34816
	ds_read_b128 v[194:197], v148 offset:35840
	ds_read_b128 v[198:201], v148 offset:36864
	ds_read_b128 v[202:205], v148 offset:37888
	ds_read_b128 v[206:209], v148 offset:38912
	ds_read_b128 v[210:213], v148 offset:39936
	s_addc_u32 s85, s47, 0
	s_nop 0
	global_load_lds_dwordx4 v132, s[84:85]
	s_mov_b32 m0, s66
	s_nop 0
	global_load_lds_dwordx4 v133, s[84:85]
	s_waitcnt vmcnt(8)
	s_waitcnt lgkmcnt(0)
	s_barrier
	s_setprio 1
	s_waitcnt lgkmcnt(0)
	v_mfma_i32_16x16x64_i8 v[126:129], v[150:153], v[182:185], v[126:129]
	v_mfma_i32_16x16x64_i8 v[122:125], v[158:161], v[182:185], v[122:125]
	v_mfma_i32_16x16x64_i8 v[110:113], v[150:153], v[190:193], v[110:113]
	v_mfma_i32_16x16x64_i8 v[106:109], v[158:161], v[190:193], v[106:109]
	v_mfma_i32_16x16x64_i8 v[94:97], v[150:153], v[198:201], v[94:97]
	v_mfma_i32_16x16x64_i8 v[90:93], v[158:161], v[198:201], v[90:93]
	v_mfma_i32_16x16x64_i8 v[78:81], v[150:153], v[206:209], v[78:81]
	v_mfma_i32_16x16x64_i8 v[74:77], v[158:161], v[206:209], v[74:77]
	v_mfma_i32_16x16x64_i8 v[126:129], v[154:157], v[186:189], v[126:129]
	v_mfma_i32_16x16x64_i8 v[122:125], v[162:165], v[186:189], v[122:125]
	v_mfma_i32_16x16x64_i8 v[110:113], v[154:157], v[194:197], v[110:113]
	v_mfma_i32_16x16x64_i8 v[106:109], v[162:165], v[194:197], v[106:109]
	v_mfma_i32_16x16x64_i8 v[94:97], v[154:157], v[202:205], v[94:97]
	v_mfma_i32_16x16x64_i8 v[90:93], v[162:165], v[202:205], v[90:93]
	v_mfma_i32_16x16x64_i8 v[78:81], v[154:157], v[210:213], v[78:81]
	v_mfma_i32_16x16x64_i8 v[74:77], v[162:165], v[210:213], v[74:77]
	s_setprio 0
	s_setprio 1
	v_mfma_i32_16x16x64_i8 v[118:121], v[166:169], v[182:185], v[118:121]
	v_mfma_i32_16x16x64_i8 v[114:117], v[174:177], v[182:185], v[114:117]
	v_mfma_i32_16x16x64_i8 v[102:105], v[166:169], v[190:193], v[102:105]
	v_mfma_i32_16x16x64_i8 v[98:101], v[174:177], v[190:193], v[98:101]
	v_mfma_i32_16x16x64_i8 v[86:89], v[166:169], v[198:201], v[86:89]
	v_mfma_i32_16x16x64_i8 v[82:85], v[174:177], v[198:201], v[82:85]
	v_mfma_i32_16x16x64_i8 v[70:73], v[166:169], v[206:209], v[70:73]
	v_mfma_i32_16x16x64_i8 v[66:69], v[174:177], v[206:209], v[66:69]
	v_mfma_i32_16x16x64_i8 v[118:121], v[170:173], v[186:189], v[118:121]
	v_mfma_i32_16x16x64_i8 v[114:117], v[178:181], v[186:189], v[114:117]
	v_mfma_i32_16x16x64_i8 v[102:105], v[170:173], v[194:197], v[102:105]
	v_mfma_i32_16x16x64_i8 v[98:101], v[178:181], v[194:197], v[98:101]
	v_mfma_i32_16x16x64_i8 v[86:89], v[170:173], v[202:205], v[86:89]
	v_mfma_i32_16x16x64_i8 v[82:85], v[178:181], v[202:205], v[82:85]
	v_mfma_i32_16x16x64_i8 v[70:73], v[170:173], v[210:213], v[70:73]
	v_mfma_i32_16x16x64_i8 v[66:69], v[178:181], v[210:213], v[66:69]
	s_setprio 0
	s_barrier
	ds_read_b128 v[182:185], v148 offset:49152
	ds_read_b128 v[186:189], v148 offset:50176
	ds_read_b128 v[190:193], v148 offset:51200
	ds_read_b128 v[194:197], v148 offset:52224
	ds_read_b128 v[198:201], v148 offset:53248
	ds_read_b128 v[202:205], v148 offset:54272
	ds_read_b128 v[206:209], v148 offset:55296
	ds_read_b128 v[210:213], v148 offset:56320
	s_add_i32 s84, s86, s40
	s_add_u32 s100, s50, s38
	s_addc_u32 s101, s51, s39
	s_mov_b32 m0, s84
	s_nop 0
	global_load_lds_dwordx4 v143, s[100:101]
	s_add_i32 m0, s84, 0x2000
	s_nop 0
	s_add_u32 s50, s50, 0x20080
	s_addc_u32 s51, s51, 0
	s_add_i32 s84, s87, s40
	global_load_lds_dwordx4 v144, s[100:101]
	s_mov_b32 m0, s84
	s_nop 0
	global_load_lds_dwordx4 v143, s[50:51]
	s_add_i32 m0, s84, 0x2000
	s_nop 0
	global_load_lds_dwordx4 v144, s[50:51]
	s_mov_b32 m0, s75
	s_add_u32 s100, s46, s38
	s_addc_u32 s101, s47, s39
	v_mov_b32_e32 v0, v133
	global_load_lds_dwordx4 v132, s[100:101]
	s_mov_b32 m0, s78
	s_nop 0
	global_load_lds_dwordx4 v133, s[100:101]
	s_waitcnt vmcnt(8)
	s_waitcnt lgkmcnt(0)
	s_barrier
	s_setprio 1
	s_waitcnt lgkmcnt(0)
	v_mfma_i32_16x16x64_i8 v[62:65], v[150:153], v[182:185], v[62:65]
	v_mfma_i32_16x16x64_i8 v[58:61], v[158:161], v[182:185], v[58:61]
	v_mfma_i32_16x16x64_i8 v[46:49], v[150:153], v[190:193], v[46:49]
	v_mfma_i32_16x16x64_i8 v[42:45], v[158:161], v[190:193], v[42:45]
	v_mfma_i32_16x16x64_i8 v[30:33], v[150:153], v[198:201], v[30:33]
	v_mfma_i32_16x16x64_i8 v[26:29], v[158:161], v[198:201], v[26:29]
	v_mfma_i32_16x16x64_i8 v[14:17], v[150:153], v[206:209], v[14:17]
	v_mfma_i32_16x16x64_i8 v[10:13], v[158:161], v[206:209], v[10:13]
	v_mfma_i32_16x16x64_i8 v[62:65], v[154:157], v[186:189], v[62:65]
	v_mfma_i32_16x16x64_i8 v[58:61], v[162:165], v[186:189], v[58:61]
	v_mfma_i32_16x16x64_i8 v[46:49], v[154:157], v[194:197], v[46:49]
	v_mfma_i32_16x16x64_i8 v[42:45], v[162:165], v[194:197], v[42:45]
	v_mfma_i32_16x16x64_i8 v[30:33], v[154:157], v[202:205], v[30:33]
	v_mfma_i32_16x16x64_i8 v[26:29], v[162:165], v[202:205], v[26:29]
	v_mfma_i32_16x16x64_i8 v[14:17], v[154:157], v[210:213], v[14:17]
	v_mfma_i32_16x16x64_i8 v[10:13], v[162:165], v[210:213], v[10:13]
	s_setprio 0
	s_setprio 1
	v_mfma_i32_16x16x64_i8 v[54:57], v[166:169], v[182:185], v[54:57]
	v_mfma_i32_16x16x64_i8 v[50:53], v[174:177], v[182:185], v[50:53]
	v_mfma_i32_16x16x64_i8 v[38:41], v[166:169], v[190:193], v[38:41]
	v_mfma_i32_16x16x64_i8 v[34:37], v[174:177], v[190:193], v[34:37]
	v_mfma_i32_16x16x64_i8 v[22:25], v[166:169], v[198:201], v[22:25]
	v_mfma_i32_16x16x64_i8 v[18:21], v[174:177], v[198:201], v[18:21]
	v_mfma_i32_16x16x64_i8 v[6:9], v[166:169], v[206:209], v[6:9]
	v_mfma_i32_16x16x64_i8 v[2:5], v[174:177], v[206:209], v[2:5]
	v_mfma_i32_16x16x64_i8 v[54:57], v[170:173], v[186:189], v[54:57]
	v_mfma_i32_16x16x64_i8 v[50:53], v[178:181], v[186:189], v[50:53]
	v_mfma_i32_16x16x64_i8 v[38:41], v[170:173], v[194:197], v[38:41]
	v_mfma_i32_16x16x64_i8 v[34:37], v[178:181], v[194:197], v[34:37]
	v_mfma_i32_16x16x64_i8 v[22:25], v[170:173], v[202:205], v[22:25]
	v_mfma_i32_16x16x64_i8 v[18:21], v[178:181], v[202:205], v[18:21]
	v_mfma_i32_16x16x64_i8 v[6:9], v[170:173], v[210:213], v[6:9]
	v_mfma_i32_16x16x64_i8 v[2:5], v[178:181], v[210:213], v[2:5]
	s_setprio 0
	s_barrier
	s_add_i32 s65, s65, 2
	s_add_u32 s48, s48, 0x100
	s_addc_u32 s49, s49, 0
	s_add_u32 s25, s25, 0x100
	s_addc_u32 s64, s64, 0
	s_cmp_gt_u32 s65, 5
	s_cbranch_scc0 .LBB0_445

.LBB0_626:
	s_add_u32 s58, s14, s50
	s_addc_u32 s59, s15, s51
	s_add_u32 s46, s58, 0x100
	s_addc_u32 s47, s59, 0
	s_and_b64 s[4:5], s[48:49], exec
	s_cselect_b32 s47, s15, s47
	s_cselect_b32 s46, s14, s46
	s_add_u32 s4, s16, s50
	s_addc_u32 s5, s17, s51
	s_add_u32 s50, s4, 0x100
	s_addc_u32 s51, s5, 0
	s_add_i32 s78, 0, 0x10000
	s_and_b64 s[4:5], s[48:49], exec
	s_cselect_b32 s49, s17, s51
	s_cselect_b32 s48, s16, s50
	s_add_i32 s4, 0, 0x14000
	s_add_u32 s96, s58, 0x80080
	s_addc_u32 s97, s59, 0
	s_add_i32 s82, s78, s42
	s_add_i32 m0, s43, 0xc000
	s_add_i32 s5, s43, 0xe000
	s_add_i32 s76, s82, 0x2000
	v_add_u32_e32 v0, s78, v136
	s_add_u32 s94, s48, 0x40000
	ds_read_b128 v[138:141], v0
	ds_read_b128 v[142:145], v0 offset:1024
	ds_read_b128 v[146:149], v0 offset:2048
	ds_read_b128 v[150:153], v0 offset:3072
	v_add_u32_e32 v0, s4, v136
	s_addc_u32 s95, s49, 0
	s_add_i32 s77, s4, s42
	ds_read_b128 v[154:157], v0
	ds_read_b128 v[158:161], v0 offset:1024
	ds_read_b128 v[162:165], v0 offset:2048
	ds_read_b128 v[166:169], v0 offset:3072
	s_add_i32 s75, s77, 0x2000
	s_add_i32 s74, 0, 0x18000
	s_add_i32 s71, 0, 0x1c000
	s_add_u32 s58, s46, 0x80000
	s_addc_u32 s59, s47, 0
	s_add_i32 s70, s74, s42
	s_add_i32 s69, s70, 0x2000
	s_add_u32 s50, s48, 0x40080
	s_addc_u32 s51, s49, 0
	s_add_i32 s79, s71, s42
	s_add_i32 s78, s79, 0x2000
	ds_read_b128 v[170:173], v137
	ds_read_b128 v[174:177], v137 offset:1024
	ds_read_b128 v[178:181], v137 offset:2048
	ds_read_b128 v[182:185], v137 offset:3072
	ds_read_b128 v[186:189], v137 offset:4096
	ds_read_b128 v[190:193], v137 offset:5120
	ds_read_b128 v[194:197], v137 offset:6144
	ds_read_b128 v[198:201], v137 offset:7168
	s_nop 0
	global_load_lds_dwordx4 v130, s[96:97]
	s_mov_b32 m0, s5
	s_nop 0
	global_load_lds_dwordx4 v132, s[96:97]
	s_waitcnt vmcnt(8)
	s_waitcnt lgkmcnt(0)
	s_barrier
	s_setprio 1
	s_waitcnt lgkmcnt(0)
	v_mfma_f32_16x16x32_bf16 v[126:129], v[138:141], v[170:173], v[126:129]
	v_mfma_f32_16x16x32_bf16 v[122:125], v[146:149], v[170:173], v[122:125]
	v_mfma_f32_16x16x32_bf16 v[118:121], v[138:141], v[178:181], v[118:121]
	v_mfma_f32_16x16x32_bf16 v[110:113], v[146:149], v[178:181], v[110:113]
	v_mfma_f32_16x16x32_bf16 v[102:105], v[138:141], v[186:189], v[102:105]
	v_mfma_f32_16x16x32_bf16 v[94:97], v[146:149], v[186:189], v[94:97]
	v_mfma_f32_16x16x32_bf16 v[86:89], v[138:141], v[194:197], v[86:89]
	v_mfma_f32_16x16x32_bf16 v[78:81], v[146:149], v[194:197], v[78:81]
	v_mfma_f32_16x16x32_bf16 v[126:129], v[142:145], v[174:177], v[126:129]
	v_mfma_f32_16x16x32_bf16 v[122:125], v[150:153], v[174:177], v[122:125]
	v_mfma_f32_16x16x32_bf16 v[118:121], v[142:145], v[182:185], v[118:121]
	v_mfma_f32_16x16x32_bf16 v[110:113], v[150:153], v[182:185], v[110:113]
	v_mfma_f32_16x16x32_bf16 v[102:105], v[142:145], v[190:193], v[102:105]
	v_mfma_f32_16x16x32_bf16 v[94:97], v[150:153], v[190:193], v[94:97]
	v_mfma_f32_16x16x32_bf16 v[86:89], v[142:145], v[198:201], v[86:89]
	v_mfma_f32_16x16x32_bf16 v[78:81], v[150:153], v[198:201], v[78:81]
	s_setprio 0
	s_setprio 1
	v_mfma_f32_16x16x32_bf16 v[114:117], v[154:157], v[170:173], v[114:117]
	v_mfma_f32_16x16x32_bf16 v[106:109], v[162:165], v[170:173], v[106:109]
	v_mfma_f32_16x16x32_bf16 v[98:101], v[154:157], v[178:181], v[98:101]
	v_mfma_f32_16x16x32_bf16 v[90:93], v[162:165], v[178:181], v[90:93]
	v_mfma_f32_16x16x32_bf16 v[82:85], v[154:157], v[186:189], v[82:85]
	v_mfma_f32_16x16x32_bf16 v[74:77], v[162:165], v[186:189], v[74:77]
	v_mfma_f32_16x16x32_bf16 v[70:73], v[154:157], v[194:197], v[70:73]
	v_mfma_f32_16x16x32_bf16 v[62:65], v[162:165], v[194:197], v[62:65]
	v_mfma_f32_16x16x32_bf16 v[114:117], v[158:161], v[174:177], v[114:117]
	v_mfma_f32_16x16x32_bf16 v[106:109], v[166:169], v[174:177], v[106:109]
	v_mfma_f32_16x16x32_bf16 v[98:101], v[158:161], v[182:185], v[98:101]
	v_mfma_f32_16x16x32_bf16 v[90:93], v[166:169], v[182:185], v[90:93]
	v_mfma_f32_16x16x32_bf16 v[82:85], v[158:161], v[190:193], v[82:85]
	v_mfma_f32_16x16x32_bf16 v[74:77], v[166:169], v[190:193], v[74:77]
	v_mfma_f32_16x16x32_bf16 v[70:73], v[158:161], v[198:201], v[70:73]
	v_mfma_f32_16x16x32_bf16 v[62:65], v[166:169], v[198:201], v[62:65]
	s_setprio 0
	s_barrier
	s_mov_b32 m0, s82
	ds_read_b128 v[170:173], v137 offset:16384
	ds_read_b128 v[174:177], v137 offset:17408
	ds_read_b128 v[178:181], v137 offset:18432
	ds_read_b128 v[182:185], v137 offset:19456
	ds_read_b128 v[186:189], v137 offset:20480
	ds_read_b128 v[190:193], v137 offset:21504
	ds_read_b128 v[194:197], v137 offset:22528
	ds_read_b128 v[198:201], v137 offset:23552
	s_nop 0
	global_load_lds_dwordx4 v131, s[48:49]
	s_mov_b32 m0, s76
	s_nop 0
	global_load_lds_dwordx4 v133, s[48:49]
	s_mov_b32 m0, s77
	s_nop 0
	global_load_lds_dwordx4 v131, s[94:95]
	s_mov_b32 m0, s75
	s_nop 0
	global_load_lds_dwordx4 v133, s[94:95]
	s_mov_b32 m0, s43
	s_nop 0
	global_load_lds_dwordx4 v130, s[46:47]
	s_mov_b32 m0, s60
	s_nop 0
	global_load_lds_dwordx4 v132, s[46:47]
	s_waitcnt vmcnt(8)
	s_waitcnt lgkmcnt(0)
	s_barrier
	s_setprio 1
	s_waitcnt lgkmcnt(0)
	v_mfma_f32_16x16x32_bf16 v[66:69], v[138:141], v[170:173], v[66:69]
	v_mfma_f32_16x16x32_bf16 v[58:61], v[146:149], v[170:173], v[58:61]
	v_mfma_f32_16x16x32_bf16 v[54:57], v[138:141], v[178:181], v[54:57]
	v_mfma_f32_16x16x32_bf16 v[46:49], v[146:149], v[178:181], v[46:49]
	v_mfma_f32_16x16x32_bf16 v[38:41], v[138:141], v[186:189], v[38:41]
	v_mfma_f32_16x16x32_bf16 v[30:33], v[146:149], v[186:189], v[30:33]
	v_mfma_f32_16x16x32_bf16 v[22:25], v[138:141], v[194:197], v[22:25]
	v_mfma_f32_16x16x32_bf16 v[14:17], v[146:149], v[194:197], v[14:17]
	v_mfma_f32_16x16x32_bf16 v[66:69], v[142:145], v[174:177], v[66:69]
	v_mfma_f32_16x16x32_bf16 v[58:61], v[150:153], v[174:177], v[58:61]
	v_mfma_f32_16x16x32_bf16 v[54:57], v[142:145], v[182:185], v[54:57]
	v_mfma_f32_16x16x32_bf16 v[46:49], v[150:153], v[182:185], v[46:49]
	v_mfma_f32_16x16x32_bf16 v[38:41], v[142:145], v[190:193], v[38:41]
	v_mfma_f32_16x16x32_bf16 v[30:33], v[150:153], v[190:193], v[30:33]
	v_mfma_f32_16x16x32_bf16 v[22:25], v[142:145], v[198:201], v[22:25]
	v_mfma_f32_16x16x32_bf16 v[14:17], v[150:153], v[198:201], v[14:17]
	s_setprio 0
	s_setprio 1
	v_mfma_f32_16x16x32_bf16 v[50:53], v[154:157], v[170:173], v[50:53]
	v_mfma_f32_16x16x32_bf16 v[42:45], v[162:165], v[170:173], v[42:45]
	v_mfma_f32_16x16x32_bf16 v[34:37], v[154:157], v[178:181], v[34:37]
	v_mfma_f32_16x16x32_bf16 v[26:29], v[162:165], v[178:181], v[26:29]
	v_mfma_f32_16x16x32_bf16 v[18:21], v[154:157], v[186:189], v[18:21]
	v_mfma_f32_16x16x32_bf16 v[10:13], v[162:165], v[186:189], v[10:13]
	v_mfma_f32_16x16x32_bf16 v[6:9], v[154:157], v[194:197], v[6:9]
	v_mfma_f32_16x16x32_bf16 v[2:5], v[162:165], v[194:197], v[2:5]
	v_mfma_f32_16x16x32_bf16 v[50:53], v[158:161], v[174:177], v[50:53]
	v_mfma_f32_16x16x32_bf16 v[42:45], v[166:169], v[174:177], v[42:45]
	v_mfma_f32_16x16x32_bf16 v[34:37], v[158:161], v[182:185], v[34:37]
	v_mfma_f32_16x16x32_bf16 v[26:29], v[166:169], v[182:185], v[26:29]
	v_mfma_f32_16x16x32_bf16 v[18:21], v[158:161], v[190:193], v[18:21]
	v_mfma_f32_16x16x32_bf16 v[10:13], v[166:169], v[190:193], v[10:13]
	v_mfma_f32_16x16x32_bf16 v[6:9], v[158:161], v[198:201], v[6:9]
	v_mfma_f32_16x16x32_bf16 v[2:5], v[166:169], v[198:201], v[2:5]
	s_setprio 0
	s_barrier
	v_add_u32_e32 v0, s74, v136
	ds_read_b128 v[138:141], v0
	ds_read_b128 v[142:145], v0 offset:1024
	ds_read_b128 v[146:149], v0 offset:2048
	ds_read_b128 v[150:153], v0 offset:3072
	v_add_u32_e32 v0, s71, v136
	ds_read_b128 v[154:157], v0
	ds_read_b128 v[158:161], v0 offset:1024
	ds_read_b128 v[162:165], v0 offset:2048
	ds_read_b128 v[166:169], v0 offset:3072
	s_mov_b32 m0, s65
	ds_read_b128 v[170:173], v137 offset:32768
	ds_read_b128 v[174:177], v137 offset:33792
	ds_read_b128 v[178:181], v137 offset:34816
	ds_read_b128 v[182:185], v137 offset:35840
	ds_read_b128 v[186:189], v137 offset:36864
	ds_read_b128 v[190:193], v137 offset:37888
	ds_read_b128 v[194:197], v137 offset:38912
	ds_read_b128 v[198:201], v137 offset:39936
	s_nop 0
	global_load_lds_dwordx4 v130, s[58:59]
	s_mov_b32 m0, s66
	s_nop 0
	global_load_lds_dwordx4 v132, s[58:59]
	s_waitcnt vmcnt(8)
	s_waitcnt lgkmcnt(0)
	s_barrier
	s_setprio 1
	s_waitcnt lgkmcnt(0)
	v_mfma_f32_16x16x32_bf16 v[126:129], v[138:141], v[170:173], v[126:129]
	v_mfma_f32_16x16x32_bf16 v[122:125], v[146:149], v[170:173], v[122:125]
	v_mfma_f32_16x16x32_bf16 v[118:121], v[138:141], v[178:181], v[118:121]
	v_mfma_f32_16x16x32_bf16 v[110:113], v[146:149], v[178:181], v[110:113]
	v_mfma_f32_16x16x32_bf16 v[102:105], v[138:141], v[186:189], v[102:105]
	v_mfma_f32_16x16x32_bf16 v[94:97], v[146:149], v[186:189], v[94:97]
	v_mfma_f32_16x16x32_bf16 v[86:89], v[138:141], v[194:197], v[86:89]
	v_mfma_f32_16x16x32_bf16 v[78:81], v[146:149], v[194:197], v[78:81]
	v_mfma_f32_16x16x32_bf16 v[126:129], v[142:145], v[174:177], v[126:129]
	v_mfma_f32_16x16x32_bf16 v[122:125], v[150:153], v[174:177], v[122:125]
	v_mfma_f32_16x16x32_bf16 v[118:121], v[142:145], v[182:185], v[118:121]
	v_mfma_f32_16x16x32_bf16 v[110:113], v[150:153], v[182:185], v[110:113]
	v_mfma_f32_16x16x32_bf16 v[102:105], v[142:145], v[190:193], v[102:105]
	v_mfma_f32_16x16x32_bf16 v[94:97], v[150:153], v[190:193], v[94:97]
	v_mfma_f32_16x16x32_bf16 v[86:89], v[142:145], v[198:201], v[86:89]
	v_mfma_f32_16x16x32_bf16 v[78:81], v[150:153], v[198:201], v[78:81]
	s_setprio 0
	s_setprio 1
	v_mfma_f32_16x16x32_bf16 v[114:117], v[154:157], v[170:173], v[114:117]
	v_mfma_f32_16x16x32_bf16 v[106:109], v[162:165], v[170:173], v[106:109]
	v_mfma_f32_16x16x32_bf16 v[98:101], v[154:157], v[178:181], v[98:101]
	v_mfma_f32_16x16x32_bf16 v[90:93], v[162:165], v[178:181], v[90:93]
	v_mfma_f32_16x16x32_bf16 v[82:85], v[154:157], v[186:189], v[82:85]
	v_mfma_f32_16x16x32_bf16 v[74:77], v[162:165], v[186:189], v[74:77]
	v_mfma_f32_16x16x32_bf16 v[70:73], v[154:157], v[194:197], v[70:73]
	v_mfma_f32_16x16x32_bf16 v[62:65], v[162:165], v[194:197], v[62:65]
	v_mfma_f32_16x16x32_bf16 v[114:117], v[158:161], v[174:177], v[114:117]
	v_mfma_f32_16x16x32_bf16 v[106:109], v[166:169], v[174:177], v[106:109]
	v_mfma_f32_16x16x32_bf16 v[98:101], v[158:161], v[182:185], v[98:101]
	v_mfma_f32_16x16x32_bf16 v[90:93], v[166:169], v[182:185], v[90:93]
	v_mfma_f32_16x16x32_bf16 v[82:85], v[158:161], v[190:193], v[82:85]
	v_mfma_f32_16x16x32_bf16 v[74:77], v[166:169], v[190:193], v[74:77]
	v_mfma_f32_16x16x32_bf16 v[70:73], v[158:161], v[198:201], v[70:73]
	v_mfma_f32_16x16x32_bf16 v[62:65], v[166:169], v[198:201], v[62:65]
	s_setprio 0
	s_barrier
	ds_read_b128 v[170:173], v137 offset:49152
	ds_read_b128 v[174:177], v137 offset:50176
	ds_read_b128 v[178:181], v137 offset:51200
	ds_read_b128 v[182:185], v137 offset:52224
	ds_read_b128 v[186:189], v137 offset:53248
	ds_read_b128 v[190:193], v137 offset:54272
	ds_read_b128 v[194:197], v137 offset:55296
	ds_read_b128 v[198:201], v137 offset:56320
	s_mov_b32 m0, s70
	s_add_u32 s100, s48, s38
	s_addc_u32 s101, s49, s39
	global_load_lds_dwordx4 v131, s[100:101]
	s_mov_b32 m0, s69
	s_nop 0
	global_load_lds_dwordx4 v133, s[100:101]
	s_mov_b32 m0, s79
	s_nop 0
	global_load_lds_dwordx4 v131, s[50:51]
	s_mov_b32 m0, s78
	s_nop 0
	global_load_lds_dwordx4 v133, s[50:51]
	s_mov_b32 m0, s67
	s_add_u32 s100, s46, s38
	s_addc_u32 s101, s47, s39
	v_mov_b32_e32 v0, v132
	global_load_lds_dwordx4 v130, s[100:101]
	s_mov_b32 m0, s68
	s_nop 0
	global_load_lds_dwordx4 v132, s[100:101]
	s_waitcnt vmcnt(8)
	s_waitcnt lgkmcnt(0)
	s_barrier
	s_setprio 1
	s_waitcnt lgkmcnt(0)
	v_mfma_f32_16x16x32_bf16 v[66:69], v[138:141], v[170:173], v[66:69]
	v_mfma_f32_16x16x32_bf16 v[58:61], v[146:149], v[170:173], v[58:61]
	v_mfma_f32_16x16x32_bf16 v[54:57], v[138:141], v[178:181], v[54:57]
	v_mfma_f32_16x16x32_bf16 v[46:49], v[146:149], v[178:181], v[46:49]
	v_mfma_f32_16x16x32_bf16 v[38:41], v[138:141], v[186:189], v[38:41]
	v_mfma_f32_16x16x32_bf16 v[30:33], v[146:149], v[186:189], v[30:33]
	v_mfma_f32_16x16x32_bf16 v[22:25], v[138:141], v[194:197], v[22:25]
	v_mfma_f32_16x16x32_bf16 v[14:17], v[146:149], v[194:197], v[14:17]
	v_mfma_f32_16x16x32_bf16 v[66:69], v[142:145], v[174:177], v[66:69]
	v_mfma_f32_16x16x32_bf16 v[58:61], v[150:153], v[174:177], v[58:61]
	v_mfma_f32_16x16x32_bf16 v[54:57], v[142:145], v[182:185], v[54:57]
	v_mfma_f32_16x16x32_bf16 v[46:49], v[150:153], v[182:185], v[46:49]
	v_mfma_f32_16x16x32_bf16 v[38:41], v[142:145], v[190:193], v[38:41]
	v_mfma_f32_16x16x32_bf16 v[30:33], v[150:153], v[190:193], v[30:33]
	v_mfma_f32_16x16x32_bf16 v[22:25], v[142:145], v[198:201], v[22:25]
	v_mfma_f32_16x16x32_bf16 v[14:17], v[150:153], v[198:201], v[14:17]
	s_setprio 0
	s_setprio 1
	v_mfma_f32_16x16x32_bf16 v[50:53], v[154:157], v[170:173], v[50:53]
	v_mfma_f32_16x16x32_bf16 v[42:45], v[162:165], v[170:173], v[42:45]
	v_mfma_f32_16x16x32_bf16 v[34:37], v[154:157], v[178:181], v[34:37]
	v_mfma_f32_16x16x32_bf16 v[26:29], v[162:165], v[178:181], v[26:29]
	v_mfma_f32_16x16x32_bf16 v[18:21], v[154:157], v[186:189], v[18:21]
	v_mfma_f32_16x16x32_bf16 v[10:13], v[162:165], v[186:189], v[10:13]
	v_mfma_f32_16x16x32_bf16 v[6:9], v[154:157], v[194:197], v[6:9]
	v_mfma_f32_16x16x32_bf16 v[2:5], v[162:165], v[194:197], v[2:5]
	v_mfma_f32_16x16x32_bf16 v[50:53], v[158:161], v[174:177], v[50:53]
	v_mfma_f32_16x16x32_bf16 v[42:45], v[166:169], v[174:177], v[42:45]
	v_mfma_f32_16x16x32_bf16 v[34:37], v[158:161], v[182:185], v[34:37]
	v_mfma_f32_16x16x32_bf16 v[26:29], v[166:169], v[182:185], v[26:29]
	v_mfma_f32_16x16x32_bf16 v[18:21], v[158:161], v[190:193], v[18:21]
	v_mfma_f32_16x16x32_bf16 v[10:13], v[166:169], v[190:193], v[10:13]
	v_mfma_f32_16x16x32_bf16 v[6:9], v[158:161], v[198:201], v[6:9]
	v_mfma_f32_16x16x32_bf16 v[2:5], v[166:169], v[198:201], v[2:5]
	s_setprio 0
	s_barrier
	s_andn2_b64 vcc, exec, s[22:23]
	s_mov_b64 s[48:49], -1
	s_mov_b64 s[22:23], 0
	s_mov_b64 s[50:51], 0x100
	s_cbranch_vccz .LBB0_626
	s_cmpk_lt_u32 s25, 0x100
	s_cbranch_scc0 .LBB0_629
	s_barrier

.LBB0_634:
	s_add_u32 s50, s2, s48
	s_addc_u32 s51, s3, s49
	s_add_u32 s22, s50, 0x100
	s_addc_u32 s23, s51, 0
	s_and_b64 s[4:5], s[46:47], exec
	s_cselect_b32 s23, s3, s23
	s_cselect_b32 s22, s2, s22
	s_add_u32 s4, s14, s48
	s_addc_u32 s5, s15, s49
	s_add_u32 s48, s4, 0x900
	s_addc_u32 s49, s5, 0
	s_add_i32 s78, 0, 0x10000
	s_and_b64 s[4:5], s[46:47], exec
	s_cselect_b32 s47, s66, s49
	s_cselect_b32 s46, s65, s48
	s_add_i32 s4, 0, 0x14000
	s_add_u32 s94, s50, 0x40080
	s_addc_u32 s95, s51, 0
	s_add_i32 s82, s78, s40
	s_add_i32 m0, s41, 0xc000
	s_add_i32 s5, s41, 0xe000
	s_add_i32 s76, s82, 0x2000
	v_add_u32_e32 v0, s78, v136
	s_add_u32 s58, s46, 0x80000
	ds_read_b128 v[138:141], v0
	ds_read_b128 v[142:145], v0 offset:1024
	ds_read_b128 v[146:149], v0 offset:2048
	ds_read_b128 v[150:153], v0 offset:3072
	v_add_u32_e32 v0, s4, v136
	s_addc_u32 s59, s47, 0
	s_add_i32 s77, s4, s40
	ds_read_b128 v[154:157], v0
	ds_read_b128 v[158:161], v0 offset:1024
	ds_read_b128 v[162:165], v0 offset:2048
	ds_read_b128 v[166:169], v0 offset:3072
	s_add_i32 s75, s77, 0x2000
	s_add_i32 s74, 0, 0x18000
	s_add_i32 s71, 0, 0x1c000
	s_add_u32 s50, s22, 0x40000
	s_addc_u32 s51, s23, 0
	s_add_i32 s70, s74, s40
	s_add_i32 s69, s70, 0x2000
	s_add_u32 s48, s46, 0x80080
	s_addc_u32 s49, s47, 0
	s_add_i32 s79, s71, s40
	s_add_i32 s78, s79, 0x2000
	ds_read_b128 v[170:173], v137
	ds_read_b128 v[174:177], v137 offset:1024
	ds_read_b128 v[178:181], v137 offset:2048
	ds_read_b128 v[182:185], v137 offset:3072
	ds_read_b128 v[186:189], v137 offset:4096
	ds_read_b128 v[190:193], v137 offset:5120
	ds_read_b128 v[194:197], v137 offset:6144
	ds_read_b128 v[198:201], v137 offset:7168
	s_nop 0
	global_load_lds_dwordx4 v130, s[94:95]
	s_mov_b32 m0, s5
	s_nop 0
	global_load_lds_dwordx4 v132, s[94:95]
	s_waitcnt vmcnt(8)
	s_waitcnt lgkmcnt(0)
	s_barrier
	s_setprio 1
	s_waitcnt lgkmcnt(0)
	v_mfma_f32_16x16x32_bf16 v[126:129], v[138:141], v[170:173], v[126:129]
	v_mfma_f32_16x16x32_bf16 v[122:125], v[146:149], v[170:173], v[122:125]
	v_mfma_f32_16x16x32_bf16 v[118:121], v[138:141], v[178:181], v[118:121]
	v_mfma_f32_16x16x32_bf16 v[110:113], v[146:149], v[178:181], v[110:113]
	v_mfma_f32_16x16x32_bf16 v[102:105], v[138:141], v[186:189], v[102:105]
	v_mfma_f32_16x16x32_bf16 v[94:97], v[146:149], v[186:189], v[94:97]
	v_mfma_f32_16x16x32_bf16 v[86:89], v[138:141], v[194:197], v[86:89]
	v_mfma_f32_16x16x32_bf16 v[78:81], v[146:149], v[194:197], v[78:81]
	v_mfma_f32_16x16x32_bf16 v[126:129], v[142:145], v[174:177], v[126:129]
	v_mfma_f32_16x16x32_bf16 v[122:125], v[150:153], v[174:177], v[122:125]
	v_mfma_f32_16x16x32_bf16 v[118:121], v[142:145], v[182:185], v[118:121]
	v_mfma_f32_16x16x32_bf16 v[110:113], v[150:153], v[182:185], v[110:113]
	v_mfma_f32_16x16x32_bf16 v[102:105], v[142:145], v[190:193], v[102:105]
	v_mfma_f32_16x16x32_bf16 v[94:97], v[150:153], v[190:193], v[94:97]
	v_mfma_f32_16x16x32_bf16 v[86:89], v[142:145], v[198:201], v[86:89]
	v_mfma_f32_16x16x32_bf16 v[78:81], v[150:153], v[198:201], v[78:81]
	s_setprio 0
	s_setprio 1
	v_mfma_f32_16x16x32_bf16 v[114:117], v[154:157], v[170:173], v[114:117]
	v_mfma_f32_16x16x32_bf16 v[106:109], v[162:165], v[170:173], v[106:109]
	v_mfma_f32_16x16x32_bf16 v[98:101], v[154:157], v[178:181], v[98:101]
	v_mfma_f32_16x16x32_bf16 v[90:93], v[162:165], v[178:181], v[90:93]
	v_mfma_f32_16x16x32_bf16 v[82:85], v[154:157], v[186:189], v[82:85]
	v_mfma_f32_16x16x32_bf16 v[74:77], v[162:165], v[186:189], v[74:77]
	v_mfma_f32_16x16x32_bf16 v[70:73], v[154:157], v[194:197], v[70:73]
	v_mfma_f32_16x16x32_bf16 v[62:65], v[162:165], v[194:197], v[62:65]
	v_mfma_f32_16x16x32_bf16 v[114:117], v[158:161], v[174:177], v[114:117]
	v_mfma_f32_16x16x32_bf16 v[106:109], v[166:169], v[174:177], v[106:109]
	v_mfma_f32_16x16x32_bf16 v[98:101], v[158:161], v[182:185], v[98:101]
	v_mfma_f32_16x16x32_bf16 v[90:93], v[166:169], v[182:185], v[90:93]
	v_mfma_f32_16x16x32_bf16 v[82:85], v[158:161], v[190:193], v[82:85]
	v_mfma_f32_16x16x32_bf16 v[74:77], v[166:169], v[190:193], v[74:77]
	v_mfma_f32_16x16x32_bf16 v[70:73], v[158:161], v[198:201], v[70:73]
	v_mfma_f32_16x16x32_bf16 v[62:65], v[166:169], v[198:201], v[62:65]
	s_setprio 0
	s_barrier
	s_mov_b32 m0, s82
	ds_read_b128 v[170:173], v137 offset:16384
	ds_read_b128 v[174:177], v137 offset:17408
	ds_read_b128 v[178:181], v137 offset:18432
	ds_read_b128 v[182:185], v137 offset:19456
	ds_read_b128 v[186:189], v137 offset:20480
	ds_read_b128 v[190:193], v137 offset:21504
	ds_read_b128 v[194:197], v137 offset:22528
	ds_read_b128 v[198:201], v137 offset:23552
	s_nop 0
	global_load_lds_dwordx4 v131, s[46:47]
	s_mov_b32 m0, s76
	s_nop 0
	global_load_lds_dwordx4 v133, s[46:47]
	s_mov_b32 m0, s77
	s_nop 0
	global_load_lds_dwordx4 v131, s[58:59]
	s_mov_b32 m0, s75
	s_nop 0
	global_load_lds_dwordx4 v133, s[58:59]
	s_mov_b32 m0, s41
	s_nop 0
	global_load_lds_dwordx4 v130, s[22:23]
	s_mov_b32 m0, s42
	s_nop 0
	global_load_lds_dwordx4 v132, s[22:23]
	s_waitcnt vmcnt(8)
	s_waitcnt lgkmcnt(0)
	s_barrier
	s_setprio 1
	s_waitcnt lgkmcnt(0)
	v_mfma_f32_16x16x32_bf16 v[66:69], v[138:141], v[170:173], v[66:69]
	v_mfma_f32_16x16x32_bf16 v[58:61], v[146:149], v[170:173], v[58:61]
	v_mfma_f32_16x16x32_bf16 v[54:57], v[138:141], v[178:181], v[54:57]
	v_mfma_f32_16x16x32_bf16 v[46:49], v[146:149], v[178:181], v[46:49]
	v_mfma_f32_16x16x32_bf16 v[38:41], v[138:141], v[186:189], v[38:41]
	v_mfma_f32_16x16x32_bf16 v[30:33], v[146:149], v[186:189], v[30:33]
	v_mfma_f32_16x16x32_bf16 v[22:25], v[138:141], v[194:197], v[22:25]
	v_mfma_f32_16x16x32_bf16 v[14:17], v[146:149], v[194:197], v[14:17]
	v_mfma_f32_16x16x32_bf16 v[66:69], v[142:145], v[174:177], v[66:69]
	v_mfma_f32_16x16x32_bf16 v[58:61], v[150:153], v[174:177], v[58:61]
	v_mfma_f32_16x16x32_bf16 v[54:57], v[142:145], v[182:185], v[54:57]
	v_mfma_f32_16x16x32_bf16 v[46:49], v[150:153], v[182:185], v[46:49]
	v_mfma_f32_16x16x32_bf16 v[38:41], v[142:145], v[190:193], v[38:41]
	v_mfma_f32_16x16x32_bf16 v[30:33], v[150:153], v[190:193], v[30:33]
	v_mfma_f32_16x16x32_bf16 v[22:25], v[142:145], v[198:201], v[22:25]
	v_mfma_f32_16x16x32_bf16 v[14:17], v[150:153], v[198:201], v[14:17]
	s_setprio 0
	s_setprio 1
	v_mfma_f32_16x16x32_bf16 v[50:53], v[154:157], v[170:173], v[50:53]
	v_mfma_f32_16x16x32_bf16 v[42:45], v[162:165], v[170:173], v[42:45]
	v_mfma_f32_16x16x32_bf16 v[34:37], v[154:157], v[178:181], v[34:37]
	v_mfma_f32_16x16x32_bf16 v[26:29], v[162:165], v[178:181], v[26:29]
	v_mfma_f32_16x16x32_bf16 v[18:21], v[154:157], v[186:189], v[18:21]
	v_mfma_f32_16x16x32_bf16 v[10:13], v[162:165], v[186:189], v[10:13]
	v_mfma_f32_16x16x32_bf16 v[6:9], v[154:157], v[194:197], v[6:9]
	v_mfma_f32_16x16x32_bf16 v[2:5], v[162:165], v[194:197], v[2:5]
	v_mfma_f32_16x16x32_bf16 v[50:53], v[158:161], v[174:177], v[50:53]
	v_mfma_f32_16x16x32_bf16 v[42:45], v[166:169], v[174:177], v[42:45]
	v_mfma_f32_16x16x32_bf16 v[34:37], v[158:161], v[182:185], v[34:37]
	v_mfma_f32_16x16x32_bf16 v[26:29], v[166:169], v[182:185], v[26:29]
	v_mfma_f32_16x16x32_bf16 v[18:21], v[158:161], v[190:193], v[18:21]
	v_mfma_f32_16x16x32_bf16 v[10:13], v[166:169], v[190:193], v[10:13]
	v_mfma_f32_16x16x32_bf16 v[6:9], v[158:161], v[198:201], v[6:9]
	v_mfma_f32_16x16x32_bf16 v[2:5], v[166:169], v[198:201], v[2:5]
	s_setprio 0
	s_barrier
	v_add_u32_e32 v0, s74, v136
	ds_read_b128 v[138:141], v0
	ds_read_b128 v[142:145], v0 offset:1024
	ds_read_b128 v[146:149], v0 offset:2048
	ds_read_b128 v[150:153], v0 offset:3072
	v_add_u32_e32 v0, s71, v136
	ds_read_b128 v[154:157], v0
	ds_read_b128 v[158:161], v0 offset:1024
	ds_read_b128 v[162:165], v0 offset:2048
	ds_read_b128 v[166:169], v0 offset:3072
	s_mov_b32 m0, s43
	ds_read_b128 v[170:173], v137 offset:32768
	ds_read_b128 v[174:177], v137 offset:33792
	ds_read_b128 v[178:181], v137 offset:34816
	ds_read_b128 v[182:185], v137 offset:35840
	ds_read_b128 v[186:189], v137 offset:36864
	ds_read_b128 v[190:193], v137 offset:37888
	ds_read_b128 v[194:197], v137 offset:38912
	ds_read_b128 v[198:201], v137 offset:39936
	s_nop 0
	global_load_lds_dwordx4 v130, s[50:51]
	s_mov_b32 m0, s64
	s_nop 0
	global_load_lds_dwordx4 v132, s[50:51]
	s_waitcnt vmcnt(8)
	s_waitcnt lgkmcnt(0)
	s_barrier
	s_setprio 1
	s_waitcnt lgkmcnt(0)
	v_mfma_f32_16x16x32_bf16 v[126:129], v[138:141], v[170:173], v[126:129]
	v_mfma_f32_16x16x32_bf16 v[122:125], v[146:149], v[170:173], v[122:125]
	v_mfma_f32_16x16x32_bf16 v[118:121], v[138:141], v[178:181], v[118:121]
	v_mfma_f32_16x16x32_bf16 v[110:113], v[146:149], v[178:181], v[110:113]
	v_mfma_f32_16x16x32_bf16 v[102:105], v[138:141], v[186:189], v[102:105]
	v_mfma_f32_16x16x32_bf16 v[94:97], v[146:149], v[186:189], v[94:97]
	v_mfma_f32_16x16x32_bf16 v[86:89], v[138:141], v[194:197], v[86:89]
	v_mfma_f32_16x16x32_bf16 v[78:81], v[146:149], v[194:197], v[78:81]
	v_mfma_f32_16x16x32_bf16 v[126:129], v[142:145], v[174:177], v[126:129]
	v_mfma_f32_16x16x32_bf16 v[122:125], v[150:153], v[174:177], v[122:125]
	v_mfma_f32_16x16x32_bf16 v[118:121], v[142:145], v[182:185], v[118:121]
	v_mfma_f32_16x16x32_bf16 v[110:113], v[150:153], v[182:185], v[110:113]
	v_mfma_f32_16x16x32_bf16 v[102:105], v[142:145], v[190:193], v[102:105]
	v_mfma_f32_16x16x32_bf16 v[94:97], v[150:153], v[190:193], v[94:97]
	v_mfma_f32_16x16x32_bf16 v[86:89], v[142:145], v[198:201], v[86:89]
	v_mfma_f32_16x16x32_bf16 v[78:81], v[150:153], v[198:201], v[78:81]
	s_setprio 0
	s_setprio 1
	v_mfma_f32_16x16x32_bf16 v[114:117], v[154:157], v[170:173], v[114:117]
	v_mfma_f32_16x16x32_bf16 v[106:109], v[162:165], v[170:173], v[106:109]
	v_mfma_f32_16x16x32_bf16 v[98:101], v[154:157], v[178:181], v[98:101]
	v_mfma_f32_16x16x32_bf16 v[90:93], v[162:165], v[178:181], v[90:93]
	v_mfma_f32_16x16x32_bf16 v[82:85], v[154:157], v[186:189], v[82:85]
	v_mfma_f32_16x16x32_bf16 v[74:77], v[162:165], v[186:189], v[74:77]
	v_mfma_f32_16x16x32_bf16 v[70:73], v[154:157], v[194:197], v[70:73]
	v_mfma_f32_16x16x32_bf16 v[62:65], v[162:165], v[194:197], v[62:65]
	v_mfma_f32_16x16x32_bf16 v[114:117], v[158:161], v[174:177], v[114:117]
	v_mfma_f32_16x16x32_bf16 v[106:109], v[166:169], v[174:177], v[106:109]
	v_mfma_f32_16x16x32_bf16 v[98:101], v[158:161], v[182:185], v[98:101]
	v_mfma_f32_16x16x32_bf16 v[90:93], v[166:169], v[182:185], v[90:93]
	v_mfma_f32_16x16x32_bf16 v[82:85], v[158:161], v[190:193], v[82:85]
	v_mfma_f32_16x16x32_bf16 v[74:77], v[166:169], v[190:193], v[74:77]
	v_mfma_f32_16x16x32_bf16 v[70:73], v[158:161], v[198:201], v[70:73]
	v_mfma_f32_16x16x32_bf16 v[62:65], v[166:169], v[198:201], v[62:65]
	s_setprio 0
	s_barrier
	ds_read_b128 v[170:173], v137 offset:49152
	ds_read_b128 v[174:177], v137 offset:50176
	ds_read_b128 v[178:181], v137 offset:51200
	ds_read_b128 v[182:185], v137 offset:52224
	ds_read_b128 v[186:189], v137 offset:53248
	ds_read_b128 v[190:193], v137 offset:54272
	ds_read_b128 v[194:197], v137 offset:55296
	ds_read_b128 v[198:201], v137 offset:56320
	s_mov_b32 m0, s70
	s_add_u32 s100, s46, s38
	s_addc_u32 s101, s47, s39
	global_load_lds_dwordx4 v131, s[100:101]
	s_mov_b32 m0, s69
	s_nop 0
	global_load_lds_dwordx4 v133, s[100:101]
	s_mov_b32 m0, s79
	s_nop 0
	global_load_lds_dwordx4 v131, s[48:49]
	s_mov_b32 m0, s78
	s_nop 0
	global_load_lds_dwordx4 v133, s[48:49]
	s_mov_b32 m0, s67
	s_add_u32 s100, s22, s38
	s_addc_u32 s101, s23, s39
	v_mov_b32_e32 v0, v132
	global_load_lds_dwordx4 v130, s[100:101]
	s_mov_b32 m0, s68
	s_nop 0
	global_load_lds_dwordx4 v132, s[100:101]
	s_waitcnt vmcnt(8)
	s_waitcnt lgkmcnt(0)
	s_barrier
	s_setprio 1
	s_waitcnt lgkmcnt(0)
	v_mfma_f32_16x16x32_bf16 v[66:69], v[138:141], v[170:173], v[66:69]
	v_mfma_f32_16x16x32_bf16 v[58:61], v[146:149], v[170:173], v[58:61]
	v_mfma_f32_16x16x32_bf16 v[54:57], v[138:141], v[178:181], v[54:57]
	v_mfma_f32_16x16x32_bf16 v[46:49], v[146:149], v[178:181], v[46:49]
	v_mfma_f32_16x16x32_bf16 v[38:41], v[138:141], v[186:189], v[38:41]
	v_mfma_f32_16x16x32_bf16 v[30:33], v[146:149], v[186:189], v[30:33]
	v_mfma_f32_16x16x32_bf16 v[22:25], v[138:141], v[194:197], v[22:25]
	v_mfma_f32_16x16x32_bf16 v[14:17], v[146:149], v[194:197], v[14:17]
	v_mfma_f32_16x16x32_bf16 v[66:69], v[142:145], v[174:177], v[66:69]
	v_mfma_f32_16x16x32_bf16 v[58:61], v[150:153], v[174:177], v[58:61]
	v_mfma_f32_16x16x32_bf16 v[54:57], v[142:145], v[182:185], v[54:57]
	v_mfma_f32_16x16x32_bf16 v[46:49], v[150:153], v[182:185], v[46:49]
	v_mfma_f32_16x16x32_bf16 v[38:41], v[142:145], v[190:193], v[38:41]
	v_mfma_f32_16x16x32_bf16 v[30:33], v[150:153], v[190:193], v[30:33]
	v_mfma_f32_16x16x32_bf16 v[22:25], v[142:145], v[198:201], v[22:25]
	v_mfma_f32_16x16x32_bf16 v[14:17], v[150:153], v[198:201], v[14:17]
	s_setprio 0
	s_setprio 1
	v_mfma_f32_16x16x32_bf16 v[50:53], v[154:157], v[170:173], v[50:53]
	v_mfma_f32_16x16x32_bf16 v[42:45], v[162:165], v[170:173], v[42:45]
	v_mfma_f32_16x16x32_bf16 v[34:37], v[154:157], v[178:181], v[34:37]
	v_mfma_f32_16x16x32_bf16 v[26:29], v[162:165], v[178:181], v[26:29]
	v_mfma_f32_16x16x32_bf16 v[18:21], v[154:157], v[186:189], v[18:21]
	v_mfma_f32_16x16x32_bf16 v[10:13], v[162:165], v[186:189], v[10:13]
	v_mfma_f32_16x16x32_bf16 v[6:9], v[154:157], v[194:197], v[6:9]
	v_mfma_f32_16x16x32_bf16 v[2:5], v[162:165], v[194:197], v[2:5]
	v_mfma_f32_16x16x32_bf16 v[50:53], v[158:161], v[174:177], v[50:53]
	v_mfma_f32_16x16x32_bf16 v[42:45], v[166:169], v[174:177], v[42:45]
	v_mfma_f32_16x16x32_bf16 v[34:37], v[158:161], v[182:185], v[34:37]
	v_mfma_f32_16x16x32_bf16 v[26:29], v[166:169], v[182:185], v[26:29]
	v_mfma_f32_16x16x32_bf16 v[18:21], v[158:161], v[190:193], v[18:21]
	v_mfma_f32_16x16x32_bf16 v[10:13], v[166:169], v[190:193], v[10:13]
	v_mfma_f32_16x16x32_bf16 v[6:9], v[158:161], v[198:201], v[6:9]
	v_mfma_f32_16x16x32_bf16 v[2:5], v[166:169], v[198:201], v[2:5]
	s_setprio 0
	s_barrier
	s_andn2_b64 vcc, exec, s[16:17]
	s_mov_b64 s[46:47], -1
	s_mov_b64 s[16:17], 0
	s_mov_b64 s[48:49], 0x100
	s_cbranch_vccz .LBB0_634
	s_cmpk_lt_u32 s25, 0x100
	s_cbranch_scc0 .LBB0_637
	s_barrier

.LBB0_667:
	s_add_u32 s4, s70, s50
	s_addc_u32 s5, s71, s51
	s_add_u32 s46, s4, 0x9400100
	s_addc_u32 s47, s5, 0
	s_add_u32 s58, s74, s50
	s_addc_u32 s59, s75, s51
	s_add_i32 s77, 0, 0x10000
	s_cmpk_eq_i32 s50, 0x300
	s_cselect_b32 s47, s23, s47
	s_cselect_b32 s46, s22, s46
	v_add_u32_e32 v0, s77, v144
	s_cselect_b32 s59, s49, s59
	s_cselect_b32 s58, s48, s58
	s_add_i32 s78, 0, 0x14000
	ds_read_b128 v[146:149], v0
	ds_read_b128 v[150:153], v0 offset:1024
	ds_read_b128 v[154:157], v0 offset:2048
	ds_read_b128 v[158:161], v0 offset:3072
	v_add_u32_e32 v0, s78, v144
	ds_read_b128 v[162:165], v0
	ds_read_b128 v[166:169], v0 offset:1024
	ds_read_b128 v[170:173], v0 offset:2048
	ds_read_b128 v[174:177], v0 offset:3072
	ds_read_b128 v[178:181], v145
	ds_read_b128 v[182:185], v145 offset:1024
	ds_read_b128 v[186:189], v145 offset:2048
	ds_read_b128 v[190:193], v145 offset:3072
	ds_read_b128 v[194:197], v145 offset:4096
	ds_read_b128 v[198:201], v145 offset:5120
	ds_read_b128 v[202:205], v145 offset:6144
	ds_read_b128 v[206:209], v145 offset:7168
	s_add_i32 m0, s61, 0xc000
	s_add_u32 s100, s4, s54
	s_addc_u32 s101, s5, s55
	global_load_lds_dwordx4 v130, s[100:101]
	s_add_i32 m0, s61, 0xe000
	s_nop 0
	global_load_lds_dwordx4 v141, s[100:101]
	s_waitcnt vmcnt(8)
	s_waitcnt lgkmcnt(0)
	s_barrier
	s_setprio 1
	s_waitcnt lgkmcnt(0)
	v_mfma_i32_16x16x64_i8 v[126:129], v[146:149], v[178:181], v[126:129]
	v_mfma_i32_16x16x64_i8 v[122:125], v[154:157], v[178:181], v[122:125]
	v_mfma_i32_16x16x64_i8 v[110:113], v[146:149], v[186:189], v[110:113]
	v_mfma_i32_16x16x64_i8 v[106:109], v[154:157], v[186:189], v[106:109]
	v_mfma_i32_16x16x64_i8 v[94:97], v[146:149], v[194:197], v[94:97]
	v_mfma_i32_16x16x64_i8 v[90:93], v[154:157], v[194:197], v[90:93]
	v_mfma_i32_16x16x64_i8 v[78:81], v[146:149], v[202:205], v[78:81]
	v_mfma_i32_16x16x64_i8 v[74:77], v[154:157], v[202:205], v[74:77]
	v_mfma_i32_16x16x64_i8 v[126:129], v[150:153], v[182:185], v[126:129]
	v_mfma_i32_16x16x64_i8 v[122:125], v[158:161], v[182:185], v[122:125]
	v_mfma_i32_16x16x64_i8 v[110:113], v[150:153], v[190:193], v[110:113]
	v_mfma_i32_16x16x64_i8 v[106:109], v[158:161], v[190:193], v[106:109]
	v_mfma_i32_16x16x64_i8 v[94:97], v[150:153], v[198:201], v[94:97]
	v_mfma_i32_16x16x64_i8 v[90:93], v[158:161], v[198:201], v[90:93]
	v_mfma_i32_16x16x64_i8 v[78:81], v[150:153], v[206:209], v[78:81]
	v_mfma_i32_16x16x64_i8 v[74:77], v[158:161], v[206:209], v[74:77]
	s_setprio 0
	s_setprio 1
	v_mfma_i32_16x16x64_i8 v[118:121], v[162:165], v[178:181], v[118:121]
	v_mfma_i32_16x16x64_i8 v[114:117], v[170:173], v[178:181], v[114:117]
	v_mfma_i32_16x16x64_i8 v[102:105], v[162:165], v[186:189], v[102:105]
	v_mfma_i32_16x16x64_i8 v[98:101], v[170:173], v[186:189], v[98:101]
	v_mfma_i32_16x16x64_i8 v[86:89], v[162:165], v[194:197], v[86:89]
	v_mfma_i32_16x16x64_i8 v[82:85], v[170:173], v[194:197], v[82:85]
	v_mfma_i32_16x16x64_i8 v[70:73], v[162:165], v[202:205], v[70:73]
	v_mfma_i32_16x16x64_i8 v[66:69], v[170:173], v[202:205], v[66:69]
	v_mfma_i32_16x16x64_i8 v[118:121], v[166:169], v[182:185], v[118:121]
	v_mfma_i32_16x16x64_i8 v[114:117], v[174:177], v[182:185], v[114:117]
	v_mfma_i32_16x16x64_i8 v[102:105], v[166:169], v[190:193], v[102:105]
	v_mfma_i32_16x16x64_i8 v[98:101], v[174:177], v[190:193], v[98:101]
	v_mfma_i32_16x16x64_i8 v[86:89], v[166:169], v[198:201], v[86:89]
	v_mfma_i32_16x16x64_i8 v[82:85], v[174:177], v[198:201], v[82:85]
	v_mfma_i32_16x16x64_i8 v[70:73], v[166:169], v[206:209], v[70:73]
	v_mfma_i32_16x16x64_i8 v[66:69], v[174:177], v[206:209], v[66:69]
	s_setprio 0
	s_barrier
	s_add_i32 s4, s77, s60
	ds_read_b128 v[178:181], v145 offset:16384
	ds_read_b128 v[182:185], v145 offset:17408
	ds_read_b128 v[186:189], v145 offset:18432
	ds_read_b128 v[190:193], v145 offset:19456
	ds_read_b128 v[194:197], v145 offset:20480
	ds_read_b128 v[198:201], v145 offset:21504
	ds_read_b128 v[202:205], v145 offset:22528
	ds_read_b128 v[206:209], v145 offset:23552
	s_mov_b32 m0, s4
	s_nop 0
	global_load_lds_dwordx4 v131, s[58:59]
	s_add_i32 m0, s4, 0x2000
	s_add_u32 s4, s58, 0x20000
	global_load_lds_dwordx4 v142, s[58:59]
	s_addc_u32 s5, s59, 0
	s_add_i32 s77, s78, s60
	s_mov_b32 m0, s77
	s_nop 0
	global_load_lds_dwordx4 v131, s[4:5]
	s_add_i32 m0, s77, 0x2000
	s_nop 0
	global_load_lds_dwordx4 v142, s[4:5]
	s_mov_b32 m0, s61
	s_nop 0
	global_load_lds_dwordx4 v130, s[46:47]
	s_mov_b32 m0, s65
	s_nop 0
	global_load_lds_dwordx4 v141, s[46:47]
	s_waitcnt vmcnt(8)
	s_waitcnt lgkmcnt(0)
	s_barrier
	s_setprio 1
	s_waitcnt lgkmcnt(0)
	v_mfma_i32_16x16x64_i8 v[62:65], v[146:149], v[178:181], v[62:65]
	v_mfma_i32_16x16x64_i8 v[58:61], v[154:157], v[178:181], v[58:61]
	v_mfma_i32_16x16x64_i8 v[46:49], v[146:149], v[186:189], v[46:49]
	v_mfma_i32_16x16x64_i8 v[42:45], v[154:157], v[186:189], v[42:45]
	v_mfma_i32_16x16x64_i8 v[30:33], v[146:149], v[194:197], v[30:33]
	v_mfma_i32_16x16x64_i8 v[26:29], v[154:157], v[194:197], v[26:29]
	v_mfma_i32_16x16x64_i8 v[14:17], v[146:149], v[202:205], v[14:17]
	v_mfma_i32_16x16x64_i8 v[10:13], v[154:157], v[202:205], v[10:13]
	v_mfma_i32_16x16x64_i8 v[62:65], v[150:153], v[182:185], v[62:65]
	v_mfma_i32_16x16x64_i8 v[58:61], v[158:161], v[182:185], v[58:61]
	v_mfma_i32_16x16x64_i8 v[46:49], v[150:153], v[190:193], v[46:49]
	v_mfma_i32_16x16x64_i8 v[42:45], v[158:161], v[190:193], v[42:45]
	v_mfma_i32_16x16x64_i8 v[30:33], v[150:153], v[198:201], v[30:33]
	v_mfma_i32_16x16x64_i8 v[26:29], v[158:161], v[198:201], v[26:29]
	v_mfma_i32_16x16x64_i8 v[14:17], v[150:153], v[206:209], v[14:17]
	v_mfma_i32_16x16x64_i8 v[10:13], v[158:161], v[206:209], v[10:13]
	s_setprio 0
	s_setprio 1
	v_mfma_i32_16x16x64_i8 v[54:57], v[162:165], v[178:181], v[54:57]
	v_mfma_i32_16x16x64_i8 v[50:53], v[170:173], v[178:181], v[50:53]
	v_mfma_i32_16x16x64_i8 v[38:41], v[162:165], v[186:189], v[38:41]
	v_mfma_i32_16x16x64_i8 v[34:37], v[170:173], v[186:189], v[34:37]
	v_mfma_i32_16x16x64_i8 v[22:25], v[162:165], v[194:197], v[22:25]
	v_mfma_i32_16x16x64_i8 v[18:21], v[170:173], v[194:197], v[18:21]
	v_mfma_i32_16x16x64_i8 v[6:9], v[162:165], v[202:205], v[6:9]
	v_mfma_i32_16x16x64_i8 v[2:5], v[170:173], v[202:205], v[2:5]
	v_mfma_i32_16x16x64_i8 v[54:57], v[166:169], v[182:185], v[54:57]
	v_mfma_i32_16x16x64_i8 v[50:53], v[174:177], v[182:185], v[50:53]
	v_mfma_i32_16x16x64_i8 v[38:41], v[166:169], v[190:193], v[38:41]
	v_mfma_i32_16x16x64_i8 v[34:37], v[174:177], v[190:193], v[34:37]
	v_mfma_i32_16x16x64_i8 v[22:25], v[166:169], v[198:201], v[22:25]
	v_mfma_i32_16x16x64_i8 v[18:21], v[174:177], v[198:201], v[18:21]
	v_mfma_i32_16x16x64_i8 v[6:9], v[166:169], v[206:209], v[6:9]
	v_mfma_i32_16x16x64_i8 v[2:5], v[174:177], v[206:209], v[2:5]
	s_setprio 0
	s_barrier
	s_add_i32 s77, 0, 0x18000
	v_add_u32_e32 v0, s77, v144
	s_add_i32 s78, 0, 0x1c000
	ds_read_b128 v[146:149], v0
	ds_read_b128 v[150:153], v0 offset:1024
	ds_read_b128 v[154:157], v0 offset:2048
	ds_read_b128 v[158:161], v0 offset:3072
	v_add_u32_e32 v0, s78, v144
	ds_read_b128 v[162:165], v0
	ds_read_b128 v[166:169], v0 offset:1024
	ds_read_b128 v[170:173], v0 offset:2048
	ds_read_b128 v[174:177], v0 offset:3072
	s_add_u32 s4, s46, 0x20000
	s_mov_b32 m0, s66
	ds_read_b128 v[178:181], v145 offset:32768
	ds_read_b128 v[182:185], v145 offset:33792
	ds_read_b128 v[186:189], v145 offset:34816
	ds_read_b128 v[190:193], v145 offset:35840
	ds_read_b128 v[194:197], v145 offset:36864
	ds_read_b128 v[198:201], v145 offset:37888
	ds_read_b128 v[202:205], v145 offset:38912
	ds_read_b128 v[206:209], v145 offset:39936
	s_addc_u32 s5, s47, 0
	s_nop 0
	global_load_lds_dwordx4 v130, s[4:5]
	s_mov_b32 m0, s67
	s_nop 0
	global_load_lds_dwordx4 v141, s[4:5]
	s_waitcnt vmcnt(8)
	s_waitcnt lgkmcnt(0)
	s_barrier
	s_setprio 1
	s_waitcnt lgkmcnt(0)
	v_mfma_i32_16x16x64_i8 v[126:129], v[146:149], v[178:181], v[126:129]
	v_mfma_i32_16x16x64_i8 v[122:125], v[154:157], v[178:181], v[122:125]
	v_mfma_i32_16x16x64_i8 v[110:113], v[146:149], v[186:189], v[110:113]
	v_mfma_i32_16x16x64_i8 v[106:109], v[154:157], v[186:189], v[106:109]
	v_mfma_i32_16x16x64_i8 v[94:97], v[146:149], v[194:197], v[94:97]
	v_mfma_i32_16x16x64_i8 v[90:93], v[154:157], v[194:197], v[90:93]
	v_mfma_i32_16x16x64_i8 v[78:81], v[146:149], v[202:205], v[78:81]
	v_mfma_i32_16x16x64_i8 v[74:77], v[154:157], v[202:205], v[74:77]
	v_mfma_i32_16x16x64_i8 v[126:129], v[150:153], v[182:185], v[126:129]
	v_mfma_i32_16x16x64_i8 v[122:125], v[158:161], v[182:185], v[122:125]
	v_mfma_i32_16x16x64_i8 v[110:113], v[150:153], v[190:193], v[110:113]
	v_mfma_i32_16x16x64_i8 v[106:109], v[158:161], v[190:193], v[106:109]
	v_mfma_i32_16x16x64_i8 v[94:97], v[150:153], v[198:201], v[94:97]
	v_mfma_i32_16x16x64_i8 v[90:93], v[158:161], v[198:201], v[90:93]
	v_mfma_i32_16x16x64_i8 v[78:81], v[150:153], v[206:209], v[78:81]
	v_mfma_i32_16x16x64_i8 v[74:77], v[158:161], v[206:209], v[74:77]
	s_setprio 0
	s_setprio 1
	v_mfma_i32_16x16x64_i8 v[118:121], v[162:165], v[178:181], v[118:121]
	v_mfma_i32_16x16x64_i8 v[114:117], v[170:173], v[178:181], v[114:117]
	v_mfma_i32_16x16x64_i8 v[102:105], v[162:165], v[186:189], v[102:105]
	v_mfma_i32_16x16x64_i8 v[98:101], v[170:173], v[186:189], v[98:101]
	v_mfma_i32_16x16x64_i8 v[86:89], v[162:165], v[194:197], v[86:89]
	v_mfma_i32_16x16x64_i8 v[82:85], v[170:173], v[194:197], v[82:85]
	v_mfma_i32_16x16x64_i8 v[70:73], v[162:165], v[202:205], v[70:73]
	v_mfma_i32_16x16x64_i8 v[66:69], v[170:173], v[202:205], v[66:69]
	v_mfma_i32_16x16x64_i8 v[118:121], v[166:169], v[182:185], v[118:121]
	v_mfma_i32_16x16x64_i8 v[114:117], v[174:177], v[182:185], v[114:117]
	v_mfma_i32_16x16x64_i8 v[102:105], v[166:169], v[190:193], v[102:105]
	v_mfma_i32_16x16x64_i8 v[98:101], v[174:177], v[190:193], v[98:101]
	v_mfma_i32_16x16x64_i8 v[86:89], v[166:169], v[198:201], v[86:89]
	v_mfma_i32_16x16x64_i8 v[82:85], v[174:177], v[198:201], v[82:85]
	v_mfma_i32_16x16x64_i8 v[70:73], v[166:169], v[206:209], v[70:73]
	v_mfma_i32_16x16x64_i8 v[66:69], v[174:177], v[206:209], v[66:69]
	s_setprio 0
	s_barrier
	ds_read_b128 v[178:181], v145 offset:49152
	ds_read_b128 v[182:185], v145 offset:50176
	ds_read_b128 v[186:189], v145 offset:51200
	ds_read_b128 v[190:193], v145 offset:52224
	ds_read_b128 v[194:197], v145 offset:53248
	ds_read_b128 v[198:201], v145 offset:54272
	ds_read_b128 v[202:205], v145 offset:55296
	ds_read_b128 v[206:209], v145 offset:56320
	s_add_i32 s4, s77, s60
	s_add_u32 s100, s58, s38
	s_addc_u32 s101, s59, s39
	s_mov_b32 m0, s4
	s_nop 0
	global_load_lds_dwordx4 v131, s[100:101]
	s_add_i32 m0, s4, 0x2000
	s_add_u32 s4, s58, 0x20080
	s_addc_u32 s5, s59, 0
	s_add_i32 s58, s78, s60
	global_load_lds_dwordx4 v142, s[100:101]
	s_mov_b32 m0, s58
	s_nop 0
	global_load_lds_dwordx4 v131, s[4:5]
	s_add_i32 m0, s58, 0x2000
	s_nop 0
	global_load_lds_dwordx4 v142, s[4:5]
	s_mov_b32 m0, s68
	s_add_u32 s100, s46, s38
	s_addc_u32 s101, s47, s39
	v_mov_b32_e32 v0, v141
	global_load_lds_dwordx4 v130, s[100:101]
	s_mov_b32 m0, s69
	s_nop 0
	global_load_lds_dwordx4 v141, s[100:101]
	s_waitcnt vmcnt(8)
	s_waitcnt lgkmcnt(0)
	s_barrier
	s_setprio 1
	s_waitcnt lgkmcnt(0)
	v_mfma_i32_16x16x64_i8 v[62:65], v[146:149], v[178:181], v[62:65]
	v_mfma_i32_16x16x64_i8 v[58:61], v[154:157], v[178:181], v[58:61]
	v_mfma_i32_16x16x64_i8 v[46:49], v[146:149], v[186:189], v[46:49]
	v_mfma_i32_16x16x64_i8 v[42:45], v[154:157], v[186:189], v[42:45]
	v_mfma_i32_16x16x64_i8 v[30:33], v[146:149], v[194:197], v[30:33]
	v_mfma_i32_16x16x64_i8 v[26:29], v[154:157], v[194:197], v[26:29]
	v_mfma_i32_16x16x64_i8 v[14:17], v[146:149], v[202:205], v[14:17]
	v_mfma_i32_16x16x64_i8 v[10:13], v[154:157], v[202:205], v[10:13]
	v_mfma_i32_16x16x64_i8 v[62:65], v[150:153], v[182:185], v[62:65]
	v_mfma_i32_16x16x64_i8 v[58:61], v[158:161], v[182:185], v[58:61]
	v_mfma_i32_16x16x64_i8 v[46:49], v[150:153], v[190:193], v[46:49]
	v_mfma_i32_16x16x64_i8 v[42:45], v[158:161], v[190:193], v[42:45]
	v_mfma_i32_16x16x64_i8 v[30:33], v[150:153], v[198:201], v[30:33]
	v_mfma_i32_16x16x64_i8 v[26:29], v[158:161], v[198:201], v[26:29]
	v_mfma_i32_16x16x64_i8 v[14:17], v[150:153], v[206:209], v[14:17]
	v_mfma_i32_16x16x64_i8 v[10:13], v[158:161], v[206:209], v[10:13]
	s_setprio 0
	s_setprio 1
	v_mfma_i32_16x16x64_i8 v[54:57], v[162:165], v[178:181], v[54:57]
	v_mfma_i32_16x16x64_i8 v[50:53], v[170:173], v[178:181], v[50:53]
	v_mfma_i32_16x16x64_i8 v[38:41], v[162:165], v[186:189], v[38:41]
	v_mfma_i32_16x16x64_i8 v[34:37], v[170:173], v[186:189], v[34:37]
	v_mfma_i32_16x16x64_i8 v[22:25], v[162:165], v[194:197], v[22:25]
	v_mfma_i32_16x16x64_i8 v[18:21], v[170:173], v[194:197], v[18:21]
	v_mfma_i32_16x16x64_i8 v[6:9], v[162:165], v[202:205], v[6:9]
	v_mfma_i32_16x16x64_i8 v[2:5], v[170:173], v[202:205], v[2:5]
	v_mfma_i32_16x16x64_i8 v[54:57], v[166:169], v[182:185], v[54:57]
	v_mfma_i32_16x16x64_i8 v[50:53], v[174:177], v[182:185], v[50:53]
	v_mfma_i32_16x16x64_i8 v[38:41], v[166:169], v[190:193], v[38:41]
	v_mfma_i32_16x16x64_i8 v[34:37], v[174:177], v[190:193], v[34:37]
	v_mfma_i32_16x16x64_i8 v[22:25], v[166:169], v[198:201], v[22:25]
	v_mfma_i32_16x16x64_i8 v[18:21], v[174:177], v[198:201], v[18:21]
	v_mfma_i32_16x16x64_i8 v[6:9], v[166:169], v[206:209], v[6:9]
	v_mfma_i32_16x16x64_i8 v[2:5], v[174:177], v[206:209], v[2:5]
	s_setprio 0
	s_barrier
	s_add_i32 s76, s76, 2
	s_add_u32 s50, s50, 0x100
	s_addc_u32 s51, s51, 0
	s_cmp_gt_u32 s76, 5
	s_cbranch_scc0 .LBB0_667
	s_cmpk_lt_u32 s17, 0x100
	s_cbranch_scc0 .LBB0_661
	s_barrier
	s_branch .LBB0_661

.LBB0_821:
	s_add_u32 s4, s79, s50
	s_addc_u32 s5, s82, s51
	s_add_u32 s46, s4, 0x9800100
	s_addc_u32 s47, s5, 0
	s_add_u32 s58, s64, s50
	s_addc_u32 s59, s83, s51
	s_add_i32 s85, 0, 0x10000
	s_cmpk_eq_i32 s50, 0x1500
	s_cselect_b32 s47, s49, s47
	s_cselect_b32 s46, s48, s46
	v_add_u32_e32 v0, s85, v134
	s_cselect_b32 s59, s71, s59
	s_cselect_b32 s58, s70, s58
	s_add_i32 s86, 0, 0x14000
	ds_read_b128 v[136:139], v0
	ds_read_b128 v[140:143], v0 offset:1024
	ds_read_b128 v[144:147], v0 offset:2048
	ds_read_b128 v[148:151], v0 offset:3072
	v_add_u32_e32 v0, s86, v134
	ds_read_b128 v[152:155], v0
	ds_read_b128 v[156:159], v0 offset:1024
	ds_read_b128 v[160:163], v0 offset:2048
	ds_read_b128 v[164:167], v0 offset:3072
	ds_read_b128 v[168:171], v135
	ds_read_b128 v[172:175], v135 offset:1024
	ds_read_b128 v[176:179], v135 offset:2048
	ds_read_b128 v[180:183], v135 offset:3072
	ds_read_b128 v[184:187], v135 offset:4096
	ds_read_b128 v[188:191], v135 offset:5120
	ds_read_b128 v[192:195], v135 offset:6144
	ds_read_b128 v[198:201], v135 offset:7168
	s_add_i32 m0, s60, 0xc000
	s_add_u32 s100, s4, s88
	s_addc_u32 s101, s5, s89
	global_load_lds_dwordx4 v130, s[100:101]
	s_add_i32 m0, s60, 0xe000
	s_nop 0
	global_load_lds_dwordx4 v131, s[100:101]
	s_waitcnt vmcnt(8)
	s_waitcnt lgkmcnt(0)
	s_barrier
	s_setprio 1
	s_waitcnt lgkmcnt(0)
	v_mfma_f32_16x16x32_bf16 v[126:129], v[136:139], v[168:171], v[126:129]
	v_mfma_f32_16x16x32_bf16 v[122:125], v[144:147], v[168:171], v[122:125]
	v_mfma_f32_16x16x32_bf16 v[110:113], v[136:139], v[176:179], v[110:113]
	v_mfma_f32_16x16x32_bf16 v[106:109], v[144:147], v[176:179], v[106:109]
	v_mfma_f32_16x16x32_bf16 v[94:97], v[136:139], v[184:187], v[94:97]
	v_mfma_f32_16x16x32_bf16 v[90:93], v[144:147], v[184:187], v[90:93]
	v_mfma_f32_16x16x32_bf16 v[78:81], v[136:139], v[192:195], v[78:81]
	v_mfma_f32_16x16x32_bf16 v[74:77], v[144:147], v[192:195], v[74:77]
	v_mfma_f32_16x16x32_bf16 v[126:129], v[140:143], v[172:175], v[126:129]
	v_mfma_f32_16x16x32_bf16 v[122:125], v[148:151], v[172:175], v[122:125]
	v_mfma_f32_16x16x32_bf16 v[110:113], v[140:143], v[180:183], v[110:113]
	v_mfma_f32_16x16x32_bf16 v[106:109], v[148:151], v[180:183], v[106:109]
	v_mfma_f32_16x16x32_bf16 v[94:97], v[140:143], v[188:191], v[94:97]
	v_mfma_f32_16x16x32_bf16 v[90:93], v[148:151], v[188:191], v[90:93]
	v_mfma_f32_16x16x32_bf16 v[78:81], v[140:143], v[198:201], v[78:81]
	v_mfma_f32_16x16x32_bf16 v[74:77], v[148:151], v[198:201], v[74:77]
	s_setprio 0
	s_setprio 1
	v_mfma_f32_16x16x32_bf16 v[118:121], v[152:155], v[168:171], v[118:121]
	v_mfma_f32_16x16x32_bf16 v[114:117], v[160:163], v[168:171], v[114:117]
	v_mfma_f32_16x16x32_bf16 v[102:105], v[152:155], v[176:179], v[102:105]
	v_mfma_f32_16x16x32_bf16 v[98:101], v[160:163], v[176:179], v[98:101]
	v_mfma_f32_16x16x32_bf16 v[86:89], v[152:155], v[184:187], v[86:89]
	v_mfma_f32_16x16x32_bf16 v[82:85], v[160:163], v[184:187], v[82:85]
	v_mfma_f32_16x16x32_bf16 v[70:73], v[152:155], v[192:195], v[70:73]
	v_mfma_f32_16x16x32_bf16 v[66:69], v[160:163], v[192:195], v[66:69]
	v_mfma_f32_16x16x32_bf16 v[118:121], v[156:159], v[172:175], v[118:121]
	v_mfma_f32_16x16x32_bf16 v[114:117], v[164:167], v[172:175], v[114:117]
	v_mfma_f32_16x16x32_bf16 v[102:105], v[156:159], v[180:183], v[102:105]
	v_mfma_f32_16x16x32_bf16 v[98:101], v[164:167], v[180:183], v[98:101]
	v_mfma_f32_16x16x32_bf16 v[86:89], v[156:159], v[188:191], v[86:89]
	v_mfma_f32_16x16x32_bf16 v[82:85], v[164:167], v[188:191], v[82:85]
	v_mfma_f32_16x16x32_bf16 v[70:73], v[156:159], v[198:201], v[70:73]
	v_mfma_f32_16x16x32_bf16 v[66:69], v[164:167], v[198:201], v[66:69]
	s_setprio 0
	s_barrier
	s_add_i32 s4, s85, s26
	ds_read_b128 v[168:171], v135 offset:16384
	ds_read_b128 v[172:175], v135 offset:17408
	ds_read_b128 v[176:179], v135 offset:18432
	ds_read_b128 v[180:183], v135 offset:19456
	ds_read_b128 v[184:187], v135 offset:20480
	ds_read_b128 v[188:191], v135 offset:21504
	ds_read_b128 v[192:195], v135 offset:22528
	ds_read_b128 v[198:201], v135 offset:23552
	s_mov_b32 m0, s4
	s_nop 0
	global_load_lds_dwordx4 v132, s[58:59]
	s_add_i32 m0, s4, 0x2000
	s_add_u32 s4, s58, 0xb0000
	global_load_lds_dwordx4 v133, s[58:59]
	s_addc_u32 s5, s59, 0
	s_add_i32 s85, s86, s26
	s_mov_b32 m0, s85
	s_nop 0
	global_load_lds_dwordx4 v132, s[4:5]
	s_add_i32 m0, s85, 0x2000
	s_nop 0
	global_load_lds_dwordx4 v133, s[4:5]
	s_mov_b32 m0, s60
	s_nop 0
	global_load_lds_dwordx4 v130, s[46:47]
	s_mov_b32 m0, s65
	s_nop 0
	global_load_lds_dwordx4 v131, s[46:47]
	s_waitcnt vmcnt(8)
	s_waitcnt lgkmcnt(0)
	s_barrier
	s_setprio 1
	s_waitcnt lgkmcnt(0)
	v_mfma_f32_16x16x32_bf16 v[62:65], v[136:139], v[168:171], v[62:65]
	v_mfma_f32_16x16x32_bf16 v[58:61], v[144:147], v[168:171], v[58:61]
	v_mfma_f32_16x16x32_bf16 v[46:49], v[136:139], v[176:179], v[46:49]
	v_mfma_f32_16x16x32_bf16 v[42:45], v[144:147], v[176:179], v[42:45]
	v_mfma_f32_16x16x32_bf16 v[30:33], v[136:139], v[184:187], v[30:33]
	v_mfma_f32_16x16x32_bf16 v[26:29], v[144:147], v[184:187], v[26:29]
	v_mfma_f32_16x16x32_bf16 v[14:17], v[136:139], v[192:195], v[14:17]
	v_mfma_f32_16x16x32_bf16 v[10:13], v[144:147], v[192:195], v[10:13]
	v_mfma_f32_16x16x32_bf16 v[62:65], v[140:143], v[172:175], v[62:65]
	v_mfma_f32_16x16x32_bf16 v[58:61], v[148:151], v[172:175], v[58:61]
	v_mfma_f32_16x16x32_bf16 v[46:49], v[140:143], v[180:183], v[46:49]
	v_mfma_f32_16x16x32_bf16 v[42:45], v[148:151], v[180:183], v[42:45]
	v_mfma_f32_16x16x32_bf16 v[30:33], v[140:143], v[188:191], v[30:33]
	v_mfma_f32_16x16x32_bf16 v[26:29], v[148:151], v[188:191], v[26:29]
	v_mfma_f32_16x16x32_bf16 v[14:17], v[140:143], v[198:201], v[14:17]
	v_mfma_f32_16x16x32_bf16 v[10:13], v[148:151], v[198:201], v[10:13]
	s_setprio 0
	s_setprio 1
	v_mfma_f32_16x16x32_bf16 v[54:57], v[152:155], v[168:171], v[54:57]
	v_mfma_f32_16x16x32_bf16 v[50:53], v[160:163], v[168:171], v[50:53]
	v_mfma_f32_16x16x32_bf16 v[38:41], v[152:155], v[176:179], v[38:41]
	v_mfma_f32_16x16x32_bf16 v[34:37], v[160:163], v[176:179], v[34:37]
	v_mfma_f32_16x16x32_bf16 v[22:25], v[152:155], v[184:187], v[22:25]
	v_mfma_f32_16x16x32_bf16 v[18:21], v[160:163], v[184:187], v[18:21]
	v_mfma_f32_16x16x32_bf16 v[6:9], v[152:155], v[192:195], v[6:9]
	v_mfma_f32_16x16x32_bf16 v[2:5], v[160:163], v[192:195], v[2:5]
	v_mfma_f32_16x16x32_bf16 v[54:57], v[156:159], v[172:175], v[54:57]
	v_mfma_f32_16x16x32_bf16 v[50:53], v[164:167], v[172:175], v[50:53]
	v_mfma_f32_16x16x32_bf16 v[38:41], v[156:159], v[180:183], v[38:41]
	v_mfma_f32_16x16x32_bf16 v[34:37], v[164:167], v[180:183], v[34:37]
	v_mfma_f32_16x16x32_bf16 v[22:25], v[156:159], v[188:191], v[22:25]
	v_mfma_f32_16x16x32_bf16 v[18:21], v[164:167], v[188:191], v[18:21]
	v_mfma_f32_16x16x32_bf16 v[6:9], v[156:159], v[198:201], v[6:9]
	v_mfma_f32_16x16x32_bf16 v[2:5], v[164:167], v[198:201], v[2:5]
	s_setprio 0
	s_barrier
	s_add_i32 s85, 0, 0x18000
	v_add_u32_e32 v0, s85, v134
	s_add_i32 s86, 0, 0x1c000
	ds_read_b128 v[136:139], v0
	ds_read_b128 v[140:143], v0 offset:1024
	ds_read_b128 v[144:147], v0 offset:2048
	ds_read_b128 v[148:151], v0 offset:3072
	v_add_u32_e32 v0, s86, v134
	ds_read_b128 v[152:155], v0
	ds_read_b128 v[156:159], v0 offset:1024
	ds_read_b128 v[160:163], v0 offset:2048
	ds_read_b128 v[164:167], v0 offset:3072
	s_add_u32 s4, s46, 0xb0000
	s_mov_b32 m0, s68
	ds_read_b128 v[168:171], v135 offset:32768
	ds_read_b128 v[172:175], v135 offset:33792
	ds_read_b128 v[176:179], v135 offset:34816
	ds_read_b128 v[180:183], v135 offset:35840
	ds_read_b128 v[184:187], v135 offset:36864
	ds_read_b128 v[188:191], v135 offset:37888
	ds_read_b128 v[192:195], v135 offset:38912
	ds_read_b128 v[198:201], v135 offset:39936
	s_addc_u32 s5, s47, 0
	s_nop 0
	global_load_lds_dwordx4 v130, s[4:5]
	s_mov_b32 m0, s69
	s_nop 0
	global_load_lds_dwordx4 v131, s[4:5]
	s_waitcnt vmcnt(8)
	s_waitcnt lgkmcnt(0)
	s_barrier
	s_setprio 1
	s_waitcnt lgkmcnt(0)
	v_mfma_f32_16x16x32_bf16 v[126:129], v[136:139], v[168:171], v[126:129]
	v_mfma_f32_16x16x32_bf16 v[122:125], v[144:147], v[168:171], v[122:125]
	v_mfma_f32_16x16x32_bf16 v[110:113], v[136:139], v[176:179], v[110:113]
	v_mfma_f32_16x16x32_bf16 v[106:109], v[144:147], v[176:179], v[106:109]
	v_mfma_f32_16x16x32_bf16 v[94:97], v[136:139], v[184:187], v[94:97]
	v_mfma_f32_16x16x32_bf16 v[90:93], v[144:147], v[184:187], v[90:93]
	v_mfma_f32_16x16x32_bf16 v[78:81], v[136:139], v[192:195], v[78:81]
	v_mfma_f32_16x16x32_bf16 v[74:77], v[144:147], v[192:195], v[74:77]
	v_mfma_f32_16x16x32_bf16 v[126:129], v[140:143], v[172:175], v[126:129]
	v_mfma_f32_16x16x32_bf16 v[122:125], v[148:151], v[172:175], v[122:125]
	v_mfma_f32_16x16x32_bf16 v[110:113], v[140:143], v[180:183], v[110:113]
	v_mfma_f32_16x16x32_bf16 v[106:109], v[148:151], v[180:183], v[106:109]
	v_mfma_f32_16x16x32_bf16 v[94:97], v[140:143], v[188:191], v[94:97]
	v_mfma_f32_16x16x32_bf16 v[90:93], v[148:151], v[188:191], v[90:93]
	v_mfma_f32_16x16x32_bf16 v[78:81], v[140:143], v[198:201], v[78:81]
	v_mfma_f32_16x16x32_bf16 v[74:77], v[148:151], v[198:201], v[74:77]
	s_setprio 0
	s_setprio 1
	v_mfma_f32_16x16x32_bf16 v[118:121], v[152:155], v[168:171], v[118:121]
	v_mfma_f32_16x16x32_bf16 v[114:117], v[160:163], v[168:171], v[114:117]
	v_mfma_f32_16x16x32_bf16 v[102:105], v[152:155], v[176:179], v[102:105]
	v_mfma_f32_16x16x32_bf16 v[98:101], v[160:163], v[176:179], v[98:101]
	v_mfma_f32_16x16x32_bf16 v[86:89], v[152:155], v[184:187], v[86:89]
	v_mfma_f32_16x16x32_bf16 v[82:85], v[160:163], v[184:187], v[82:85]
	v_mfma_f32_16x16x32_bf16 v[70:73], v[152:155], v[192:195], v[70:73]
	v_mfma_f32_16x16x32_bf16 v[66:69], v[160:163], v[192:195], v[66:69]
	v_mfma_f32_16x16x32_bf16 v[118:121], v[156:159], v[172:175], v[118:121]
	v_mfma_f32_16x16x32_bf16 v[114:117], v[164:167], v[172:175], v[114:117]
	v_mfma_f32_16x16x32_bf16 v[102:105], v[156:159], v[180:183], v[102:105]
	v_mfma_f32_16x16x32_bf16 v[98:101], v[164:167], v[180:183], v[98:101]
	v_mfma_f32_16x16x32_bf16 v[86:89], v[156:159], v[188:191], v[86:89]
	v_mfma_f32_16x16x32_bf16 v[82:85], v[164:167], v[188:191], v[82:85]
	v_mfma_f32_16x16x32_bf16 v[70:73], v[156:159], v[198:201], v[70:73]
	v_mfma_f32_16x16x32_bf16 v[66:69], v[164:167], v[198:201], v[66:69]
	s_setprio 0
	s_barrier
	ds_read_b128 v[168:171], v135 offset:49152
	ds_read_b128 v[172:175], v135 offset:50176
	ds_read_b128 v[176:179], v135 offset:51200
	ds_read_b128 v[180:183], v135 offset:52224
	ds_read_b128 v[184:187], v135 offset:53248
	ds_read_b128 v[188:191], v135 offset:54272
	ds_read_b128 v[192:195], v135 offset:55296
	ds_read_b128 v[198:201], v135 offset:56320
	s_add_i32 s4, s85, s26
	s_add_u32 s100, s58, s38
	s_addc_u32 s101, s59, s39
	s_mov_b32 m0, s4
	s_nop 0
	global_load_lds_dwordx4 v132, s[100:101]
	s_add_i32 m0, s4, 0x2000
	s_add_u32 s4, s58, 0xb0080
	s_addc_u32 s5, s59, 0
	s_add_i32 s58, s86, s26
	global_load_lds_dwordx4 v133, s[100:101]
	s_mov_b32 m0, s58
	s_nop 0
	global_load_lds_dwordx4 v132, s[4:5]
	s_add_i32 m0, s58, 0x2000
	s_nop 0
	global_load_lds_dwordx4 v133, s[4:5]
	s_mov_b32 m0, s75
	s_add_u32 s100, s46, s38
	s_addc_u32 s101, s47, s39
	v_mov_b32_e32 v0, v131
	global_load_lds_dwordx4 v130, s[100:101]
	s_mov_b32 m0, s78
	s_nop 0
	global_load_lds_dwordx4 v131, s[100:101]
	s_waitcnt vmcnt(8)
	s_waitcnt lgkmcnt(0)
	s_barrier
	s_setprio 1
	s_waitcnt lgkmcnt(0)
	v_mfma_f32_16x16x32_bf16 v[62:65], v[136:139], v[168:171], v[62:65]
	v_mfma_f32_16x16x32_bf16 v[58:61], v[144:147], v[168:171], v[58:61]
	v_mfma_f32_16x16x32_bf16 v[46:49], v[136:139], v[176:179], v[46:49]
	v_mfma_f32_16x16x32_bf16 v[42:45], v[144:147], v[176:179], v[42:45]
	v_mfma_f32_16x16x32_bf16 v[30:33], v[136:139], v[184:187], v[30:33]
	v_mfma_f32_16x16x32_bf16 v[26:29], v[144:147], v[184:187], v[26:29]
	v_mfma_f32_16x16x32_bf16 v[14:17], v[136:139], v[192:195], v[14:17]
	v_mfma_f32_16x16x32_bf16 v[10:13], v[144:147], v[192:195], v[10:13]
	v_mfma_f32_16x16x32_bf16 v[62:65], v[140:143], v[172:175], v[62:65]
	v_mfma_f32_16x16x32_bf16 v[58:61], v[148:151], v[172:175], v[58:61]
	v_mfma_f32_16x16x32_bf16 v[46:49], v[140:143], v[180:183], v[46:49]
	v_mfma_f32_16x16x32_bf16 v[42:45], v[148:151], v[180:183], v[42:45]
	v_mfma_f32_16x16x32_bf16 v[30:33], v[140:143], v[188:191], v[30:33]
	v_mfma_f32_16x16x32_bf16 v[26:29], v[148:151], v[188:191], v[26:29]
	v_mfma_f32_16x16x32_bf16 v[14:17], v[140:143], v[198:201], v[14:17]
	v_mfma_f32_16x16x32_bf16 v[10:13], v[148:151], v[198:201], v[10:13]
	s_setprio 0
	s_setprio 1
	v_mfma_f32_16x16x32_bf16 v[54:57], v[152:155], v[168:171], v[54:57]
	v_mfma_f32_16x16x32_bf16 v[50:53], v[160:163], v[168:171], v[50:53]
	v_mfma_f32_16x16x32_bf16 v[38:41], v[152:155], v[176:179], v[38:41]
	v_mfma_f32_16x16x32_bf16 v[34:37], v[160:163], v[176:179], v[34:37]
	v_mfma_f32_16x16x32_bf16 v[22:25], v[152:155], v[184:187], v[22:25]
	v_mfma_f32_16x16x32_bf16 v[18:21], v[160:163], v[184:187], v[18:21]
	v_mfma_f32_16x16x32_bf16 v[6:9], v[152:155], v[192:195], v[6:9]
	v_mfma_f32_16x16x32_bf16 v[2:5], v[160:163], v[192:195], v[2:5]
	v_mfma_f32_16x16x32_bf16 v[54:57], v[156:159], v[172:175], v[54:57]
	v_mfma_f32_16x16x32_bf16 v[50:53], v[164:167], v[172:175], v[50:53]
	v_mfma_f32_16x16x32_bf16 v[38:41], v[156:159], v[180:183], v[38:41]
	v_mfma_f32_16x16x32_bf16 v[34:37], v[164:167], v[180:183], v[34:37]
	v_mfma_f32_16x16x32_bf16 v[22:25], v[156:159], v[188:191], v[22:25]
	v_mfma_f32_16x16x32_bf16 v[18:21], v[164:167], v[188:191], v[18:21]
	v_mfma_f32_16x16x32_bf16 v[6:9], v[156:159], v[198:201], v[6:9]
	v_mfma_f32_16x16x32_bf16 v[2:5], v[164:167], v[198:201], v[2:5]
	s_setprio 0
	s_barrier
	s_add_i32 s84, s84, 2
	s_add_u32 s50, s50, 0x100
	s_addc_u32 s51, s51, 0
	s_cmp_gt_u32 s84, 41
	s_cbranch_scc0 .LBB0_821
	s_cmpk_lt_u32 s24, 0x100
	s_cbranch_scc0 .LBB0_824
	s_barrier

.LBB0_869:
	s_add_u32 s4, s10, s2
	s_addc_u32 s5, s11, s3
	s_add_u32 s22, s4, 0x100
	s_addc_u32 s23, s5, 0
	s_add_u32 s46, s58, s2
	s_addc_u32 s47, s59, s3
	s_add_i32 s69, 0, 0x10000
	s_cmp_eq_u32 s68, 40
	s_cselect_b32 s23, s11, s23
	s_cselect_b32 s22, s10, s22
	v_add_u32_e32 v0, s69, v126
	s_cselect_b32 s47, s17, s47
	s_cselect_b32 s46, s16, s46
	s_add_i32 s70, 0, 0x14000
	ds_read_b128 v[128:131], v0
	ds_read_b128 v[142:145], v0 offset:1024
	ds_read_b128 v[146:149], v0 offset:2048
	ds_read_b128 v[150:153], v0 offset:3072
	v_add_u32_e32 v0, s70, v126
	ds_read_b128 v[154:157], v0
	ds_read_b128 v[160:163], v0 offset:1024
	ds_read_b128 v[164:167], v0 offset:2048
	ds_read_b128 v[168:171], v0 offset:3072
	ds_read_b128 v[172:175], v127
	ds_read_b128 v[176:179], v127 offset:1024
	ds_read_b128 v[180:183], v127 offset:2048
	ds_read_b128 v[184:187], v127 offset:3072
	ds_read_b128 v[188:191], v127 offset:4096
	ds_read_b128 v[192:195], v127 offset:5120
	ds_read_b128 v[196:199], v127 offset:6144
	ds_read_b128 v[200:203], v127 offset:7168
	s_add_i32 m0, s41, 0xc000
	s_add_u32 s100, s4, s62
	s_addc_u32 s101, s5, s63
	global_load_lds_dwordx4 v122, s[100:101]
	s_add_i32 m0, s41, 0xe000
	s_nop 0
	global_load_lds_dwordx4 v123, s[100:101]
	s_waitcnt vmcnt(8)
	s_waitcnt lgkmcnt(0)
	s_barrier
	s_setprio 1
	s_waitcnt lgkmcnt(0)
	v_mfma_f32_16x16x32_bf16 v[138:141], v[128:131], v[172:175], v[138:141]
	v_mfma_f32_16x16x32_bf16 v[132:135], v[146:149], v[172:175], v[134:137]
	v_mfma_f32_16x16x32_bf16 v[110:113], v[128:131], v[180:183], v[110:113]
	v_mfma_f32_16x16x32_bf16 v[106:109], v[146:149], v[180:183], v[106:109]
	v_mfma_f32_16x16x32_bf16 v[94:97], v[128:131], v[188:191], v[94:97]
	v_mfma_f32_16x16x32_bf16 v[90:93], v[146:149], v[188:191], v[90:93]
	v_mfma_f32_16x16x32_bf16 v[78:81], v[128:131], v[196:199], v[78:81]
	v_mfma_f32_16x16x32_bf16 v[74:77], v[146:149], v[196:199], v[74:77]
	v_mfma_f32_16x16x32_bf16 v[138:141], v[142:145], v[176:179], v[138:141]
	v_mfma_f32_16x16x32_bf16 v[132:135], v[150:153], v[176:179], v[132:135]
	v_mfma_f32_16x16x32_bf16 v[110:113], v[142:145], v[184:187], v[110:113]
	v_mfma_f32_16x16x32_bf16 v[106:109], v[150:153], v[184:187], v[106:109]
	v_mfma_f32_16x16x32_bf16 v[94:97], v[142:145], v[192:195], v[94:97]
	v_mfma_f32_16x16x32_bf16 v[90:93], v[150:153], v[192:195], v[90:93]
	v_mfma_f32_16x16x32_bf16 v[78:81], v[142:145], v[200:203], v[78:81]
	v_mfma_f32_16x16x32_bf16 v[74:77], v[150:153], v[200:203], v[74:77]
	s_setprio 0
	s_setprio 1
	v_mfma_f32_16x16x32_bf16 v[118:121], v[154:157], v[172:175], v[118:121]
	v_mfma_f32_16x16x32_bf16 v[114:117], v[164:167], v[172:175], v[114:117]
	v_mfma_f32_16x16x32_bf16 v[102:105], v[154:157], v[180:183], v[102:105]
	v_mfma_f32_16x16x32_bf16 v[98:101], v[164:167], v[180:183], v[98:101]
	v_mfma_f32_16x16x32_bf16 v[86:89], v[154:157], v[188:191], v[86:89]
	v_mfma_f32_16x16x32_bf16 v[82:85], v[164:167], v[188:191], v[82:85]
	v_mfma_f32_16x16x32_bf16 v[70:73], v[154:157], v[196:199], v[70:73]
	v_mfma_f32_16x16x32_bf16 v[66:69], v[164:167], v[196:199], v[66:69]
	v_mfma_f32_16x16x32_bf16 v[118:121], v[160:163], v[176:179], v[118:121]
	v_mfma_f32_16x16x32_bf16 v[114:117], v[168:171], v[176:179], v[114:117]
	v_mfma_f32_16x16x32_bf16 v[102:105], v[160:163], v[184:187], v[102:105]
	v_mfma_f32_16x16x32_bf16 v[98:101], v[168:171], v[184:187], v[98:101]
	v_mfma_f32_16x16x32_bf16 v[86:89], v[160:163], v[192:195], v[86:89]
	v_mfma_f32_16x16x32_bf16 v[82:85], v[168:171], v[192:195], v[82:85]
	v_mfma_f32_16x16x32_bf16 v[70:73], v[160:163], v[200:203], v[70:73]
	v_mfma_f32_16x16x32_bf16 v[66:69], v[168:171], v[200:203], v[66:69]
	s_setprio 0
	s_barrier
	s_add_i32 s4, s69, s26
	ds_read_b128 v[172:175], v127 offset:16384
	ds_read_b128 v[176:179], v127 offset:17408
	ds_read_b128 v[180:183], v127 offset:18432
	ds_read_b128 v[184:187], v127 offset:19456
	ds_read_b128 v[188:191], v127 offset:20480
	ds_read_b128 v[192:195], v127 offset:21504
	ds_read_b128 v[196:199], v127 offset:22528
	ds_read_b128 v[200:203], v127 offset:23552
	s_mov_b32 m0, s4
	s_nop 0
	global_load_lds_dwordx4 v124, s[46:47]
	s_add_i32 m0, s4, 0x2000
	s_add_u32 s4, s46, 0xb0000
	global_load_lds_dwordx4 v125, s[46:47]
	s_addc_u32 s5, s47, 0
	s_add_i32 s69, s70, s26
	s_mov_b32 m0, s69
	s_nop 0
	global_load_lds_dwordx4 v124, s[4:5]
	s_add_i32 m0, s69, 0x2000
	s_nop 0
	global_load_lds_dwordx4 v125, s[4:5]
	s_mov_b32 m0, s41
	s_nop 0
	global_load_lds_dwordx4 v122, s[22:23]
	s_mov_b32 m0, s48
	s_nop 0
	global_load_lds_dwordx4 v123, s[22:23]
	s_waitcnt vmcnt(8)
	s_waitcnt lgkmcnt(0)
	s_barrier
	s_setprio 1
	s_waitcnt lgkmcnt(0)
	v_mfma_f32_16x16x32_bf16 v[62:65], v[128:131], v[172:175], v[62:65]
	v_mfma_f32_16x16x32_bf16 v[58:61], v[146:149], v[172:175], v[58:61]
	v_mfma_f32_16x16x32_bf16 v[46:49], v[128:131], v[180:183], v[46:49]
	v_mfma_f32_16x16x32_bf16 v[42:45], v[146:149], v[180:183], v[42:45]
	v_mfma_f32_16x16x32_bf16 v[30:33], v[128:131], v[188:191], v[30:33]
	v_mfma_f32_16x16x32_bf16 v[26:29], v[146:149], v[188:191], v[26:29]
	v_mfma_f32_16x16x32_bf16 v[14:17], v[128:131], v[196:199], v[14:17]
	v_mfma_f32_16x16x32_bf16 v[10:13], v[146:149], v[196:199], v[10:13]
	v_mfma_f32_16x16x32_bf16 v[62:65], v[142:145], v[176:179], v[62:65]
	v_mfma_f32_16x16x32_bf16 v[58:61], v[150:153], v[176:179], v[58:61]
	v_mfma_f32_16x16x32_bf16 v[46:49], v[142:145], v[184:187], v[46:49]
	v_mfma_f32_16x16x32_bf16 v[42:45], v[150:153], v[184:187], v[42:45]
	v_mfma_f32_16x16x32_bf16 v[30:33], v[142:145], v[192:195], v[30:33]
	v_mfma_f32_16x16x32_bf16 v[26:29], v[150:153], v[192:195], v[26:29]
	v_mfma_f32_16x16x32_bf16 v[14:17], v[142:145], v[200:203], v[14:17]
	v_mfma_f32_16x16x32_bf16 v[10:13], v[150:153], v[200:203], v[10:13]
	s_setprio 0
	s_setprio 1
	v_mfma_f32_16x16x32_bf16 v[54:57], v[154:157], v[172:175], v[54:57]
	v_mfma_f32_16x16x32_bf16 v[50:53], v[164:167], v[172:175], v[50:53]
	v_mfma_f32_16x16x32_bf16 v[38:41], v[154:157], v[180:183], v[38:41]
	v_mfma_f32_16x16x32_bf16 v[34:37], v[164:167], v[180:183], v[34:37]
	v_mfma_f32_16x16x32_bf16 v[22:25], v[154:157], v[188:191], v[22:25]
	v_mfma_f32_16x16x32_bf16 v[18:21], v[164:167], v[188:191], v[18:21]
	v_mfma_f32_16x16x32_bf16 v[6:9], v[154:157], v[196:199], v[6:9]
	v_mfma_f32_16x16x32_bf16 v[2:5], v[164:167], v[196:199], v[2:5]
	v_mfma_f32_16x16x32_bf16 v[54:57], v[160:163], v[176:179], v[54:57]
	v_mfma_f32_16x16x32_bf16 v[50:53], v[168:171], v[176:179], v[50:53]
	v_mfma_f32_16x16x32_bf16 v[38:41], v[160:163], v[184:187], v[38:41]
	v_mfma_f32_16x16x32_bf16 v[34:37], v[168:171], v[184:187], v[34:37]
	v_mfma_f32_16x16x32_bf16 v[22:25], v[160:163], v[192:195], v[22:25]
	v_mfma_f32_16x16x32_bf16 v[18:21], v[168:171], v[192:195], v[18:21]
	v_mfma_f32_16x16x32_bf16 v[6:9], v[160:163], v[200:203], v[6:9]
	v_mfma_f32_16x16x32_bf16 v[2:5], v[168:171], v[200:203], v[2:5]
	s_setprio 0
	s_barrier
	s_add_i32 s69, 0, 0x18000
	v_add_u32_e32 v0, s69, v126
	s_add_i32 s70, 0, 0x1c000
	ds_read_b128 v[128:131], v0
	ds_read_b128 v[142:145], v0 offset:1024
	ds_read_b128 v[146:149], v0 offset:2048
	ds_read_b128 v[150:153], v0 offset:3072
	v_add_u32_e32 v0, s70, v126
	ds_read_b128 v[154:157], v0
	ds_read_b128 v[160:163], v0 offset:1024
	ds_read_b128 v[164:167], v0 offset:2048
	ds_read_b128 v[168:171], v0 offset:3072
	s_add_u32 s4, s22, 0xb0000
	s_mov_b32 m0, s49
	ds_read_b128 v[172:175], v127 offset:32768
	ds_read_b128 v[176:179], v127 offset:33792
	ds_read_b128 v[180:183], v127 offset:34816
	ds_read_b128 v[184:187], v127 offset:35840
	ds_read_b128 v[188:191], v127 offset:36864
	ds_read_b128 v[192:195], v127 offset:37888
	ds_read_b128 v[196:199], v127 offset:38912
	ds_read_b128 v[200:203], v127 offset:39936
	s_addc_u32 s5, s23, 0
	s_nop 0
	global_load_lds_dwordx4 v122, s[4:5]
	s_mov_b32 m0, s50
	s_nop 0
	global_load_lds_dwordx4 v123, s[4:5]
	s_waitcnt vmcnt(8)
	s_waitcnt lgkmcnt(0)
	s_barrier
	s_setprio 1
	s_waitcnt lgkmcnt(0)
	v_mfma_f32_16x16x32_bf16 v[136:139], v[128:131], v[172:175], v[138:141]
	v_mfma_f32_16x16x32_bf16 v[132:135], v[146:149], v[172:175], v[132:135]
	v_mfma_f32_16x16x32_bf16 v[110:113], v[128:131], v[180:183], v[110:113]
	v_mfma_f32_16x16x32_bf16 v[106:109], v[146:149], v[180:183], v[106:109]
	v_mfma_f32_16x16x32_bf16 v[94:97], v[128:131], v[188:191], v[94:97]
	v_mfma_f32_16x16x32_bf16 v[90:93], v[146:149], v[188:191], v[90:93]
	v_mfma_f32_16x16x32_bf16 v[78:81], v[128:131], v[196:199], v[78:81]
	v_mfma_f32_16x16x32_bf16 v[74:77], v[146:149], v[196:199], v[74:77]
	v_mfma_f32_16x16x32_bf16 v[138:141], v[142:145], v[176:179], v[136:139]
	v_mfma_f32_16x16x32_bf16 v[134:137], v[150:153], v[176:179], v[132:135]
	v_mfma_f32_16x16x32_bf16 v[110:113], v[142:145], v[184:187], v[110:113]
	v_mfma_f32_16x16x32_bf16 v[106:109], v[150:153], v[184:187], v[106:109]
	v_mfma_f32_16x16x32_bf16 v[94:97], v[142:145], v[192:195], v[94:97]
	v_mfma_f32_16x16x32_bf16 v[90:93], v[150:153], v[192:195], v[90:93]
	v_mfma_f32_16x16x32_bf16 v[78:81], v[142:145], v[200:203], v[78:81]
	v_mfma_f32_16x16x32_bf16 v[74:77], v[150:153], v[200:203], v[74:77]
	s_setprio 0
	s_setprio 1
	v_mfma_f32_16x16x32_bf16 v[118:121], v[154:157], v[172:175], v[118:121]
	v_mfma_f32_16x16x32_bf16 v[114:117], v[164:167], v[172:175], v[114:117]
	v_mfma_f32_16x16x32_bf16 v[102:105], v[154:157], v[180:183], v[102:105]
	v_mfma_f32_16x16x32_bf16 v[98:101], v[164:167], v[180:183], v[98:101]
	v_mfma_f32_16x16x32_bf16 v[86:89], v[154:157], v[188:191], v[86:89]
	v_mfma_f32_16x16x32_bf16 v[82:85], v[164:167], v[188:191], v[82:85]
	v_mfma_f32_16x16x32_bf16 v[70:73], v[154:157], v[196:199], v[70:73]
	v_mfma_f32_16x16x32_bf16 v[66:69], v[164:167], v[196:199], v[66:69]
	v_mfma_f32_16x16x32_bf16 v[118:121], v[160:163], v[176:179], v[118:121]
	v_mfma_f32_16x16x32_bf16 v[114:117], v[168:171], v[176:179], v[114:117]
	v_mfma_f32_16x16x32_bf16 v[102:105], v[160:163], v[184:187], v[102:105]
	v_mfma_f32_16x16x32_bf16 v[98:101], v[168:171], v[184:187], v[98:101]
	v_mfma_f32_16x16x32_bf16 v[86:89], v[160:163], v[192:195], v[86:89]
	v_mfma_f32_16x16x32_bf16 v[82:85], v[168:171], v[192:195], v[82:85]
	v_mfma_f32_16x16x32_bf16 v[70:73], v[160:163], v[200:203], v[70:73]
	v_mfma_f32_16x16x32_bf16 v[66:69], v[168:171], v[200:203], v[66:69]
	s_setprio 0
	s_barrier
	ds_read_b128 v[172:175], v127 offset:49152
	ds_read_b128 v[176:179], v127 offset:50176
	ds_read_b128 v[180:183], v127 offset:51200
	ds_read_b128 v[184:187], v127 offset:52224
	ds_read_b128 v[188:191], v127 offset:53248
	ds_read_b128 v[192:195], v127 offset:54272
	ds_read_b128 v[196:199], v127 offset:55296
	ds_read_b128 v[200:203], v127 offset:56320
	s_add_i32 s4, s69, s26
	s_add_u32 s100, s46, s38
	s_addc_u32 s101, s47, s39
	s_mov_b32 m0, s4
	s_nop 0
	global_load_lds_dwordx4 v124, s[100:101]
	s_add_i32 m0, s4, 0x2000
	s_add_u32 s4, s46, 0xb0080
	s_addc_u32 s5, s47, 0
	s_add_i32 s46, s70, s26
	global_load_lds_dwordx4 v125, s[100:101]
	s_mov_b32 m0, s46
	s_nop 0
	global_load_lds_dwordx4 v124, s[4:5]
	s_add_i32 m0, s46, 0x2000
	s_nop 0
	global_load_lds_dwordx4 v125, s[4:5]
	s_mov_b32 m0, s64
	s_add_u32 s100, s22, s38
	s_addc_u32 s101, s23, s39
	v_mov_b32_e32 v0, v123
	global_load_lds_dwordx4 v122, s[100:101]
	s_mov_b32 m0, s65
	s_nop 0
	global_load_lds_dwordx4 v123, s[100:101]
	s_waitcnt vmcnt(8)
	s_waitcnt lgkmcnt(0)
	s_barrier
	s_setprio 1
	s_waitcnt lgkmcnt(0)
	v_mfma_f32_16x16x32_bf16 v[62:65], v[128:131], v[172:175], v[62:65]
	v_mfma_f32_16x16x32_bf16 v[58:61], v[146:149], v[172:175], v[58:61]
	v_mfma_f32_16x16x32_bf16 v[46:49], v[128:131], v[180:183], v[46:49]
	v_mfma_f32_16x16x32_bf16 v[42:45], v[146:149], v[180:183], v[42:45]
	v_mfma_f32_16x16x32_bf16 v[30:33], v[128:131], v[188:191], v[30:33]
	v_mfma_f32_16x16x32_bf16 v[26:29], v[146:149], v[188:191], v[26:29]
	v_mfma_f32_16x16x32_bf16 v[14:17], v[128:131], v[196:199], v[14:17]
	v_mfma_f32_16x16x32_bf16 v[10:13], v[146:149], v[196:199], v[10:13]
	v_mfma_f32_16x16x32_bf16 v[62:65], v[142:145], v[176:179], v[62:65]
	v_mfma_f32_16x16x32_bf16 v[58:61], v[150:153], v[176:179], v[58:61]
	v_mfma_f32_16x16x32_bf16 v[46:49], v[142:145], v[184:187], v[46:49]
	v_mfma_f32_16x16x32_bf16 v[42:45], v[150:153], v[184:187], v[42:45]
	v_mfma_f32_16x16x32_bf16 v[30:33], v[142:145], v[192:195], v[30:33]
	v_mfma_f32_16x16x32_bf16 v[26:29], v[150:153], v[192:195], v[26:29]
	v_mfma_f32_16x16x32_bf16 v[14:17], v[142:145], v[200:203], v[14:17]
	v_mfma_f32_16x16x32_bf16 v[10:13], v[150:153], v[200:203], v[10:13]
	s_setprio 0
	s_setprio 1
	v_mfma_f32_16x16x32_bf16 v[54:57], v[154:157], v[172:175], v[54:57]
	v_mfma_f32_16x16x32_bf16 v[50:53], v[164:167], v[172:175], v[50:53]
	v_mfma_f32_16x16x32_bf16 v[38:41], v[154:157], v[180:183], v[38:41]
	v_mfma_f32_16x16x32_bf16 v[34:37], v[164:167], v[180:183], v[34:37]
	v_mfma_f32_16x16x32_bf16 v[22:25], v[154:157], v[188:191], v[22:25]
	v_mfma_f32_16x16x32_bf16 v[18:21], v[164:167], v[188:191], v[18:21]
	v_mfma_f32_16x16x32_bf16 v[6:9], v[154:157], v[196:199], v[6:9]
	v_mfma_f32_16x16x32_bf16 v[2:5], v[164:167], v[196:199], v[2:5]
	v_mfma_f32_16x16x32_bf16 v[54:57], v[160:163], v[176:179], v[54:57]
	v_mfma_f32_16x16x32_bf16 v[50:53], v[168:171], v[176:179], v[50:53]
	v_mfma_f32_16x16x32_bf16 v[38:41], v[160:163], v[184:187], v[38:41]
	v_mfma_f32_16x16x32_bf16 v[34:37], v[168:171], v[184:187], v[34:37]
	v_mfma_f32_16x16x32_bf16 v[22:25], v[160:163], v[192:195], v[22:25]
	v_mfma_f32_16x16x32_bf16 v[18:21], v[168:171], v[192:195], v[18:21]
	v_mfma_f32_16x16x32_bf16 v[6:9], v[160:163], v[200:203], v[6:9]
	v_mfma_f32_16x16x32_bf16 v[2:5], v[168:171], v[200:203], v[2:5]
	s_setprio 0
	s_barrier
	s_add_i32 s68, s68, 2
	s_add_u32 s2, s2, 0x100
	s_addc_u32 s3, s3, 0
	s_cmp_gt_u32 s68, 41
	s_cbranch_scc0 .LBB0_869
	s_cmpk_lt_u32 s25, 0x100
	s_cbranch_scc0 .LBB0_872
	s_barrier

.LBB0_953:
	s_add_u32 s58, s4, s2
	s_addc_u32 s59, s5, s3
	s_add_u32 s14, s58, 0x100
	s_addc_u32 s15, s59, 0
	s_add_u32 s16, s43, s2
	s_addc_u32 s17, s46, s3
	s_add_i32 s51, 0, 0x10000
	s_cmp_eq_u32 s50, 40
	s_cselect_b32 s15, s5, s15
	s_cselect_b32 s14, s4, s14
	v_add_u32_e32 v0, s51, v135
	s_cselect_b32 s17, s7, s17
	s_cselect_b32 s16, s6, s16
	s_add_i32 s60, 0, 0x14000
	ds_read_b128 v[138:141], v0
	ds_read_b128 v[142:145], v0 offset:1024
	ds_read_b128 v[146:149], v0 offset:2048
	ds_read_b128 v[150:153], v0 offset:3072
	v_add_u32_e32 v0, s60, v135
	ds_read_b128 v[154:157], v0
	ds_read_b128 v[158:161], v0 offset:1024
	ds_read_b128 v[162:165], v0 offset:2048
	ds_read_b128 v[166:169], v0 offset:3072
	ds_read_b128 v[170:173], v136
	ds_read_b128 v[174:177], v136 offset:1024
	ds_read_b128 v[178:181], v136 offset:2048
	ds_read_b128 v[182:185], v136 offset:3072
	ds_read_b128 v[186:189], v136 offset:4096
	ds_read_b128 v[190:193], v136 offset:5120
	ds_read_b128 v[194:197], v136 offset:6144
	ds_read_b128 v[198:201], v136 offset:7168
	s_add_i32 m0, s37, 0xc000
	s_add_u32 s100, s58, s62
	s_addc_u32 s101, s59, s63
	global_load_lds_dwordx4 v130, s[100:101]
	s_add_i32 m0, s37, 0xe000
	s_nop 0
	global_load_lds_dwordx4 v131, s[100:101]
	s_waitcnt vmcnt(8)
	s_waitcnt lgkmcnt(0)
	s_barrier
	s_setprio 1
	s_waitcnt lgkmcnt(0)
	v_mfma_f32_16x16x32_bf16 v[126:129], v[138:141], v[170:173], v[126:129]
	v_mfma_f32_16x16x32_bf16 v[122:125], v[146:149], v[170:173], v[122:125]
	v_mfma_f32_16x16x32_bf16 v[110:113], v[138:141], v[178:181], v[110:113]
	v_mfma_f32_16x16x32_bf16 v[106:109], v[146:149], v[178:181], v[106:109]
	v_mfma_f32_16x16x32_bf16 v[94:97], v[138:141], v[186:189], v[94:97]
	v_mfma_f32_16x16x32_bf16 v[90:93], v[146:149], v[186:189], v[90:93]
	v_mfma_f32_16x16x32_bf16 v[78:81], v[138:141], v[194:197], v[78:81]
	v_mfma_f32_16x16x32_bf16 v[74:77], v[146:149], v[194:197], v[74:77]
	v_mfma_f32_16x16x32_bf16 v[126:129], v[142:145], v[174:177], v[126:129]
	v_mfma_f32_16x16x32_bf16 v[122:125], v[150:153], v[174:177], v[122:125]
	v_mfma_f32_16x16x32_bf16 v[110:113], v[142:145], v[182:185], v[110:113]
	v_mfma_f32_16x16x32_bf16 v[106:109], v[150:153], v[182:185], v[106:109]
	v_mfma_f32_16x16x32_bf16 v[94:97], v[142:145], v[190:193], v[94:97]
	v_mfma_f32_16x16x32_bf16 v[90:93], v[150:153], v[190:193], v[90:93]
	v_mfma_f32_16x16x32_bf16 v[78:81], v[142:145], v[198:201], v[78:81]
	v_mfma_f32_16x16x32_bf16 v[74:77], v[150:153], v[198:201], v[74:77]
	s_setprio 0
	s_setprio 1
	v_mfma_f32_16x16x32_bf16 v[118:121], v[154:157], v[170:173], v[118:121]
	v_mfma_f32_16x16x32_bf16 v[114:117], v[162:165], v[170:173], v[114:117]
	v_mfma_f32_16x16x32_bf16 v[102:105], v[154:157], v[178:181], v[102:105]
	v_mfma_f32_16x16x32_bf16 v[98:101], v[162:165], v[178:181], v[98:101]
	v_mfma_f32_16x16x32_bf16 v[86:89], v[154:157], v[186:189], v[86:89]
	v_mfma_f32_16x16x32_bf16 v[82:85], v[162:165], v[186:189], v[82:85]
	v_mfma_f32_16x16x32_bf16 v[70:73], v[154:157], v[194:197], v[70:73]
	v_mfma_f32_16x16x32_bf16 v[66:69], v[162:165], v[194:197], v[66:69]
	v_mfma_f32_16x16x32_bf16 v[118:121], v[158:161], v[174:177], v[118:121]
	v_mfma_f32_16x16x32_bf16 v[114:117], v[166:169], v[174:177], v[114:117]
	v_mfma_f32_16x16x32_bf16 v[102:105], v[158:161], v[182:185], v[102:105]
	v_mfma_f32_16x16x32_bf16 v[98:101], v[166:169], v[182:185], v[98:101]
	v_mfma_f32_16x16x32_bf16 v[86:89], v[158:161], v[190:193], v[86:89]
	v_mfma_f32_16x16x32_bf16 v[82:85], v[166:169], v[190:193], v[82:85]
	v_mfma_f32_16x16x32_bf16 v[70:73], v[158:161], v[198:201], v[70:73]
	v_mfma_f32_16x16x32_bf16 v[66:69], v[166:169], v[198:201], v[66:69]
	s_setprio 0
	s_barrier
	s_add_i32 s51, s51, s26
	ds_read_b128 v[170:173], v136 offset:16384
	ds_read_b128 v[174:177], v136 offset:17408
	ds_read_b128 v[178:181], v136 offset:18432
	ds_read_b128 v[182:185], v136 offset:19456
	ds_read_b128 v[186:189], v136 offset:20480
	ds_read_b128 v[190:193], v136 offset:21504
	ds_read_b128 v[194:197], v136 offset:22528
	ds_read_b128 v[198:201], v136 offset:23552
	s_mov_b32 m0, s51
	s_nop 0
	global_load_lds_dwordx4 v133, s[16:17]
	s_add_i32 m0, s51, 0x2000
	s_add_u32 s58, s16, 0xb0000
	global_load_lds_dwordx4 v134, s[16:17]
	s_addc_u32 s59, s17, 0
	s_add_i32 s51, s60, s26
	s_mov_b32 m0, s51
	s_nop 0
	global_load_lds_dwordx4 v133, s[58:59]
	s_add_i32 m0, s51, 0x2000
	s_nop 0
	global_load_lds_dwordx4 v134, s[58:59]
	s_mov_b32 m0, s37
	s_nop 0
	global_load_lds_dwordx4 v130, s[14:15]
	s_mov_b32 m0, s40
	s_nop 0
	global_load_lds_dwordx4 v131, s[14:15]
	s_waitcnt vmcnt(8)
	s_waitcnt lgkmcnt(0)
	s_barrier
	s_setprio 1
	s_waitcnt lgkmcnt(0)
	v_mfma_f32_16x16x32_bf16 v[62:65], v[138:141], v[170:173], v[62:65]
	v_mfma_f32_16x16x32_bf16 v[58:61], v[146:149], v[170:173], v[58:61]
	v_mfma_f32_16x16x32_bf16 v[46:49], v[138:141], v[178:181], v[46:49]
	v_mfma_f32_16x16x32_bf16 v[42:45], v[146:149], v[178:181], v[42:45]
	v_mfma_f32_16x16x32_bf16 v[30:33], v[138:141], v[186:189], v[30:33]
	v_mfma_f32_16x16x32_bf16 v[26:29], v[146:149], v[186:189], v[26:29]
	v_mfma_f32_16x16x32_bf16 v[14:17], v[138:141], v[194:197], v[14:17]
	v_mfma_f32_16x16x32_bf16 v[10:13], v[146:149], v[194:197], v[10:13]
	v_mfma_f32_16x16x32_bf16 v[62:65], v[142:145], v[174:177], v[62:65]
	v_mfma_f32_16x16x32_bf16 v[58:61], v[150:153], v[174:177], v[58:61]
	v_mfma_f32_16x16x32_bf16 v[46:49], v[142:145], v[182:185], v[46:49]
	v_mfma_f32_16x16x32_bf16 v[42:45], v[150:153], v[182:185], v[42:45]
	v_mfma_f32_16x16x32_bf16 v[30:33], v[142:145], v[190:193], v[30:33]
	v_mfma_f32_16x16x32_bf16 v[26:29], v[150:153], v[190:193], v[26:29]
	v_mfma_f32_16x16x32_bf16 v[14:17], v[142:145], v[198:201], v[14:17]
	v_mfma_f32_16x16x32_bf16 v[10:13], v[150:153], v[198:201], v[10:13]
	s_setprio 0
	s_setprio 1
	v_mfma_f32_16x16x32_bf16 v[54:57], v[154:157], v[170:173], v[54:57]
	v_mfma_f32_16x16x32_bf16 v[50:53], v[162:165], v[170:173], v[50:53]
	v_mfma_f32_16x16x32_bf16 v[38:41], v[154:157], v[178:181], v[38:41]
	v_mfma_f32_16x16x32_bf16 v[34:37], v[162:165], v[178:181], v[34:37]
	v_mfma_f32_16x16x32_bf16 v[22:25], v[154:157], v[186:189], v[22:25]
	v_mfma_f32_16x16x32_bf16 v[18:21], v[162:165], v[186:189], v[18:21]
	v_mfma_f32_16x16x32_bf16 v[6:9], v[154:157], v[194:197], v[6:9]
	v_mfma_f32_16x16x32_bf16 v[2:5], v[162:165], v[194:197], v[2:5]
	v_mfma_f32_16x16x32_bf16 v[54:57], v[158:161], v[174:177], v[54:57]
	v_mfma_f32_16x16x32_bf16 v[50:53], v[166:169], v[174:177], v[50:53]
	v_mfma_f32_16x16x32_bf16 v[38:41], v[158:161], v[182:185], v[38:41]
	v_mfma_f32_16x16x32_bf16 v[34:37], v[166:169], v[182:185], v[34:37]
	v_mfma_f32_16x16x32_bf16 v[22:25], v[158:161], v[190:193], v[22:25]
	v_mfma_f32_16x16x32_bf16 v[18:21], v[166:169], v[190:193], v[18:21]
	v_mfma_f32_16x16x32_bf16 v[6:9], v[158:161], v[198:201], v[6:9]
	v_mfma_f32_16x16x32_bf16 v[2:5], v[166:169], v[198:201], v[2:5]
	s_setprio 0
	s_barrier
	s_add_i32 s51, 0, 0x18000
	v_add_u32_e32 v0, s51, v135
	s_add_i32 s60, 0, 0x1c000
	ds_read_b128 v[138:141], v0
	ds_read_b128 v[142:145], v0 offset:1024
	ds_read_b128 v[146:149], v0 offset:2048
	ds_read_b128 v[150:153], v0 offset:3072
	v_add_u32_e32 v0, s60, v135
	ds_read_b128 v[154:157], v0
	ds_read_b128 v[158:161], v0 offset:1024
	ds_read_b128 v[162:165], v0 offset:2048
	ds_read_b128 v[166:169], v0 offset:3072
	s_add_u32 s58, s14, 0xb0000
	s_mov_b32 m0, s41
	ds_read_b128 v[170:173], v136 offset:32768
	ds_read_b128 v[174:177], v136 offset:33792
	ds_read_b128 v[178:181], v136 offset:34816
	ds_read_b128 v[182:185], v136 offset:35840
	ds_read_b128 v[186:189], v136 offset:36864
	ds_read_b128 v[190:193], v136 offset:37888
	ds_read_b128 v[194:197], v136 offset:38912
	ds_read_b128 v[198:201], v136 offset:39936
	s_addc_u32 s59, s15, 0
	s_nop 0
	global_load_lds_dwordx4 v130, s[58:59]
	s_mov_b32 m0, s42
	s_nop 0
	global_load_lds_dwordx4 v131, s[58:59]
	s_waitcnt vmcnt(8)
	s_waitcnt lgkmcnt(0)
	s_barrier
	s_setprio 1
	s_waitcnt lgkmcnt(0)
	v_mfma_f32_16x16x32_bf16 v[126:129], v[138:141], v[170:173], v[126:129]
	v_mfma_f32_16x16x32_bf16 v[122:125], v[146:149], v[170:173], v[122:125]
	v_mfma_f32_16x16x32_bf16 v[110:113], v[138:141], v[178:181], v[110:113]
	v_mfma_f32_16x16x32_bf16 v[106:109], v[146:149], v[178:181], v[106:109]
	v_mfma_f32_16x16x32_bf16 v[94:97], v[138:141], v[186:189], v[94:97]
	v_mfma_f32_16x16x32_bf16 v[90:93], v[146:149], v[186:189], v[90:93]
	v_mfma_f32_16x16x32_bf16 v[78:81], v[138:141], v[194:197], v[78:81]
	v_mfma_f32_16x16x32_bf16 v[74:77], v[146:149], v[194:197], v[74:77]
	v_mfma_f32_16x16x32_bf16 v[126:129], v[142:145], v[174:177], v[126:129]
	v_mfma_f32_16x16x32_bf16 v[122:125], v[150:153], v[174:177], v[122:125]
	v_mfma_f32_16x16x32_bf16 v[110:113], v[142:145], v[182:185], v[110:113]
	v_mfma_f32_16x16x32_bf16 v[106:109], v[150:153], v[182:185], v[106:109]
	v_mfma_f32_16x16x32_bf16 v[94:97], v[142:145], v[190:193], v[94:97]
	v_mfma_f32_16x16x32_bf16 v[90:93], v[150:153], v[190:193], v[90:93]
	v_mfma_f32_16x16x32_bf16 v[78:81], v[142:145], v[198:201], v[78:81]
	v_mfma_f32_16x16x32_bf16 v[74:77], v[150:153], v[198:201], v[74:77]
	s_setprio 0
	s_setprio 1
	v_mfma_f32_16x16x32_bf16 v[118:121], v[154:157], v[170:173], v[118:121]
	v_mfma_f32_16x16x32_bf16 v[114:117], v[162:165], v[170:173], v[114:117]
	v_mfma_f32_16x16x32_bf16 v[102:105], v[154:157], v[178:181], v[102:105]
	v_mfma_f32_16x16x32_bf16 v[98:101], v[162:165], v[178:181], v[98:101]
	v_mfma_f32_16x16x32_bf16 v[86:89], v[154:157], v[186:189], v[86:89]
	v_mfma_f32_16x16x32_bf16 v[82:85], v[162:165], v[186:189], v[82:85]
	v_mfma_f32_16x16x32_bf16 v[70:73], v[154:157], v[194:197], v[70:73]
	v_mfma_f32_16x16x32_bf16 v[66:69], v[162:165], v[194:197], v[66:69]
	v_mfma_f32_16x16x32_bf16 v[118:121], v[158:161], v[174:177], v[118:121]
	v_mfma_f32_16x16x32_bf16 v[114:117], v[166:169], v[174:177], v[114:117]
	v_mfma_f32_16x16x32_bf16 v[102:105], v[158:161], v[182:185], v[102:105]
	v_mfma_f32_16x16x32_bf16 v[98:101], v[166:169], v[182:185], v[98:101]
	v_mfma_f32_16x16x32_bf16 v[86:89], v[158:161], v[190:193], v[86:89]
	v_mfma_f32_16x16x32_bf16 v[82:85], v[166:169], v[190:193], v[82:85]
	v_mfma_f32_16x16x32_bf16 v[70:73], v[158:161], v[198:201], v[70:73]
	v_mfma_f32_16x16x32_bf16 v[66:69], v[166:169], v[198:201], v[66:69]
	s_setprio 0
	s_barrier
	ds_read_b128 v[170:173], v136 offset:49152
	ds_read_b128 v[174:177], v136 offset:50176
	ds_read_b128 v[178:181], v136 offset:51200
	ds_read_b128 v[182:185], v136 offset:52224
	ds_read_b128 v[186:189], v136 offset:53248
	ds_read_b128 v[190:193], v136 offset:54272
	ds_read_b128 v[194:197], v136 offset:55296
	ds_read_b128 v[198:201], v136 offset:56320
	s_add_i32 s51, s51, s26
	s_add_u32 s100, s16, s38
	s_addc_u32 s101, s17, s39
	s_mov_b32 m0, s51
	s_nop 0
	global_load_lds_dwordx4 v133, s[100:101]
	s_add_i32 m0, s51, 0x2000
	s_nop 0
	s_add_u32 s16, s16, 0xb0080
	s_addc_u32 s17, s17, 0
	s_add_i32 s51, s60, s26
	global_load_lds_dwordx4 v134, s[100:101]
	s_mov_b32 m0, s51
	s_nop 0
	global_load_lds_dwordx4 v133, s[16:17]
	s_add_i32 m0, s51, 0x2000
	s_nop 0
	global_load_lds_dwordx4 v134, s[16:17]
	s_mov_b32 m0, s48
	s_add_u32 s100, s14, s38
	s_addc_u32 s101, s15, s39
	v_mov_b32_e32 v0, v131
	global_load_lds_dwordx4 v130, s[100:101]
	s_mov_b32 m0, s49
	s_nop 0
	global_load_lds_dwordx4 v131, s[100:101]
	s_waitcnt vmcnt(8)
	s_waitcnt lgkmcnt(0)
	s_barrier
	s_setprio 1
	s_waitcnt lgkmcnt(0)
	v_mfma_f32_16x16x32_bf16 v[62:65], v[138:141], v[170:173], v[62:65]
	v_mfma_f32_16x16x32_bf16 v[58:61], v[146:149], v[170:173], v[58:61]
	v_mfma_f32_16x16x32_bf16 v[46:49], v[138:141], v[178:181], v[46:49]
	v_mfma_f32_16x16x32_bf16 v[42:45], v[146:149], v[178:181], v[42:45]
	v_mfma_f32_16x16x32_bf16 v[30:33], v[138:141], v[186:189], v[30:33]
	v_mfma_f32_16x16x32_bf16 v[26:29], v[146:149], v[186:189], v[26:29]
	v_mfma_f32_16x16x32_bf16 v[14:17], v[138:141], v[194:197], v[14:17]
	v_mfma_f32_16x16x32_bf16 v[10:13], v[146:149], v[194:197], v[10:13]
	v_mfma_f32_16x16x32_bf16 v[62:65], v[142:145], v[174:177], v[62:65]
	v_mfma_f32_16x16x32_bf16 v[58:61], v[150:153], v[174:177], v[58:61]
	v_mfma_f32_16x16x32_bf16 v[46:49], v[142:145], v[182:185], v[46:49]
	v_mfma_f32_16x16x32_bf16 v[42:45], v[150:153], v[182:185], v[42:45]
	v_mfma_f32_16x16x32_bf16 v[30:33], v[142:145], v[190:193], v[30:33]
	v_mfma_f32_16x16x32_bf16 v[26:29], v[150:153], v[190:193], v[26:29]
	v_mfma_f32_16x16x32_bf16 v[14:17], v[142:145], v[198:201], v[14:17]
	v_mfma_f32_16x16x32_bf16 v[10:13], v[150:153], v[198:201], v[10:13]
	s_setprio 0
	s_setprio 1
	v_mfma_f32_16x16x32_bf16 v[54:57], v[154:157], v[170:173], v[54:57]
	v_mfma_f32_16x16x32_bf16 v[50:53], v[162:165], v[170:173], v[50:53]
	v_mfma_f32_16x16x32_bf16 v[38:41], v[154:157], v[178:181], v[38:41]
	v_mfma_f32_16x16x32_bf16 v[34:37], v[162:165], v[178:181], v[34:37]
	v_mfma_f32_16x16x32_bf16 v[22:25], v[154:157], v[186:189], v[22:25]
	v_mfma_f32_16x16x32_bf16 v[18:21], v[162:165], v[186:189], v[18:21]
	v_mfma_f32_16x16x32_bf16 v[6:9], v[154:157], v[194:197], v[6:9]
	v_mfma_f32_16x16x32_bf16 v[2:5], v[162:165], v[194:197], v[2:5]
	v_mfma_f32_16x16x32_bf16 v[54:57], v[158:161], v[174:177], v[54:57]
	v_mfma_f32_16x16x32_bf16 v[50:53], v[166:169], v[174:177], v[50:53]
	v_mfma_f32_16x16x32_bf16 v[38:41], v[158:161], v[182:185], v[38:41]
	v_mfma_f32_16x16x32_bf16 v[34:37], v[166:169], v[182:185], v[34:37]
	v_mfma_f32_16x16x32_bf16 v[22:25], v[158:161], v[190:193], v[22:25]
	v_mfma_f32_16x16x32_bf16 v[18:21], v[166:169], v[190:193], v[18:21]
	v_mfma_f32_16x16x32_bf16 v[6:9], v[158:161], v[198:201], v[6:9]
	v_mfma_f32_16x16x32_bf16 v[2:5], v[166:169], v[198:201], v[2:5]
	s_setprio 0
	s_barrier
	s_add_i32 s50, s50, 2
	s_add_u32 s2, s2, 0x100
	s_addc_u32 s3, s3, 0
	s_cmp_gt_u32 s50, 41
	s_cbranch_scc0 .LBB0_953
	s_cmpk_lt_u32 s25, 0x100
	s_cbranch_scc0 .LBB0_956
	s_barrier

.LBB0_1087:
	s_add_u32 s2, s6, 0x40080
	s_addc_u32 s3, s7, 0
	s_add_u32 s8, s8, 0x100
	s_addc_u32 s9, s9, 0
	s_mov_b32 s22, -2
	s_add_u32 s4, s2, 0xfffc0080
	s_addc_u32 s5, s3, -1
	s_add_i32 s23, 0, 0x10000
	s_cmp_eq_u32 s22, 12
	s_cselect_b32 s5, s49, s5
	s_cselect_b32 s4, s48, s4
	s_waitcnt vmcnt(0)
	v_add_u32_e32 v0, s23, v145
	s_cselect_b32 s7, s97, s9
	s_cselect_b32 s6, s96, s8
	s_add_i32 s25, 0, 0x14000
	ds_read_b128 v[146:149], v0
	ds_read_b128 v[152:155], v0 offset:1024
	ds_read_b128 v[156:159], v0 offset:2048
	ds_read_b128 v[160:163], v0 offset:3072
	v_add_u32_e32 v0, s25, v145
	ds_read_b128 v[164:167], v0
	ds_read_b128 v[168:171], v0 offset:1024
	ds_read_b128 v[172:175], v0 offset:2048
	ds_read_b128 v[176:179], v0 offset:3072
	ds_read_b128 v[180:183], v150
	ds_read_b128 v[184:187], v150 offset:1024
	ds_read_b128 v[188:191], v150 offset:2048
	ds_read_b128 v[192:195], v150 offset:3072
	ds_read_b128 v[196:199], v150 offset:4096
	ds_read_b128 v[200:203], v150 offset:5120
	ds_read_b128 v[204:207], v150 offset:6144
	ds_read_b128 v[208:211], v150 offset:7168
	s_add_i32 m0, s60, 0xc000
	s_nop 0
	global_load_lds_dwordx4 v131, s[2:3]
	s_add_i32 m0, s60, 0xe000
	s_nop 0
	global_load_lds_dwordx4 v133, s[2:3]
	s_waitcnt vmcnt(8)
	s_waitcnt lgkmcnt(0)
	s_barrier
	s_setprio 1
	s_waitcnt lgkmcnt(0)
	v_mfma_f32_16x16x32_bf16 v[126:129], v[146:149], v[180:183], 0
	v_mfma_f32_16x16x32_bf16 v[122:125], v[156:159], v[180:183], 0
	v_mfma_f32_16x16x32_bf16 v[110:113], v[146:149], v[188:191], 0
	v_mfma_f32_16x16x32_bf16 v[106:109], v[156:159], v[188:191], 0
	v_mfma_f32_16x16x32_bf16 v[94:97], v[146:149], v[196:199], 0
	v_mfma_f32_16x16x32_bf16 v[90:93], v[156:159], v[196:199], 0
	v_mfma_f32_16x16x32_bf16 v[78:81], v[146:149], v[204:207], 0
	v_mfma_f32_16x16x32_bf16 v[74:77], v[156:159], v[204:207], 0
	v_mfma_f32_16x16x32_bf16 v[126:129], v[152:155], v[184:187], v[126:129]
	v_mfma_f32_16x16x32_bf16 v[122:125], v[160:163], v[184:187], v[122:125]
	v_mfma_f32_16x16x32_bf16 v[110:113], v[152:155], v[192:195], v[110:113]
	v_mfma_f32_16x16x32_bf16 v[106:109], v[160:163], v[192:195], v[106:109]
	v_mfma_f32_16x16x32_bf16 v[94:97], v[152:155], v[200:203], v[94:97]
	v_mfma_f32_16x16x32_bf16 v[90:93], v[160:163], v[200:203], v[90:93]
	v_mfma_f32_16x16x32_bf16 v[78:81], v[152:155], v[208:211], v[78:81]
	v_mfma_f32_16x16x32_bf16 v[74:77], v[160:163], v[208:211], v[74:77]
	s_setprio 0
	s_setprio 1
	v_mfma_f32_16x16x32_bf16 v[118:121], v[164:167], v[180:183], 0
	v_mfma_f32_16x16x32_bf16 v[114:117], v[172:175], v[180:183], 0
	v_mfma_f32_16x16x32_bf16 v[102:105], v[164:167], v[188:191], 0
	v_mfma_f32_16x16x32_bf16 v[98:101], v[172:175], v[188:191], 0
	v_mfma_f32_16x16x32_bf16 v[86:89], v[164:167], v[196:199], 0
	v_mfma_f32_16x16x32_bf16 v[82:85], v[172:175], v[196:199], 0
	v_mfma_f32_16x16x32_bf16 v[70:73], v[164:167], v[204:207], 0
	v_mfma_f32_16x16x32_bf16 v[66:69], v[172:175], v[204:207], 0
	v_mfma_f32_16x16x32_bf16 v[118:121], v[168:171], v[184:187], v[118:121]
	v_mfma_f32_16x16x32_bf16 v[114:117], v[176:179], v[184:187], v[114:117]
	v_mfma_f32_16x16x32_bf16 v[102:105], v[168:171], v[192:195], v[102:105]
	v_mfma_f32_16x16x32_bf16 v[98:101], v[176:179], v[192:195], v[98:101]
	v_mfma_f32_16x16x32_bf16 v[86:89], v[168:171], v[200:203], v[86:89]
	v_mfma_f32_16x16x32_bf16 v[82:85], v[176:179], v[200:203], v[82:85]
	v_mfma_f32_16x16x32_bf16 v[70:73], v[168:171], v[208:211], v[70:73]
	v_mfma_f32_16x16x32_bf16 v[66:69], v[176:179], v[208:211], v[66:69]
	s_setprio 0
	s_barrier
	s_add_i32 s23, s23, s42
	ds_read_b128 v[180:183], v150 offset:16384
	ds_read_b128 v[184:187], v150 offset:17408
	ds_read_b128 v[188:191], v150 offset:18432
	ds_read_b128 v[192:195], v150 offset:19456
	ds_read_b128 v[196:199], v150 offset:20480
	ds_read_b128 v[200:203], v150 offset:21504
	ds_read_b128 v[204:207], v150 offset:22528
	ds_read_b128 v[208:211], v150 offset:23552
	s_mov_b32 m0, s23
	s_nop 0
	global_load_lds_dwordx4 v137, s[6:7]
	s_add_i32 m0, s23, 0x2000
	s_add_u32 s46, s6, 0x40000
	global_load_lds_dwordx4 v139, s[6:7]
	s_addc_u32 s47, s7, 0
	s_add_i32 s23, s25, s42
	s_mov_b32 m0, s23
	s_nop 0
	global_load_lds_dwordx4 v137, s[46:47]
	s_add_i32 m0, s23, 0x2000
	s_nop 0
	global_load_lds_dwordx4 v139, s[46:47]
	s_mov_b32 m0, s60
	s_nop 0
	global_load_lds_dwordx4 v131, s[4:5]
	s_mov_b32 m0, s61
	s_nop 0
	global_load_lds_dwordx4 v133, s[4:5]
	s_waitcnt vmcnt(8)
	s_waitcnt lgkmcnt(0)
	s_barrier
	s_setprio 1
	s_waitcnt lgkmcnt(0)
	v_mfma_f32_16x16x32_bf16 v[62:65], v[146:149], v[180:183], 0
	v_mfma_f32_16x16x32_bf16 v[58:61], v[156:159], v[180:183], 0
	v_mfma_f32_16x16x32_bf16 v[46:49], v[146:149], v[188:191], 0
	v_mfma_f32_16x16x32_bf16 v[42:45], v[156:159], v[188:191], 0
	v_mfma_f32_16x16x32_bf16 v[30:33], v[146:149], v[196:199], 0
	v_mfma_f32_16x16x32_bf16 v[26:29], v[156:159], v[196:199], 0
	v_mfma_f32_16x16x32_bf16 v[14:17], v[146:149], v[204:207], 0
	v_mfma_f32_16x16x32_bf16 v[10:13], v[156:159], v[204:207], 0
	v_mfma_f32_16x16x32_bf16 v[62:65], v[152:155], v[184:187], v[62:65]
	v_mfma_f32_16x16x32_bf16 v[58:61], v[160:163], v[184:187], v[58:61]
	v_mfma_f32_16x16x32_bf16 v[46:49], v[152:155], v[192:195], v[46:49]
	v_mfma_f32_16x16x32_bf16 v[42:45], v[160:163], v[192:195], v[42:45]
	v_mfma_f32_16x16x32_bf16 v[30:33], v[152:155], v[200:203], v[30:33]
	v_mfma_f32_16x16x32_bf16 v[26:29], v[160:163], v[200:203], v[26:29]
	v_mfma_f32_16x16x32_bf16 v[14:17], v[152:155], v[208:211], v[14:17]
	v_mfma_f32_16x16x32_bf16 v[10:13], v[160:163], v[208:211], v[10:13]
	s_setprio 0
	s_setprio 1
	v_mfma_f32_16x16x32_bf16 v[54:57], v[164:167], v[180:183], 0
	v_mfma_f32_16x16x32_bf16 v[50:53], v[172:175], v[180:183], 0
	v_mfma_f32_16x16x32_bf16 v[38:41], v[164:167], v[188:191], 0
	v_mfma_f32_16x16x32_bf16 v[34:37], v[172:175], v[188:191], 0
	v_mfma_f32_16x16x32_bf16 v[22:25], v[164:167], v[196:199], 0
	v_mfma_f32_16x16x32_bf16 v[18:21], v[172:175], v[196:199], 0
	v_mfma_f32_16x16x32_bf16 v[6:9], v[164:167], v[204:207], 0
	v_mfma_f32_16x16x32_bf16 v[2:5], v[172:175], v[204:207], 0
	v_mfma_f32_16x16x32_bf16 v[54:57], v[168:171], v[184:187], v[54:57]
	v_mfma_f32_16x16x32_bf16 v[50:53], v[176:179], v[184:187], v[50:53]
	v_mfma_f32_16x16x32_bf16 v[38:41], v[168:171], v[192:195], v[38:41]
	v_mfma_f32_16x16x32_bf16 v[34:37], v[176:179], v[192:195], v[34:37]
	v_mfma_f32_16x16x32_bf16 v[22:25], v[168:171], v[200:203], v[22:25]
	v_mfma_f32_16x16x32_bf16 v[18:21], v[176:179], v[200:203], v[18:21]
	v_mfma_f32_16x16x32_bf16 v[6:9], v[168:171], v[208:211], v[6:9]
	v_mfma_f32_16x16x32_bf16 v[2:5], v[176:179], v[208:211], v[2:5]
	s_setprio 0
	s_barrier
	s_add_i32 s23, 0, 0x18000
	v_add_u32_e32 v0, s23, v145
	s_add_i32 s25, 0, 0x1c000
	ds_read_b128 v[146:149], v0
	ds_read_b128 v[152:155], v0 offset:1024
	ds_read_b128 v[156:159], v0 offset:2048
	ds_read_b128 v[160:163], v0 offset:3072
	v_add_u32_e32 v0, s25, v145
	ds_read_b128 v[164:167], v0
	ds_read_b128 v[168:171], v0 offset:1024
	ds_read_b128 v[172:175], v0 offset:2048
	ds_read_b128 v[176:179], v0 offset:3072
	s_add_u32 s46, s4, 0x40000
	s_mov_b32 m0, s66
	ds_read_b128 v[180:183], v150 offset:32768
	ds_read_b128 v[184:187], v150 offset:33792
	ds_read_b128 v[188:191], v150 offset:34816
	ds_read_b128 v[192:195], v150 offset:35840
	ds_read_b128 v[196:199], v150 offset:36864
	ds_read_b128 v[200:203], v150 offset:37888
	ds_read_b128 v[204:207], v150 offset:38912
	ds_read_b128 v[208:211], v150 offset:39936
	s_addc_u32 s47, s5, 0
	s_nop 0
	global_load_lds_dwordx4 v131, s[46:47]
	s_mov_b32 m0, s67
	s_nop 0
	global_load_lds_dwordx4 v133, s[46:47]
	s_waitcnt vmcnt(8)
	s_waitcnt lgkmcnt(0)
	s_barrier
	s_setprio 1
	s_waitcnt lgkmcnt(0)
	v_mfma_f32_16x16x32_bf16 v[126:129], v[146:149], v[180:183], v[126:129]
	v_mfma_f32_16x16x32_bf16 v[122:125], v[156:159], v[180:183], v[122:125]
	v_mfma_f32_16x16x32_bf16 v[110:113], v[146:149], v[188:191], v[110:113]
	v_mfma_f32_16x16x32_bf16 v[106:109], v[156:159], v[188:191], v[106:109]
	v_mfma_f32_16x16x32_bf16 v[94:97], v[146:149], v[196:199], v[94:97]
	v_mfma_f32_16x16x32_bf16 v[90:93], v[156:159], v[196:199], v[90:93]
	v_mfma_f32_16x16x32_bf16 v[78:81], v[146:149], v[204:207], v[78:81]
	v_mfma_f32_16x16x32_bf16 v[74:77], v[156:159], v[204:207], v[74:77]
	v_mfma_f32_16x16x32_bf16 v[126:129], v[152:155], v[184:187], v[126:129]
	v_mfma_f32_16x16x32_bf16 v[122:125], v[160:163], v[184:187], v[122:125]
	v_mfma_f32_16x16x32_bf16 v[110:113], v[152:155], v[192:195], v[110:113]
	v_mfma_f32_16x16x32_bf16 v[106:109], v[160:163], v[192:195], v[106:109]
	v_mfma_f32_16x16x32_bf16 v[94:97], v[152:155], v[200:203], v[94:97]
	v_mfma_f32_16x16x32_bf16 v[90:93], v[160:163], v[200:203], v[90:93]
	v_mfma_f32_16x16x32_bf16 v[78:81], v[152:155], v[208:211], v[78:81]
	v_mfma_f32_16x16x32_bf16 v[74:77], v[160:163], v[208:211], v[74:77]
	s_setprio 0
	s_setprio 1
	v_mfma_f32_16x16x32_bf16 v[118:121], v[164:167], v[180:183], v[118:121]
	v_mfma_f32_16x16x32_bf16 v[114:117], v[172:175], v[180:183], v[114:117]
	v_mfma_f32_16x16x32_bf16 v[102:105], v[164:167], v[188:191], v[102:105]
	v_mfma_f32_16x16x32_bf16 v[98:101], v[172:175], v[188:191], v[98:101]
	v_mfma_f32_16x16x32_bf16 v[86:89], v[164:167], v[196:199], v[86:89]
	v_mfma_f32_16x16x32_bf16 v[82:85], v[172:175], v[196:199], v[82:85]
	v_mfma_f32_16x16x32_bf16 v[70:73], v[164:167], v[204:207], v[70:73]
	v_mfma_f32_16x16x32_bf16 v[66:69], v[172:175], v[204:207], v[66:69]
	v_mfma_f32_16x16x32_bf16 v[118:121], v[168:171], v[184:187], v[118:121]
	v_mfma_f32_16x16x32_bf16 v[114:117], v[176:179], v[184:187], v[114:117]
	v_mfma_f32_16x16x32_bf16 v[102:105], v[168:171], v[192:195], v[102:105]
	v_mfma_f32_16x16x32_bf16 v[98:101], v[176:179], v[192:195], v[98:101]
	v_mfma_f32_16x16x32_bf16 v[86:89], v[168:171], v[200:203], v[86:89]
	v_mfma_f32_16x16x32_bf16 v[82:85], v[176:179], v[200:203], v[82:85]
	v_mfma_f32_16x16x32_bf16 v[70:73], v[168:171], v[208:211], v[70:73]
	v_mfma_f32_16x16x32_bf16 v[66:69], v[176:179], v[208:211], v[66:69]
	s_setprio 0
	s_barrier
	ds_read_b128 v[180:183], v150 offset:49152
	ds_read_b128 v[184:187], v150 offset:50176
	ds_read_b128 v[188:191], v150 offset:51200
	ds_read_b128 v[192:195], v150 offset:52224
	ds_read_b128 v[196:199], v150 offset:53248
	ds_read_b128 v[200:203], v150 offset:54272
	ds_read_b128 v[204:207], v150 offset:55296
	ds_read_b128 v[208:211], v150 offset:56320
	s_add_i32 s23, s23, s42
	s_add_u32 s100, s6, s38
	s_addc_u32 s101, s7, s39
	s_mov_b32 m0, s23
	s_nop 0
	global_load_lds_dwordx4 v137, s[100:101]
	s_add_i32 m0, s23, 0x2000
	s_nop 0
	s_add_u32 s6, s6, 0x40080
	s_addc_u32 s7, s7, 0
	s_add_i32 s23, s25, s42
	global_load_lds_dwordx4 v139, s[100:101]
	s_mov_b32 m0, s23
	s_nop 0
	global_load_lds_dwordx4 v137, s[6:7]
	s_add_i32 m0, s23, 0x2000
	s_nop 0
	global_load_lds_dwordx4 v139, s[6:7]
	s_mov_b32 m0, s70
	s_add_u32 s100, s4, s38
	s_addc_u32 s101, s5, s39
	v_mov_b32_e32 v0, v133
	global_load_lds_dwordx4 v131, s[100:101]
	s_mov_b32 m0, s71
	s_nop 0
	global_load_lds_dwordx4 v133, s[100:101]
	s_waitcnt vmcnt(8)
	s_waitcnt lgkmcnt(0)
	s_barrier
	s_setprio 1
	s_waitcnt lgkmcnt(0)
	v_mfma_f32_16x16x32_bf16 v[62:65], v[146:149], v[180:183], v[62:65]
	v_mfma_f32_16x16x32_bf16 v[58:61], v[156:159], v[180:183], v[58:61]
	v_mfma_f32_16x16x32_bf16 v[46:49], v[146:149], v[188:191], v[46:49]
	v_mfma_f32_16x16x32_bf16 v[42:45], v[156:159], v[188:191], v[42:45]
	v_mfma_f32_16x16x32_bf16 v[30:33], v[146:149], v[196:199], v[30:33]
	v_mfma_f32_16x16x32_bf16 v[26:29], v[156:159], v[196:199], v[26:29]
	v_mfma_f32_16x16x32_bf16 v[14:17], v[146:149], v[204:207], v[14:17]
	v_mfma_f32_16x16x32_bf16 v[10:13], v[156:159], v[204:207], v[10:13]
	v_mfma_f32_16x16x32_bf16 v[62:65], v[152:155], v[184:187], v[62:65]
	v_mfma_f32_16x16x32_bf16 v[58:61], v[160:163], v[184:187], v[58:61]
	v_mfma_f32_16x16x32_bf16 v[46:49], v[152:155], v[192:195], v[46:49]
	v_mfma_f32_16x16x32_bf16 v[42:45], v[160:163], v[192:195], v[42:45]
	v_mfma_f32_16x16x32_bf16 v[30:33], v[152:155], v[200:203], v[30:33]
	v_mfma_f32_16x16x32_bf16 v[26:29], v[160:163], v[200:203], v[26:29]
	v_mfma_f32_16x16x32_bf16 v[14:17], v[152:155], v[208:211], v[14:17]
	v_mfma_f32_16x16x32_bf16 v[10:13], v[160:163], v[208:211], v[10:13]
	s_setprio 0
	s_setprio 1
	v_mfma_f32_16x16x32_bf16 v[54:57], v[164:167], v[180:183], v[54:57]
	v_mfma_f32_16x16x32_bf16 v[50:53], v[172:175], v[180:183], v[50:53]
	v_mfma_f32_16x16x32_bf16 v[38:41], v[164:167], v[188:191], v[38:41]
	v_mfma_f32_16x16x32_bf16 v[34:37], v[172:175], v[188:191], v[34:37]
	v_mfma_f32_16x16x32_bf16 v[22:25], v[164:167], v[196:199], v[22:25]
	v_mfma_f32_16x16x32_bf16 v[18:21], v[172:175], v[196:199], v[18:21]
	v_mfma_f32_16x16x32_bf16 v[6:9], v[164:167], v[204:207], v[6:9]
	v_mfma_f32_16x16x32_bf16 v[2:5], v[172:175], v[204:207], v[2:5]
	v_mfma_f32_16x16x32_bf16 v[54:57], v[168:171], v[184:187], v[54:57]
	v_mfma_f32_16x16x32_bf16 v[50:53], v[176:179], v[184:187], v[50:53]
	v_mfma_f32_16x16x32_bf16 v[38:41], v[168:171], v[192:195], v[38:41]
	v_mfma_f32_16x16x32_bf16 v[34:37], v[176:179], v[192:195], v[34:37]
	v_mfma_f32_16x16x32_bf16 v[22:25], v[168:171], v[200:203], v[22:25]
	v_mfma_f32_16x16x32_bf16 v[18:21], v[176:179], v[200:203], v[18:21]
	v_mfma_f32_16x16x32_bf16 v[6:9], v[168:171], v[208:211], v[6:9]
	v_mfma_f32_16x16x32_bf16 v[2:5], v[176:179], v[208:211], v[2:5]
	s_setprio 0
	s_barrier
	s_add_i32 s22, s22, 2
	s_add_u32 s2, s2, 0x100
	s_addc_u32 s3, s3, 0
	s_add_u32 s8, s8, 0x100
	s_addc_u32 s9, s9, 0
	s_cmp_gt_u32 s22, 13
	s_cbranch_scc0 .LBB0_1088
	s_branch .Lpeel_exit_1088
.LBB0_1088:
	s_add_u32 s4, s2, 0xfffc0080
	s_addc_u32 s5, s3, -1
	s_add_i32 s23, 0, 0x10000
	s_cmp_eq_u32 s22, 12
	s_cselect_b32 s5, s49, s5
	s_cselect_b32 s4, s48, s4
	v_add_u32_e32 v0, s23, v145
	s_cselect_b32 s7, s97, s9
	s_cselect_b32 s6, s96, s8
	s_add_i32 s25, 0, 0x14000
	ds_read_b128 v[146:149], v0
	ds_read_b128 v[152:155], v0 offset:1024
	ds_read_b128 v[156:159], v0 offset:2048
	ds_read_b128 v[160:163], v0 offset:3072
	v_add_u32_e32 v0, s25, v145
	ds_read_b128 v[164:167], v0
	ds_read_b128 v[168:171], v0 offset:1024
	ds_read_b128 v[172:175], v0 offset:2048
	ds_read_b128 v[176:179], v0 offset:3072
	ds_read_b128 v[180:183], v150
	ds_read_b128 v[184:187], v150 offset:1024
	ds_read_b128 v[188:191], v150 offset:2048
	ds_read_b128 v[192:195], v150 offset:3072
	ds_read_b128 v[196:199], v150 offset:4096
	ds_read_b128 v[200:203], v150 offset:5120
	ds_read_b128 v[204:207], v150 offset:6144
	ds_read_b128 v[208:211], v150 offset:7168
	s_add_i32 m0, s60, 0xc000
	s_nop 0
	global_load_lds_dwordx4 v131, s[2:3]
	s_add_i32 m0, s60, 0xe000
	s_nop 0
	global_load_lds_dwordx4 v133, s[2:3]
	s_waitcnt vmcnt(8)
	s_waitcnt lgkmcnt(0)
	s_barrier
	s_setprio 1
	s_waitcnt lgkmcnt(0)
	v_mfma_f32_16x16x32_bf16 v[126:129], v[146:149], v[180:183], v[126:129]
	v_mfma_f32_16x16x32_bf16 v[122:125], v[156:159], v[180:183], v[122:125]
	v_mfma_f32_16x16x32_bf16 v[110:113], v[146:149], v[188:191], v[110:113]
	v_mfma_f32_16x16x32_bf16 v[106:109], v[156:159], v[188:191], v[106:109]
	v_mfma_f32_16x16x32_bf16 v[94:97], v[146:149], v[196:199], v[94:97]
	v_mfma_f32_16x16x32_bf16 v[90:93], v[156:159], v[196:199], v[90:93]
	v_mfma_f32_16x16x32_bf16 v[78:81], v[146:149], v[204:207], v[78:81]
	v_mfma_f32_16x16x32_bf16 v[74:77], v[156:159], v[204:207], v[74:77]
	v_mfma_f32_16x16x32_bf16 v[126:129], v[152:155], v[184:187], v[126:129]
	v_mfma_f32_16x16x32_bf16 v[122:125], v[160:163], v[184:187], v[122:125]
	v_mfma_f32_16x16x32_bf16 v[110:113], v[152:155], v[192:195], v[110:113]
	v_mfma_f32_16x16x32_bf16 v[106:109], v[160:163], v[192:195], v[106:109]
	v_mfma_f32_16x16x32_bf16 v[94:97], v[152:155], v[200:203], v[94:97]
	v_mfma_f32_16x16x32_bf16 v[90:93], v[160:163], v[200:203], v[90:93]
	v_mfma_f32_16x16x32_bf16 v[78:81], v[152:155], v[208:211], v[78:81]
	v_mfma_f32_16x16x32_bf16 v[74:77], v[160:163], v[208:211], v[74:77]
	s_setprio 0
	s_setprio 1
	v_mfma_f32_16x16x32_bf16 v[118:121], v[164:167], v[180:183], v[118:121]
	v_mfma_f32_16x16x32_bf16 v[114:117], v[172:175], v[180:183], v[114:117]
	v_mfma_f32_16x16x32_bf16 v[102:105], v[164:167], v[188:191], v[102:105]
	v_mfma_f32_16x16x32_bf16 v[98:101], v[172:175], v[188:191], v[98:101]
	v_mfma_f32_16x16x32_bf16 v[86:89], v[164:167], v[196:199], v[86:89]
	v_mfma_f32_16x16x32_bf16 v[82:85], v[172:175], v[196:199], v[82:85]
	v_mfma_f32_16x16x32_bf16 v[70:73], v[164:167], v[204:207], v[70:73]
	v_mfma_f32_16x16x32_bf16 v[66:69], v[172:175], v[204:207], v[66:69]
	v_mfma_f32_16x16x32_bf16 v[118:121], v[168:171], v[184:187], v[118:121]
	v_mfma_f32_16x16x32_bf16 v[114:117], v[176:179], v[184:187], v[114:117]
	v_mfma_f32_16x16x32_bf16 v[102:105], v[168:171], v[192:195], v[102:105]
	v_mfma_f32_16x16x32_bf16 v[98:101], v[176:179], v[192:195], v[98:101]
	v_mfma_f32_16x16x32_bf16 v[86:89], v[168:171], v[200:203], v[86:89]
	v_mfma_f32_16x16x32_bf16 v[82:85], v[176:179], v[200:203], v[82:85]
	v_mfma_f32_16x16x32_bf16 v[70:73], v[168:171], v[208:211], v[70:73]
	v_mfma_f32_16x16x32_bf16 v[66:69], v[176:179], v[208:211], v[66:69]
	s_setprio 0
	s_barrier
	s_add_i32 s23, s23, s42
	ds_read_b128 v[180:183], v150 offset:16384
	ds_read_b128 v[184:187], v150 offset:17408
	ds_read_b128 v[188:191], v150 offset:18432
	ds_read_b128 v[192:195], v150 offset:19456
	ds_read_b128 v[196:199], v150 offset:20480
	ds_read_b128 v[200:203], v150 offset:21504
	ds_read_b128 v[204:207], v150 offset:22528
	ds_read_b128 v[208:211], v150 offset:23552
	s_mov_b32 m0, s23
	s_nop 0
	global_load_lds_dwordx4 v137, s[6:7]
	s_add_i32 m0, s23, 0x2000
	s_add_u32 s46, s6, 0x40000
	global_load_lds_dwordx4 v139, s[6:7]
	s_addc_u32 s47, s7, 0
	s_add_i32 s23, s25, s42
	s_mov_b32 m0, s23
	s_nop 0
	global_load_lds_dwordx4 v137, s[46:47]
	s_add_i32 m0, s23, 0x2000
	s_nop 0
	global_load_lds_dwordx4 v139, s[46:47]
	s_mov_b32 m0, s60
	s_nop 0
	global_load_lds_dwordx4 v131, s[4:5]
	s_mov_b32 m0, s61
	s_nop 0
	global_load_lds_dwordx4 v133, s[4:5]
	s_waitcnt vmcnt(8)
	s_waitcnt lgkmcnt(0)
	s_barrier
	s_setprio 1
	s_waitcnt lgkmcnt(0)
	v_mfma_f32_16x16x32_bf16 v[62:65], v[146:149], v[180:183], v[62:65]
	v_mfma_f32_16x16x32_bf16 v[58:61], v[156:159], v[180:183], v[58:61]
	v_mfma_f32_16x16x32_bf16 v[46:49], v[146:149], v[188:191], v[46:49]
	v_mfma_f32_16x16x32_bf16 v[42:45], v[156:159], v[188:191], v[42:45]
	v_mfma_f32_16x16x32_bf16 v[30:33], v[146:149], v[196:199], v[30:33]
	v_mfma_f32_16x16x32_bf16 v[26:29], v[156:159], v[196:199], v[26:29]
	v_mfma_f32_16x16x32_bf16 v[14:17], v[146:149], v[204:207], v[14:17]
	v_mfma_f32_16x16x32_bf16 v[10:13], v[156:159], v[204:207], v[10:13]
	v_mfma_f32_16x16x32_bf16 v[62:65], v[152:155], v[184:187], v[62:65]
	v_mfma_f32_16x16x32_bf16 v[58:61], v[160:163], v[184:187], v[58:61]
	v_mfma_f32_16x16x32_bf16 v[46:49], v[152:155], v[192:195], v[46:49]
	v_mfma_f32_16x16x32_bf16 v[42:45], v[160:163], v[192:195], v[42:45]
	v_mfma_f32_16x16x32_bf16 v[30:33], v[152:155], v[200:203], v[30:33]
	v_mfma_f32_16x16x32_bf16 v[26:29], v[160:163], v[200:203], v[26:29]
	v_mfma_f32_16x16x32_bf16 v[14:17], v[152:155], v[208:211], v[14:17]
	v_mfma_f32_16x16x32_bf16 v[10:13], v[160:163], v[208:211], v[10:13]
	s_setprio 0
	s_setprio 1
	v_mfma_f32_16x16x32_bf16 v[54:57], v[164:167], v[180:183], v[54:57]
	v_mfma_f32_16x16x32_bf16 v[50:53], v[172:175], v[180:183], v[50:53]
	v_mfma_f32_16x16x32_bf16 v[38:41], v[164:167], v[188:191], v[38:41]
	v_mfma_f32_16x16x32_bf16 v[34:37], v[172:175], v[188:191], v[34:37]
	v_mfma_f32_16x16x32_bf16 v[22:25], v[164:167], v[196:199], v[22:25]
	v_mfma_f32_16x16x32_bf16 v[18:21], v[172:175], v[196:199], v[18:21]
	v_mfma_f32_16x16x32_bf16 v[6:9], v[164:167], v[204:207], v[6:9]
	v_mfma_f32_16x16x32_bf16 v[2:5], v[172:175], v[204:207], v[2:5]
	v_mfma_f32_16x16x32_bf16 v[54:57], v[168:171], v[184:187], v[54:57]
	v_mfma_f32_16x16x32_bf16 v[50:53], v[176:179], v[184:187], v[50:53]
	v_mfma_f32_16x16x32_bf16 v[38:41], v[168:171], v[192:195], v[38:41]
	v_mfma_f32_16x16x32_bf16 v[34:37], v[176:179], v[192:195], v[34:37]
	v_mfma_f32_16x16x32_bf16 v[22:25], v[168:171], v[200:203], v[22:25]
	v_mfma_f32_16x16x32_bf16 v[18:21], v[176:179], v[200:203], v[18:21]
	v_mfma_f32_16x16x32_bf16 v[6:9], v[168:171], v[208:211], v[6:9]
	v_mfma_f32_16x16x32_bf16 v[2:5], v[176:179], v[208:211], v[2:5]
	s_setprio 0
	s_barrier
	s_add_i32 s23, 0, 0x18000
	v_add_u32_e32 v0, s23, v145
	s_add_i32 s25, 0, 0x1c000
	ds_read_b128 v[146:149], v0
	ds_read_b128 v[152:155], v0 offset:1024
	ds_read_b128 v[156:159], v0 offset:2048
	ds_read_b128 v[160:163], v0 offset:3072
	v_add_u32_e32 v0, s25, v145
	ds_read_b128 v[164:167], v0
	ds_read_b128 v[168:171], v0 offset:1024
	ds_read_b128 v[172:175], v0 offset:2048
	ds_read_b128 v[176:179], v0 offset:3072
	s_add_u32 s46, s4, 0x40000
	s_mov_b32 m0, s66
	ds_read_b128 v[180:183], v150 offset:32768
	ds_read_b128 v[184:187], v150 offset:33792
	ds_read_b128 v[188:191], v150 offset:34816
	ds_read_b128 v[192:195], v150 offset:35840
	ds_read_b128 v[196:199], v150 offset:36864
	ds_read_b128 v[200:203], v150 offset:37888
	ds_read_b128 v[204:207], v150 offset:38912
	ds_read_b128 v[208:211], v150 offset:39936
	s_addc_u32 s47, s5, 0
	s_nop 0
	global_load_lds_dwordx4 v131, s[46:47]
	s_mov_b32 m0, s67
	s_nop 0
	global_load_lds_dwordx4 v133, s[46:47]
	s_waitcnt vmcnt(8)
	s_waitcnt lgkmcnt(0)
	s_barrier
	s_setprio 1
	s_waitcnt lgkmcnt(0)
	v_mfma_f32_16x16x32_bf16 v[126:129], v[146:149], v[180:183], v[126:129]
	v_mfma_f32_16x16x32_bf16 v[122:125], v[156:159], v[180:183], v[122:125]
	v_mfma_f32_16x16x32_bf16 v[110:113], v[146:149], v[188:191], v[110:113]
	v_mfma_f32_16x16x32_bf16 v[106:109], v[156:159], v[188:191], v[106:109]
	v_mfma_f32_16x16x32_bf16 v[94:97], v[146:149], v[196:199], v[94:97]
	v_mfma_f32_16x16x32_bf16 v[90:93], v[156:159], v[196:199], v[90:93]
	v_mfma_f32_16x16x32_bf16 v[78:81], v[146:149], v[204:207], v[78:81]
	v_mfma_f32_16x16x32_bf16 v[74:77], v[156:159], v[204:207], v[74:77]
	v_mfma_f32_16x16x32_bf16 v[126:129], v[152:155], v[184:187], v[126:129]
	v_mfma_f32_16x16x32_bf16 v[122:125], v[160:163], v[184:187], v[122:125]
	v_mfma_f32_16x16x32_bf16 v[110:113], v[152:155], v[192:195], v[110:113]
	v_mfma_f32_16x16x32_bf16 v[106:109], v[160:163], v[192:195], v[106:109]
	v_mfma_f32_16x16x32_bf16 v[94:97], v[152:155], v[200:203], v[94:97]
	v_mfma_f32_16x16x32_bf16 v[90:93], v[160:163], v[200:203], v[90:93]
	v_mfma_f32_16x16x32_bf16 v[78:81], v[152:155], v[208:211], v[78:81]
	v_mfma_f32_16x16x32_bf16 v[74:77], v[160:163], v[208:211], v[74:77]
	s_setprio 0
	s_setprio 1
	v_mfma_f32_16x16x32_bf16 v[118:121], v[164:167], v[180:183], v[118:121]
	v_mfma_f32_16x16x32_bf16 v[114:117], v[172:175], v[180:183], v[114:117]
	v_mfma_f32_16x16x32_bf16 v[102:105], v[164:167], v[188:191], v[102:105]
	v_mfma_f32_16x16x32_bf16 v[98:101], v[172:175], v[188:191], v[98:101]
	v_mfma_f32_16x16x32_bf16 v[86:89], v[164:167], v[196:199], v[86:89]
	v_mfma_f32_16x16x32_bf16 v[82:85], v[172:175], v[196:199], v[82:85]
	v_mfma_f32_16x16x32_bf16 v[70:73], v[164:167], v[204:207], v[70:73]
	v_mfma_f32_16x16x32_bf16 v[66:69], v[172:175], v[204:207], v[66:69]
	v_mfma_f32_16x16x32_bf16 v[118:121], v[168:171], v[184:187], v[118:121]
	v_mfma_f32_16x16x32_bf16 v[114:117], v[176:179], v[184:187], v[114:117]
	v_mfma_f32_16x16x32_bf16 v[102:105], v[168:171], v[192:195], v[102:105]
	v_mfma_f32_16x16x32_bf16 v[98:101], v[176:179], v[192:195], v[98:101]
	v_mfma_f32_16x16x32_bf16 v[86:89], v[168:171], v[200:203], v[86:89]
	v_mfma_f32_16x16x32_bf16 v[82:85], v[176:179], v[200:203], v[82:85]
	v_mfma_f32_16x16x32_bf16 v[70:73], v[168:171], v[208:211], v[70:73]
	v_mfma_f32_16x16x32_bf16 v[66:69], v[176:179], v[208:211], v[66:69]
	s_setprio 0
	s_barrier
	ds_read_b128 v[180:183], v150 offset:49152
	ds_read_b128 v[184:187], v150 offset:50176
	ds_read_b128 v[188:191], v150 offset:51200
	ds_read_b128 v[192:195], v150 offset:52224
	ds_read_b128 v[196:199], v150 offset:53248
	ds_read_b128 v[200:203], v150 offset:54272
	ds_read_b128 v[204:207], v150 offset:55296
	ds_read_b128 v[208:211], v150 offset:56320
	s_add_i32 s23, s23, s42
	s_add_u32 s100, s6, s38
	s_addc_u32 s101, s7, s39
	s_mov_b32 m0, s23
	s_nop 0
	global_load_lds_dwordx4 v137, s[100:101]
	s_add_i32 m0, s23, 0x2000
	s_nop 0
	s_add_u32 s6, s6, 0x40080
	s_addc_u32 s7, s7, 0
	s_add_i32 s23, s25, s42
	global_load_lds_dwordx4 v139, s[100:101]
	s_mov_b32 m0, s23
	s_nop 0
	global_load_lds_dwordx4 v137, s[6:7]
	s_add_i32 m0, s23, 0x2000
	s_nop 0
	global_load_lds_dwordx4 v139, s[6:7]
	s_mov_b32 m0, s70
	s_add_u32 s100, s4, s38
	s_addc_u32 s101, s5, s39
	v_mov_b32_e32 v0, v133
	global_load_lds_dwordx4 v131, s[100:101]
	s_mov_b32 m0, s71
	s_nop 0
	global_load_lds_dwordx4 v133, s[100:101]
	s_waitcnt vmcnt(8)
	s_waitcnt lgkmcnt(0)
	s_barrier
	s_setprio 1
	s_waitcnt lgkmcnt(0)
	v_mfma_f32_16x16x32_bf16 v[62:65], v[146:149], v[180:183], v[62:65]
	v_mfma_f32_16x16x32_bf16 v[58:61], v[156:159], v[180:183], v[58:61]
	v_mfma_f32_16x16x32_bf16 v[46:49], v[146:149], v[188:191], v[46:49]
	v_mfma_f32_16x16x32_bf16 v[42:45], v[156:159], v[188:191], v[42:45]
	v_mfma_f32_16x16x32_bf16 v[30:33], v[146:149], v[196:199], v[30:33]
	v_mfma_f32_16x16x32_bf16 v[26:29], v[156:159], v[196:199], v[26:29]
	v_mfma_f32_16x16x32_bf16 v[14:17], v[146:149], v[204:207], v[14:17]
	v_mfma_f32_16x16x32_bf16 v[10:13], v[156:159], v[204:207], v[10:13]
	v_mfma_f32_16x16x32_bf16 v[62:65], v[152:155], v[184:187], v[62:65]
	v_mfma_f32_16x16x32_bf16 v[58:61], v[160:163], v[184:187], v[58:61]
	v_mfma_f32_16x16x32_bf16 v[46:49], v[152:155], v[192:195], v[46:49]
	v_mfma_f32_16x16x32_bf16 v[42:45], v[160:163], v[192:195], v[42:45]
	v_mfma_f32_16x16x32_bf16 v[30:33], v[152:155], v[200:203], v[30:33]
	v_mfma_f32_16x16x32_bf16 v[26:29], v[160:163], v[200:203], v[26:29]
	v_mfma_f32_16x16x32_bf16 v[14:17], v[152:155], v[208:211], v[14:17]
	v_mfma_f32_16x16x32_bf16 v[10:13], v[160:163], v[208:211], v[10:13]
	s_setprio 0
	s_setprio 1
	v_mfma_f32_16x16x32_bf16 v[54:57], v[164:167], v[180:183], v[54:57]
	v_mfma_f32_16x16x32_bf16 v[50:53], v[172:175], v[180:183], v[50:53]
	v_mfma_f32_16x16x32_bf16 v[38:41], v[164:167], v[188:191], v[38:41]
	v_mfma_f32_16x16x32_bf16 v[34:37], v[172:175], v[188:191], v[34:37]
	v_mfma_f32_16x16x32_bf16 v[22:25], v[164:167], v[196:199], v[22:25]
	v_mfma_f32_16x16x32_bf16 v[18:21], v[172:175], v[196:199], v[18:21]
	v_mfma_f32_16x16x32_bf16 v[6:9], v[164:167], v[204:207], v[6:9]
	v_mfma_f32_16x16x32_bf16 v[2:5], v[172:175], v[204:207], v[2:5]
	v_mfma_f32_16x16x32_bf16 v[54:57], v[168:171], v[184:187], v[54:57]
	v_mfma_f32_16x16x32_bf16 v[50:53], v[176:179], v[184:187], v[50:53]
	v_mfma_f32_16x16x32_bf16 v[38:41], v[168:171], v[192:195], v[38:41]
	v_mfma_f32_16x16x32_bf16 v[34:37], v[176:179], v[192:195], v[34:37]
	v_mfma_f32_16x16x32_bf16 v[22:25], v[168:171], v[200:203], v[22:25]
	v_mfma_f32_16x16x32_bf16 v[18:21], v[176:179], v[200:203], v[18:21]
	v_mfma_f32_16x16x32_bf16 v[6:9], v[168:171], v[208:211], v[6:9]
	v_mfma_f32_16x16x32_bf16 v[2:5], v[176:179], v[208:211], v[2:5]
	s_setprio 0
	s_barrier
	s_add_i32 s22, s22, 2
	s_add_u32 s2, s2, 0x100
	s_addc_u32 s3, s3, 0
	s_add_u32 s8, s8, 0x100
	s_addc_u32 s9, s9, 0
	s_cmp_gt_u32 s22, 13
	s_cbranch_scc0 .LBB0_1088

.LBB0_1473:
	s_add_u32 s16, s4, s14
	s_addc_u32 s17, s5, s15
	s_add_u32 s22, s16, 0x100
	s_addc_u32 s23, s17, 0
	s_and_b64 s[10:11], s[12:13], exec
	s_cselect_b32 s11, s5, s23
	s_cselect_b32 s10, s4, s22
	s_add_u32 s14, s6, s14
	s_addc_u32 s15, s7, s15
	s_add_u32 s14, s14, 0x100
	s_addc_u32 s15, s15, 0
	s_add_i32 s69, 0, 0x10000
	s_and_b64 s[12:13], s[12:13], exec
	s_cselect_b32 s13, s7, s15
	s_cselect_b32 s12, s6, s14
	s_add_i32 s15, 0, 0x14000
	s_add_u32 s46, s16, 0x80080
	s_addc_u32 s47, s17, 0
	s_add_i32 s71, s69, s41
	s_add_i32 m0, s42, 0xc000
	s_add_i32 s74, s42, 0xe000
	s_add_i32 s67, s71, 0x2000
	v_add_u32_e32 v0, s69, v136
	s_add_u32 s22, s12, 0x40000
	ds_read_b128 v[138:141], v0
	ds_read_b128 v[142:145], v0 offset:1024
	ds_read_b128 v[146:149], v0 offset:2048
	ds_read_b128 v[150:153], v0 offset:3072
	v_add_u32_e32 v0, s15, v136
	s_addc_u32 s23, s13, 0
	s_add_i32 s68, s15, s41
	ds_read_b128 v[154:157], v0
	ds_read_b128 v[158:161], v0 offset:1024
	ds_read_b128 v[162:165], v0 offset:2048
	ds_read_b128 v[166:169], v0 offset:3072
	s_add_i32 s66, s68, 0x2000
	s_add_i32 s65, 0, 0x18000
	s_add_i32 s64, 0, 0x1c000
	s_add_u32 s16, s10, 0x80000
	s_addc_u32 s17, s11, 0
	s_add_i32 s61, s65, s41
	s_add_i32 s60, s61, 0x2000
	s_add_u32 s14, s12, 0x40080
	s_addc_u32 s15, s13, 0
	s_add_i32 s70, s64, s41
	s_add_i32 s69, s70, 0x2000
	ds_read_b128 v[170:173], v137
	ds_read_b128 v[174:177], v137 offset:1024
	ds_read_b128 v[178:181], v137 offset:2048
	ds_read_b128 v[182:185], v137 offset:3072
	ds_read_b128 v[186:189], v137 offset:4096
	ds_read_b128 v[190:193], v137 offset:5120
	ds_read_b128 v[194:197], v137 offset:6144
	ds_read_b128 v[198:201], v137 offset:7168
	s_nop 0
	global_load_lds_dwordx4 v130, s[46:47]
	s_mov_b32 m0, s74
	s_nop 0
	global_load_lds_dwordx4 v132, s[46:47]
	s_waitcnt vmcnt(8)
	s_waitcnt lgkmcnt(0)
	s_barrier
	s_setprio 1
	s_waitcnt lgkmcnt(0)
	v_mfma_f32_16x16x32_bf16 v[126:129], v[138:141], v[170:173], v[126:129]
	v_mfma_f32_16x16x32_bf16 v[122:125], v[146:149], v[170:173], v[122:125]
	v_mfma_f32_16x16x32_bf16 v[118:121], v[138:141], v[178:181], v[118:121]
	v_mfma_f32_16x16x32_bf16 v[110:113], v[146:149], v[178:181], v[110:113]
	v_mfma_f32_16x16x32_bf16 v[102:105], v[138:141], v[186:189], v[102:105]
	v_mfma_f32_16x16x32_bf16 v[94:97], v[146:149], v[186:189], v[94:97]
	v_mfma_f32_16x16x32_bf16 v[86:89], v[138:141], v[194:197], v[86:89]
	v_mfma_f32_16x16x32_bf16 v[78:81], v[146:149], v[194:197], v[78:81]
	v_mfma_f32_16x16x32_bf16 v[126:129], v[142:145], v[174:177], v[126:129]
	v_mfma_f32_16x16x32_bf16 v[122:125], v[150:153], v[174:177], v[122:125]
	v_mfma_f32_16x16x32_bf16 v[118:121], v[142:145], v[182:185], v[118:121]
	v_mfma_f32_16x16x32_bf16 v[110:113], v[150:153], v[182:185], v[110:113]
	v_mfma_f32_16x16x32_bf16 v[102:105], v[142:145], v[190:193], v[102:105]
	v_mfma_f32_16x16x32_bf16 v[94:97], v[150:153], v[190:193], v[94:97]
	v_mfma_f32_16x16x32_bf16 v[86:89], v[142:145], v[198:201], v[86:89]
	v_mfma_f32_16x16x32_bf16 v[78:81], v[150:153], v[198:201], v[78:81]
	s_setprio 0
	s_setprio 1
	v_mfma_f32_16x16x32_bf16 v[114:117], v[154:157], v[170:173], v[114:117]
	v_mfma_f32_16x16x32_bf16 v[106:109], v[162:165], v[170:173], v[106:109]
	v_mfma_f32_16x16x32_bf16 v[98:101], v[154:157], v[178:181], v[98:101]
	v_mfma_f32_16x16x32_bf16 v[90:93], v[162:165], v[178:181], v[90:93]
	v_mfma_f32_16x16x32_bf16 v[82:85], v[154:157], v[186:189], v[82:85]
	v_mfma_f32_16x16x32_bf16 v[74:77], v[162:165], v[186:189], v[74:77]
	v_mfma_f32_16x16x32_bf16 v[70:73], v[154:157], v[194:197], v[70:73]
	v_mfma_f32_16x16x32_bf16 v[62:65], v[162:165], v[194:197], v[62:65]
	v_mfma_f32_16x16x32_bf16 v[114:117], v[158:161], v[174:177], v[114:117]
	v_mfma_f32_16x16x32_bf16 v[106:109], v[166:169], v[174:177], v[106:109]
	v_mfma_f32_16x16x32_bf16 v[98:101], v[158:161], v[182:185], v[98:101]
	v_mfma_f32_16x16x32_bf16 v[90:93], v[166:169], v[182:185], v[90:93]
	v_mfma_f32_16x16x32_bf16 v[82:85], v[158:161], v[190:193], v[82:85]
	v_mfma_f32_16x16x32_bf16 v[74:77], v[166:169], v[190:193], v[74:77]
	v_mfma_f32_16x16x32_bf16 v[70:73], v[158:161], v[198:201], v[70:73]
	v_mfma_f32_16x16x32_bf16 v[62:65], v[166:169], v[198:201], v[62:65]
	s_setprio 0
	s_barrier
	s_mov_b32 m0, s71
	ds_read_b128 v[170:173], v137 offset:16384
	ds_read_b128 v[174:177], v137 offset:17408
	ds_read_b128 v[178:181], v137 offset:18432
	ds_read_b128 v[182:185], v137 offset:19456
	ds_read_b128 v[186:189], v137 offset:20480
	ds_read_b128 v[190:193], v137 offset:21504
	ds_read_b128 v[194:197], v137 offset:22528
	ds_read_b128 v[198:201], v137 offset:23552
	s_nop 0
	global_load_lds_dwordx4 v131, s[12:13]
	s_mov_b32 m0, s67
	s_nop 0
	global_load_lds_dwordx4 v133, s[12:13]
	s_mov_b32 m0, s68
	s_nop 0
	global_load_lds_dwordx4 v131, s[22:23]
	s_mov_b32 m0, s66
	s_nop 0
	global_load_lds_dwordx4 v133, s[22:23]
	s_mov_b32 m0, s42
	s_nop 0
	global_load_lds_dwordx4 v130, s[10:11]
	s_mov_b32 m0, s43
	s_nop 0
	global_load_lds_dwordx4 v132, s[10:11]
	s_waitcnt vmcnt(8)
	s_waitcnt lgkmcnt(0)
	s_barrier
	s_setprio 1
	s_waitcnt lgkmcnt(0)
	v_mfma_f32_16x16x32_bf16 v[66:69], v[138:141], v[170:173], v[66:69]
	v_mfma_f32_16x16x32_bf16 v[58:61], v[146:149], v[170:173], v[58:61]
	v_mfma_f32_16x16x32_bf16 v[54:57], v[138:141], v[178:181], v[54:57]
	v_mfma_f32_16x16x32_bf16 v[46:49], v[146:149], v[178:181], v[46:49]
	v_mfma_f32_16x16x32_bf16 v[38:41], v[138:141], v[186:189], v[38:41]
	v_mfma_f32_16x16x32_bf16 v[30:33], v[146:149], v[186:189], v[30:33]
	v_mfma_f32_16x16x32_bf16 v[22:25], v[138:141], v[194:197], v[22:25]
	v_mfma_f32_16x16x32_bf16 v[14:17], v[146:149], v[194:197], v[14:17]
	v_mfma_f32_16x16x32_bf16 v[66:69], v[142:145], v[174:177], v[66:69]
	v_mfma_f32_16x16x32_bf16 v[58:61], v[150:153], v[174:177], v[58:61]
	v_mfma_f32_16x16x32_bf16 v[54:57], v[142:145], v[182:185], v[54:57]
	v_mfma_f32_16x16x32_bf16 v[46:49], v[150:153], v[182:185], v[46:49]
	v_mfma_f32_16x16x32_bf16 v[38:41], v[142:145], v[190:193], v[38:41]
	v_mfma_f32_16x16x32_bf16 v[30:33], v[150:153], v[190:193], v[30:33]
	v_mfma_f32_16x16x32_bf16 v[22:25], v[142:145], v[198:201], v[22:25]
	v_mfma_f32_16x16x32_bf16 v[14:17], v[150:153], v[198:201], v[14:17]
	s_setprio 0
	s_setprio 1
	v_mfma_f32_16x16x32_bf16 v[50:53], v[154:157], v[170:173], v[50:53]
	v_mfma_f32_16x16x32_bf16 v[42:45], v[162:165], v[170:173], v[42:45]
	v_mfma_f32_16x16x32_bf16 v[34:37], v[154:157], v[178:181], v[34:37]
	v_mfma_f32_16x16x32_bf16 v[26:29], v[162:165], v[178:181], v[26:29]
	v_mfma_f32_16x16x32_bf16 v[18:21], v[154:157], v[186:189], v[18:21]
	v_mfma_f32_16x16x32_bf16 v[10:13], v[162:165], v[186:189], v[10:13]
	v_mfma_f32_16x16x32_bf16 v[6:9], v[154:157], v[194:197], v[6:9]
	v_mfma_f32_16x16x32_bf16 v[2:5], v[162:165], v[194:197], v[2:5]
	v_mfma_f32_16x16x32_bf16 v[50:53], v[158:161], v[174:177], v[50:53]
	v_mfma_f32_16x16x32_bf16 v[42:45], v[166:169], v[174:177], v[42:45]
	v_mfma_f32_16x16x32_bf16 v[34:37], v[158:161], v[182:185], v[34:37]
	v_mfma_f32_16x16x32_bf16 v[26:29], v[166:169], v[182:185], v[26:29]
	v_mfma_f32_16x16x32_bf16 v[18:21], v[158:161], v[190:193], v[18:21]
	v_mfma_f32_16x16x32_bf16 v[10:13], v[166:169], v[190:193], v[10:13]
	v_mfma_f32_16x16x32_bf16 v[6:9], v[158:161], v[198:201], v[6:9]
	v_mfma_f32_16x16x32_bf16 v[2:5], v[166:169], v[198:201], v[2:5]
	s_setprio 0
	s_barrier
	v_add_u32_e32 v0, s65, v136
	ds_read_b128 v[138:141], v0
	ds_read_b128 v[142:145], v0 offset:1024
	ds_read_b128 v[146:149], v0 offset:2048
	ds_read_b128 v[150:153], v0 offset:3072
	v_add_u32_e32 v0, s64, v136
	ds_read_b128 v[154:157], v0
	ds_read_b128 v[158:161], v0 offset:1024
	ds_read_b128 v[162:165], v0 offset:2048
	ds_read_b128 v[166:169], v0 offset:3072
	s_mov_b32 m0, s50
	ds_read_b128 v[170:173], v137 offset:32768
	ds_read_b128 v[174:177], v137 offset:33792
	ds_read_b128 v[178:181], v137 offset:34816
	ds_read_b128 v[182:185], v137 offset:35840
	ds_read_b128 v[186:189], v137 offset:36864
	ds_read_b128 v[190:193], v137 offset:37888
	ds_read_b128 v[194:197], v137 offset:38912
	ds_read_b128 v[198:201], v137 offset:39936
	s_nop 0
	global_load_lds_dwordx4 v130, s[16:17]
	s_mov_b32 m0, s51
	s_nop 0
	global_load_lds_dwordx4 v132, s[16:17]
	s_waitcnt vmcnt(8)
	s_waitcnt lgkmcnt(0)
	s_barrier
	s_setprio 1
	s_waitcnt lgkmcnt(0)
	v_mfma_f32_16x16x32_bf16 v[126:129], v[138:141], v[170:173], v[126:129]
	v_mfma_f32_16x16x32_bf16 v[122:125], v[146:149], v[170:173], v[122:125]
	v_mfma_f32_16x16x32_bf16 v[118:121], v[138:141], v[178:181], v[118:121]
	v_mfma_f32_16x16x32_bf16 v[110:113], v[146:149], v[178:181], v[110:113]
	v_mfma_f32_16x16x32_bf16 v[102:105], v[138:141], v[186:189], v[102:105]
	v_mfma_f32_16x16x32_bf16 v[94:97], v[146:149], v[186:189], v[94:97]
	v_mfma_f32_16x16x32_bf16 v[86:89], v[138:141], v[194:197], v[86:89]
	v_mfma_f32_16x16x32_bf16 v[78:81], v[146:149], v[194:197], v[78:81]
	v_mfma_f32_16x16x32_bf16 v[126:129], v[142:145], v[174:177], v[126:129]
	v_mfma_f32_16x16x32_bf16 v[122:125], v[150:153], v[174:177], v[122:125]
	v_mfma_f32_16x16x32_bf16 v[118:121], v[142:145], v[182:185], v[118:121]
	v_mfma_f32_16x16x32_bf16 v[110:113], v[150:153], v[182:185], v[110:113]
	v_mfma_f32_16x16x32_bf16 v[102:105], v[142:145], v[190:193], v[102:105]
	v_mfma_f32_16x16x32_bf16 v[94:97], v[150:153], v[190:193], v[94:97]
	v_mfma_f32_16x16x32_bf16 v[86:89], v[142:145], v[198:201], v[86:89]
	v_mfma_f32_16x16x32_bf16 v[78:81], v[150:153], v[198:201], v[78:81]
	s_setprio 0
	s_setprio 1
	v_mfma_f32_16x16x32_bf16 v[114:117], v[154:157], v[170:173], v[114:117]
	v_mfma_f32_16x16x32_bf16 v[106:109], v[162:165], v[170:173], v[106:109]
	v_mfma_f32_16x16x32_bf16 v[98:101], v[154:157], v[178:181], v[98:101]
	v_mfma_f32_16x16x32_bf16 v[90:93], v[162:165], v[178:181], v[90:93]
	v_mfma_f32_16x16x32_bf16 v[82:85], v[154:157], v[186:189], v[82:85]
	v_mfma_f32_16x16x32_bf16 v[74:77], v[162:165], v[186:189], v[74:77]
	v_mfma_f32_16x16x32_bf16 v[70:73], v[154:157], v[194:197], v[70:73]
	v_mfma_f32_16x16x32_bf16 v[62:65], v[162:165], v[194:197], v[62:65]
	v_mfma_f32_16x16x32_bf16 v[114:117], v[158:161], v[174:177], v[114:117]
	v_mfma_f32_16x16x32_bf16 v[106:109], v[166:169], v[174:177], v[106:109]
	v_mfma_f32_16x16x32_bf16 v[98:101], v[158:161], v[182:185], v[98:101]
	v_mfma_f32_16x16x32_bf16 v[90:93], v[166:169], v[182:185], v[90:93]
	v_mfma_f32_16x16x32_bf16 v[82:85], v[158:161], v[190:193], v[82:85]
	v_mfma_f32_16x16x32_bf16 v[74:77], v[166:169], v[190:193], v[74:77]
	v_mfma_f32_16x16x32_bf16 v[70:73], v[158:161], v[198:201], v[70:73]
	v_mfma_f32_16x16x32_bf16 v[62:65], v[166:169], v[198:201], v[62:65]
	s_setprio 0
	s_barrier
	ds_read_b128 v[170:173], v137 offset:49152
	ds_read_b128 v[174:177], v137 offset:50176
	ds_read_b128 v[178:181], v137 offset:51200
	ds_read_b128 v[182:185], v137 offset:52224
	ds_read_b128 v[186:189], v137 offset:53248
	ds_read_b128 v[190:193], v137 offset:54272
	ds_read_b128 v[194:197], v137 offset:55296
	ds_read_b128 v[198:201], v137 offset:56320
	s_mov_b32 m0, s61
	s_add_u32 s100, s12, s38
	s_addc_u32 s101, s13, s39
	global_load_lds_dwordx4 v131, s[100:101]
	s_mov_b32 m0, s60
	s_nop 0
	global_load_lds_dwordx4 v133, s[100:101]
	s_mov_b32 m0, s70
	s_nop 0
	global_load_lds_dwordx4 v131, s[14:15]
	s_mov_b32 m0, s69
	s_nop 0
	global_load_lds_dwordx4 v133, s[14:15]
	s_mov_b32 m0, s58
	s_add_u32 s100, s10, s38
	s_addc_u32 s101, s11, s39
	v_mov_b32_e32 v0, v132
	global_load_lds_dwordx4 v130, s[100:101]
	s_mov_b32 m0, s59
	s_nop 0
	global_load_lds_dwordx4 v132, s[100:101]
	s_waitcnt vmcnt(8)
	s_waitcnt lgkmcnt(0)
	s_barrier
	s_setprio 1
	s_waitcnt lgkmcnt(0)
	v_mfma_f32_16x16x32_bf16 v[66:69], v[138:141], v[170:173], v[66:69]
	v_mfma_f32_16x16x32_bf16 v[58:61], v[146:149], v[170:173], v[58:61]
	v_mfma_f32_16x16x32_bf16 v[54:57], v[138:141], v[178:181], v[54:57]
	v_mfma_f32_16x16x32_bf16 v[46:49], v[146:149], v[178:181], v[46:49]
	v_mfma_f32_16x16x32_bf16 v[38:41], v[138:141], v[186:189], v[38:41]
	v_mfma_f32_16x16x32_bf16 v[30:33], v[146:149], v[186:189], v[30:33]
	v_mfma_f32_16x16x32_bf16 v[22:25], v[138:141], v[194:197], v[22:25]
	v_mfma_f32_16x16x32_bf16 v[14:17], v[146:149], v[194:197], v[14:17]
	v_mfma_f32_16x16x32_bf16 v[66:69], v[142:145], v[174:177], v[66:69]
	v_mfma_f32_16x16x32_bf16 v[58:61], v[150:153], v[174:177], v[58:61]
	v_mfma_f32_16x16x32_bf16 v[54:57], v[142:145], v[182:185], v[54:57]
	v_mfma_f32_16x16x32_bf16 v[46:49], v[150:153], v[182:185], v[46:49]
	v_mfma_f32_16x16x32_bf16 v[38:41], v[142:145], v[190:193], v[38:41]
	v_mfma_f32_16x16x32_bf16 v[30:33], v[150:153], v[190:193], v[30:33]
	v_mfma_f32_16x16x32_bf16 v[22:25], v[142:145], v[198:201], v[22:25]
	v_mfma_f32_16x16x32_bf16 v[14:17], v[150:153], v[198:201], v[14:17]
	s_setprio 0
	s_setprio 1
	v_mfma_f32_16x16x32_bf16 v[50:53], v[154:157], v[170:173], v[50:53]
	v_mfma_f32_16x16x32_bf16 v[42:45], v[162:165], v[170:173], v[42:45]
	v_mfma_f32_16x16x32_bf16 v[34:37], v[154:157], v[178:181], v[34:37]
	v_mfma_f32_16x16x32_bf16 v[26:29], v[162:165], v[178:181], v[26:29]
	v_mfma_f32_16x16x32_bf16 v[18:21], v[154:157], v[186:189], v[18:21]
	v_mfma_f32_16x16x32_bf16 v[10:13], v[162:165], v[186:189], v[10:13]
	v_mfma_f32_16x16x32_bf16 v[6:9], v[154:157], v[194:197], v[6:9]
	v_mfma_f32_16x16x32_bf16 v[2:5], v[162:165], v[194:197], v[2:5]
	v_mfma_f32_16x16x32_bf16 v[50:53], v[158:161], v[174:177], v[50:53]
	v_mfma_f32_16x16x32_bf16 v[42:45], v[166:169], v[174:177], v[42:45]
	v_mfma_f32_16x16x32_bf16 v[34:37], v[158:161], v[182:185], v[34:37]
	v_mfma_f32_16x16x32_bf16 v[26:29], v[166:169], v[182:185], v[26:29]
	v_mfma_f32_16x16x32_bf16 v[18:21], v[158:161], v[190:193], v[18:21]
	v_mfma_f32_16x16x32_bf16 v[10:13], v[166:169], v[190:193], v[10:13]
	v_mfma_f32_16x16x32_bf16 v[6:9], v[158:161], v[198:201], v[6:9]
	v_mfma_f32_16x16x32_bf16 v[2:5], v[166:169], v[198:201], v[2:5]
	s_setprio 0
	s_barrier
	s_andn2_b64 vcc, exec, s[8:9]
	s_mov_b64 s[12:13], -1
	s_mov_b64 s[8:9], 0
	s_mov_b64 s[14:15], 0x100
	s_cbranch_vccz .LBB0_1473
	s_cmpk_lt_u32 s24, 0x100
	s_cbranch_scc0 .LBB0_1476
	s_barrier

.LBB0_1481:
	s_add_u32 s16, s4, s14
	s_addc_u32 s17, s5, s15
	s_add_u32 s22, s16, 0x100
	s_addc_u32 s23, s17, 0
	s_and_b64 s[10:11], s[12:13], exec
	s_cselect_b32 s11, s5, s23
	s_cselect_b32 s10, s4, s22
	s_add_u32 s14, s6, s14
	s_addc_u32 s15, s7, s15
	s_add_u32 s14, s14, 0x900
	s_addc_u32 s15, s15, 0
	s_add_i32 s70, 0, 0x10000
	s_and_b64 s[12:13], s[12:13], exec
	s_cselect_b32 s13, s58, s15
	s_cselect_b32 s12, s51, s14
	s_add_i32 s15, 0, 0x14000
	s_add_u32 s46, s16, 0x40080
	s_addc_u32 s47, s17, 0
	s_add_i32 s74, s70, s40
	s_add_i32 m0, s41, 0xc000
	s_add_i32 s75, s41, 0xe000
	s_add_i32 s68, s74, 0x2000
	v_add_u32_e32 v0, s70, v136
	s_add_u32 s22, s12, 0x80000
	ds_read_b128 v[138:141], v0
	ds_read_b128 v[142:145], v0 offset:1024
	ds_read_b128 v[146:149], v0 offset:2048
	ds_read_b128 v[150:153], v0 offset:3072
	v_add_u32_e32 v0, s15, v136
	s_addc_u32 s23, s13, 0
	s_add_i32 s69, s15, s40
	ds_read_b128 v[154:157], v0
	ds_read_b128 v[158:161], v0 offset:1024
	ds_read_b128 v[162:165], v0 offset:2048
	ds_read_b128 v[166:169], v0 offset:3072
	s_add_i32 s67, s69, 0x2000
	s_add_i32 s66, 0, 0x18000
	s_add_i32 s65, 0, 0x1c000
	s_add_u32 s16, s10, 0x40000
	s_addc_u32 s17, s11, 0
	s_add_i32 s64, s66, s40
	s_add_i32 s61, s64, 0x2000
	s_add_u32 s14, s12, 0x80080
	s_addc_u32 s15, s13, 0
	s_add_i32 s71, s65, s40
	s_add_i32 s70, s71, 0x2000
	ds_read_b128 v[170:173], v137
	ds_read_b128 v[174:177], v137 offset:1024
	ds_read_b128 v[178:181], v137 offset:2048
	ds_read_b128 v[182:185], v137 offset:3072
	ds_read_b128 v[186:189], v137 offset:4096
	ds_read_b128 v[190:193], v137 offset:5120
	ds_read_b128 v[194:197], v137 offset:6144
	ds_read_b128 v[198:201], v137 offset:7168
	s_nop 0
	global_load_lds_dwordx4 v130, s[46:47]
	s_mov_b32 m0, s75
	s_nop 0
	global_load_lds_dwordx4 v132, s[46:47]
	s_waitcnt vmcnt(8)
	s_waitcnt lgkmcnt(0)
	s_barrier
	s_setprio 1
	s_waitcnt lgkmcnt(0)
	v_mfma_f32_16x16x32_bf16 v[126:129], v[138:141], v[170:173], v[126:129]
	v_mfma_f32_16x16x32_bf16 v[122:125], v[146:149], v[170:173], v[122:125]
	v_mfma_f32_16x16x32_bf16 v[118:121], v[138:141], v[178:181], v[118:121]
	v_mfma_f32_16x16x32_bf16 v[110:113], v[146:149], v[178:181], v[110:113]
	v_mfma_f32_16x16x32_bf16 v[102:105], v[138:141], v[186:189], v[102:105]
	v_mfma_f32_16x16x32_bf16 v[94:97], v[146:149], v[186:189], v[94:97]
	v_mfma_f32_16x16x32_bf16 v[86:89], v[138:141], v[194:197], v[86:89]
	v_mfma_f32_16x16x32_bf16 v[78:81], v[146:149], v[194:197], v[78:81]
	v_mfma_f32_16x16x32_bf16 v[126:129], v[142:145], v[174:177], v[126:129]
	v_mfma_f32_16x16x32_bf16 v[122:125], v[150:153], v[174:177], v[122:125]
	v_mfma_f32_16x16x32_bf16 v[118:121], v[142:145], v[182:185], v[118:121]
	v_mfma_f32_16x16x32_bf16 v[110:113], v[150:153], v[182:185], v[110:113]
	v_mfma_f32_16x16x32_bf16 v[102:105], v[142:145], v[190:193], v[102:105]
	v_mfma_f32_16x16x32_bf16 v[94:97], v[150:153], v[190:193], v[94:97]
	v_mfma_f32_16x16x32_bf16 v[86:89], v[142:145], v[198:201], v[86:89]
	v_mfma_f32_16x16x32_bf16 v[78:81], v[150:153], v[198:201], v[78:81]
	s_setprio 0
	s_setprio 1
	v_mfma_f32_16x16x32_bf16 v[114:117], v[154:157], v[170:173], v[114:117]
	v_mfma_f32_16x16x32_bf16 v[106:109], v[162:165], v[170:173], v[106:109]
	v_mfma_f32_16x16x32_bf16 v[98:101], v[154:157], v[178:181], v[98:101]
	v_mfma_f32_16x16x32_bf16 v[90:93], v[162:165], v[178:181], v[90:93]
	v_mfma_f32_16x16x32_bf16 v[82:85], v[154:157], v[186:189], v[82:85]
	v_mfma_f32_16x16x32_bf16 v[74:77], v[162:165], v[186:189], v[74:77]
	v_mfma_f32_16x16x32_bf16 v[70:73], v[154:157], v[194:197], v[70:73]
	v_mfma_f32_16x16x32_bf16 v[62:65], v[162:165], v[194:197], v[62:65]
	v_mfma_f32_16x16x32_bf16 v[114:117], v[158:161], v[174:177], v[114:117]
	v_mfma_f32_16x16x32_bf16 v[106:109], v[166:169], v[174:177], v[106:109]
	v_mfma_f32_16x16x32_bf16 v[98:101], v[158:161], v[182:185], v[98:101]
	v_mfma_f32_16x16x32_bf16 v[90:93], v[166:169], v[182:185], v[90:93]
	v_mfma_f32_16x16x32_bf16 v[82:85], v[158:161], v[190:193], v[82:85]
	v_mfma_f32_16x16x32_bf16 v[74:77], v[166:169], v[190:193], v[74:77]
	v_mfma_f32_16x16x32_bf16 v[70:73], v[158:161], v[198:201], v[70:73]
	v_mfma_f32_16x16x32_bf16 v[62:65], v[166:169], v[198:201], v[62:65]
	s_setprio 0
	s_barrier
	s_mov_b32 m0, s74
	ds_read_b128 v[170:173], v137 offset:16384
	ds_read_b128 v[174:177], v137 offset:17408
	ds_read_b128 v[178:181], v137 offset:18432
	ds_read_b128 v[182:185], v137 offset:19456
	ds_read_b128 v[186:189], v137 offset:20480
	ds_read_b128 v[190:193], v137 offset:21504
	ds_read_b128 v[194:197], v137 offset:22528
	ds_read_b128 v[198:201], v137 offset:23552
	s_nop 0
	global_load_lds_dwordx4 v131, s[12:13]
	s_mov_b32 m0, s68
	s_nop 0
	global_load_lds_dwordx4 v133, s[12:13]
	s_mov_b32 m0, s69
	s_nop 0
	global_load_lds_dwordx4 v131, s[22:23]
	s_mov_b32 m0, s67
	s_nop 0
	global_load_lds_dwordx4 v133, s[22:23]
	s_mov_b32 m0, s41
	s_nop 0
	global_load_lds_dwordx4 v130, s[10:11]
	s_mov_b32 m0, s42
	s_nop 0
	global_load_lds_dwordx4 v132, s[10:11]
	s_waitcnt vmcnt(8)
	s_waitcnt lgkmcnt(0)
	s_barrier
	s_setprio 1
	s_waitcnt lgkmcnt(0)
	v_mfma_f32_16x16x32_bf16 v[66:69], v[138:141], v[170:173], v[66:69]
	v_mfma_f32_16x16x32_bf16 v[58:61], v[146:149], v[170:173], v[58:61]
	v_mfma_f32_16x16x32_bf16 v[54:57], v[138:141], v[178:181], v[54:57]
	v_mfma_f32_16x16x32_bf16 v[46:49], v[146:149], v[178:181], v[46:49]
	v_mfma_f32_16x16x32_bf16 v[38:41], v[138:141], v[186:189], v[38:41]
	v_mfma_f32_16x16x32_bf16 v[30:33], v[146:149], v[186:189], v[30:33]
	v_mfma_f32_16x16x32_bf16 v[22:25], v[138:141], v[194:197], v[22:25]
	v_mfma_f32_16x16x32_bf16 v[14:17], v[146:149], v[194:197], v[14:17]
	v_mfma_f32_16x16x32_bf16 v[66:69], v[142:145], v[174:177], v[66:69]
	v_mfma_f32_16x16x32_bf16 v[58:61], v[150:153], v[174:177], v[58:61]
	v_mfma_f32_16x16x32_bf16 v[54:57], v[142:145], v[182:185], v[54:57]
	v_mfma_f32_16x16x32_bf16 v[46:49], v[150:153], v[182:185], v[46:49]
	v_mfma_f32_16x16x32_bf16 v[38:41], v[142:145], v[190:193], v[38:41]
	v_mfma_f32_16x16x32_bf16 v[30:33], v[150:153], v[190:193], v[30:33]
	v_mfma_f32_16x16x32_bf16 v[22:25], v[142:145], v[198:201], v[22:25]
	v_mfma_f32_16x16x32_bf16 v[14:17], v[150:153], v[198:201], v[14:17]
	s_setprio 0
	s_setprio 1
	v_mfma_f32_16x16x32_bf16 v[50:53], v[154:157], v[170:173], v[50:53]
	v_mfma_f32_16x16x32_bf16 v[42:45], v[162:165], v[170:173], v[42:45]
	v_mfma_f32_16x16x32_bf16 v[34:37], v[154:157], v[178:181], v[34:37]
	v_mfma_f32_16x16x32_bf16 v[26:29], v[162:165], v[178:181], v[26:29]
	v_mfma_f32_16x16x32_bf16 v[18:21], v[154:157], v[186:189], v[18:21]
	v_mfma_f32_16x16x32_bf16 v[10:13], v[162:165], v[186:189], v[10:13]
	v_mfma_f32_16x16x32_bf16 v[6:9], v[154:157], v[194:197], v[6:9]
	v_mfma_f32_16x16x32_bf16 v[2:5], v[162:165], v[194:197], v[2:5]
	v_mfma_f32_16x16x32_bf16 v[50:53], v[158:161], v[174:177], v[50:53]
	v_mfma_f32_16x16x32_bf16 v[42:45], v[166:169], v[174:177], v[42:45]
	v_mfma_f32_16x16x32_bf16 v[34:37], v[158:161], v[182:185], v[34:37]
	v_mfma_f32_16x16x32_bf16 v[26:29], v[166:169], v[182:185], v[26:29]
	v_mfma_f32_16x16x32_bf16 v[18:21], v[158:161], v[190:193], v[18:21]
	v_mfma_f32_16x16x32_bf16 v[10:13], v[166:169], v[190:193], v[10:13]
	v_mfma_f32_16x16x32_bf16 v[6:9], v[158:161], v[198:201], v[6:9]
	v_mfma_f32_16x16x32_bf16 v[2:5], v[166:169], v[198:201], v[2:5]
	s_setprio 0
	s_barrier
	v_add_u32_e32 v0, s66, v136
	ds_read_b128 v[138:141], v0
	ds_read_b128 v[142:145], v0 offset:1024
	ds_read_b128 v[146:149], v0 offset:2048
	ds_read_b128 v[150:153], v0 offset:3072
	v_add_u32_e32 v0, s65, v136
	ds_read_b128 v[154:157], v0
	ds_read_b128 v[158:161], v0 offset:1024
	ds_read_b128 v[162:165], v0 offset:2048
	ds_read_b128 v[166:169], v0 offset:3072
	s_mov_b32 m0, s43
	ds_read_b128 v[170:173], v137 offset:32768
	ds_read_b128 v[174:177], v137 offset:33792
	ds_read_b128 v[178:181], v137 offset:34816
	ds_read_b128 v[182:185], v137 offset:35840
	ds_read_b128 v[186:189], v137 offset:36864
	ds_read_b128 v[190:193], v137 offset:37888
	ds_read_b128 v[194:197], v137 offset:38912
	ds_read_b128 v[198:201], v137 offset:39936
	s_nop 0
	global_load_lds_dwordx4 v130, s[16:17]
	s_mov_b32 m0, s50
	s_nop 0
	global_load_lds_dwordx4 v132, s[16:17]
	s_waitcnt vmcnt(8)
	s_waitcnt lgkmcnt(0)
	s_barrier
	s_setprio 1
	s_waitcnt lgkmcnt(0)
	v_mfma_f32_16x16x32_bf16 v[126:129], v[138:141], v[170:173], v[126:129]
	v_mfma_f32_16x16x32_bf16 v[122:125], v[146:149], v[170:173], v[122:125]
	v_mfma_f32_16x16x32_bf16 v[118:121], v[138:141], v[178:181], v[118:121]
	v_mfma_f32_16x16x32_bf16 v[110:113], v[146:149], v[178:181], v[110:113]
	v_mfma_f32_16x16x32_bf16 v[102:105], v[138:141], v[186:189], v[102:105]
	v_mfma_f32_16x16x32_bf16 v[94:97], v[146:149], v[186:189], v[94:97]
	v_mfma_f32_16x16x32_bf16 v[86:89], v[138:141], v[194:197], v[86:89]
	v_mfma_f32_16x16x32_bf16 v[78:81], v[146:149], v[194:197], v[78:81]
	v_mfma_f32_16x16x32_bf16 v[126:129], v[142:145], v[174:177], v[126:129]
	v_mfma_f32_16x16x32_bf16 v[122:125], v[150:153], v[174:177], v[122:125]
	v_mfma_f32_16x16x32_bf16 v[118:121], v[142:145], v[182:185], v[118:121]
	v_mfma_f32_16x16x32_bf16 v[110:113], v[150:153], v[182:185], v[110:113]
	v_mfma_f32_16x16x32_bf16 v[102:105], v[142:145], v[190:193], v[102:105]
	v_mfma_f32_16x16x32_bf16 v[94:97], v[150:153], v[190:193], v[94:97]
	v_mfma_f32_16x16x32_bf16 v[86:89], v[142:145], v[198:201], v[86:89]
	v_mfma_f32_16x16x32_bf16 v[78:81], v[150:153], v[198:201], v[78:81]
	s_setprio 0
	s_setprio 1
	v_mfma_f32_16x16x32_bf16 v[114:117], v[154:157], v[170:173], v[114:117]
	v_mfma_f32_16x16x32_bf16 v[106:109], v[162:165], v[170:173], v[106:109]
	v_mfma_f32_16x16x32_bf16 v[98:101], v[154:157], v[178:181], v[98:101]
	v_mfma_f32_16x16x32_bf16 v[90:93], v[162:165], v[178:181], v[90:93]
	v_mfma_f32_16x16x32_bf16 v[82:85], v[154:157], v[186:189], v[82:85]
	v_mfma_f32_16x16x32_bf16 v[74:77], v[162:165], v[186:189], v[74:77]
	v_mfma_f32_16x16x32_bf16 v[70:73], v[154:157], v[194:197], v[70:73]
	v_mfma_f32_16x16x32_bf16 v[62:65], v[162:165], v[194:197], v[62:65]
	v_mfma_f32_16x16x32_bf16 v[114:117], v[158:161], v[174:177], v[114:117]
	v_mfma_f32_16x16x32_bf16 v[106:109], v[166:169], v[174:177], v[106:109]
	v_mfma_f32_16x16x32_bf16 v[98:101], v[158:161], v[182:185], v[98:101]
	v_mfma_f32_16x16x32_bf16 v[90:93], v[166:169], v[182:185], v[90:93]
	v_mfma_f32_16x16x32_bf16 v[82:85], v[158:161], v[190:193], v[82:85]
	v_mfma_f32_16x16x32_bf16 v[74:77], v[166:169], v[190:193], v[74:77]
	v_mfma_f32_16x16x32_bf16 v[70:73], v[158:161], v[198:201], v[70:73]
	v_mfma_f32_16x16x32_bf16 v[62:65], v[166:169], v[198:201], v[62:65]
	s_setprio 0
	s_barrier
	ds_read_b128 v[170:173], v137 offset:49152
	ds_read_b128 v[174:177], v137 offset:50176
	ds_read_b128 v[178:181], v137 offset:51200
	ds_read_b128 v[182:185], v137 offset:52224
	ds_read_b128 v[186:189], v137 offset:53248
	ds_read_b128 v[190:193], v137 offset:54272
	ds_read_b128 v[194:197], v137 offset:55296
	ds_read_b128 v[198:201], v137 offset:56320
	s_mov_b32 m0, s64
	s_add_u32 s100, s12, s38
	s_addc_u32 s101, s13, s39
	global_load_lds_dwordx4 v131, s[100:101]
	s_mov_b32 m0, s61
	s_nop 0
	global_load_lds_dwordx4 v133, s[100:101]
	s_mov_b32 m0, s71
	s_nop 0
	global_load_lds_dwordx4 v131, s[14:15]
	s_mov_b32 m0, s70
	s_nop 0
	global_load_lds_dwordx4 v133, s[14:15]
	s_mov_b32 m0, s59
	s_add_u32 s100, s10, s38
	s_addc_u32 s101, s11, s39
	v_mov_b32_e32 v0, v132
	global_load_lds_dwordx4 v130, s[100:101]
	s_mov_b32 m0, s60
	s_nop 0
	global_load_lds_dwordx4 v132, s[100:101]
	s_waitcnt vmcnt(8)
	s_waitcnt lgkmcnt(0)
	s_barrier
	s_setprio 1
	s_waitcnt lgkmcnt(0)
	v_mfma_f32_16x16x32_bf16 v[66:69], v[138:141], v[170:173], v[66:69]
	v_mfma_f32_16x16x32_bf16 v[58:61], v[146:149], v[170:173], v[58:61]
	v_mfma_f32_16x16x32_bf16 v[54:57], v[138:141], v[178:181], v[54:57]
	v_mfma_f32_16x16x32_bf16 v[46:49], v[146:149], v[178:181], v[46:49]
	v_mfma_f32_16x16x32_bf16 v[38:41], v[138:141], v[186:189], v[38:41]
	v_mfma_f32_16x16x32_bf16 v[30:33], v[146:149], v[186:189], v[30:33]
	v_mfma_f32_16x16x32_bf16 v[22:25], v[138:141], v[194:197], v[22:25]
	v_mfma_f32_16x16x32_bf16 v[14:17], v[146:149], v[194:197], v[14:17]
	v_mfma_f32_16x16x32_bf16 v[66:69], v[142:145], v[174:177], v[66:69]
	v_mfma_f32_16x16x32_bf16 v[58:61], v[150:153], v[174:177], v[58:61]
	v_mfma_f32_16x16x32_bf16 v[54:57], v[142:145], v[182:185], v[54:57]
	v_mfma_f32_16x16x32_bf16 v[46:49], v[150:153], v[182:185], v[46:49]
	v_mfma_f32_16x16x32_bf16 v[38:41], v[142:145], v[190:193], v[38:41]
	v_mfma_f32_16x16x32_bf16 v[30:33], v[150:153], v[190:193], v[30:33]
	v_mfma_f32_16x16x32_bf16 v[22:25], v[142:145], v[198:201], v[22:25]
	v_mfma_f32_16x16x32_bf16 v[14:17], v[150:153], v[198:201], v[14:17]
	s_setprio 0
	s_setprio 1
	v_mfma_f32_16x16x32_bf16 v[50:53], v[154:157], v[170:173], v[50:53]
	v_mfma_f32_16x16x32_bf16 v[42:45], v[162:165], v[170:173], v[42:45]
	v_mfma_f32_16x16x32_bf16 v[34:37], v[154:157], v[178:181], v[34:37]
	v_mfma_f32_16x16x32_bf16 v[26:29], v[162:165], v[178:181], v[26:29]
	v_mfma_f32_16x16x32_bf16 v[18:21], v[154:157], v[186:189], v[18:21]
	v_mfma_f32_16x16x32_bf16 v[10:13], v[162:165], v[186:189], v[10:13]
	v_mfma_f32_16x16x32_bf16 v[6:9], v[154:157], v[194:197], v[6:9]
	v_mfma_f32_16x16x32_bf16 v[2:5], v[162:165], v[194:197], v[2:5]
	v_mfma_f32_16x16x32_bf16 v[50:53], v[158:161], v[174:177], v[50:53]
	v_mfma_f32_16x16x32_bf16 v[42:45], v[166:169], v[174:177], v[42:45]
	v_mfma_f32_16x16x32_bf16 v[34:37], v[158:161], v[182:185], v[34:37]
	v_mfma_f32_16x16x32_bf16 v[26:29], v[166:169], v[182:185], v[26:29]
	v_mfma_f32_16x16x32_bf16 v[18:21], v[158:161], v[190:193], v[18:21]
	v_mfma_f32_16x16x32_bf16 v[10:13], v[166:169], v[190:193], v[10:13]
	v_mfma_f32_16x16x32_bf16 v[6:9], v[158:161], v[198:201], v[6:9]
	v_mfma_f32_16x16x32_bf16 v[2:5], v[166:169], v[198:201], v[2:5]
	s_setprio 0
	s_barrier
	s_andn2_b64 vcc, exec, s[8:9]
	s_mov_b64 s[12:13], -1
	s_mov_b64 s[8:9], 0
	s_mov_b64 s[14:15], 0x100
	s_cbranch_vccz .LBB0_1481
	s_cmpk_lt_u32 s24, 0x100
	s_cbranch_scc0 .LBB0_1484
	s_barrier

.LBB0_1570:
	s_add_u32 s48, s41, s6
	s_addc_u32 s49, s42, s7
	s_add_u32 s8, s48, 0x9800100
	s_addc_u32 s9, s49, 0
	s_add_u32 s10, s43, s6
	s_addc_u32 s11, s46, s7
	s_cmpk_eq_i32 s6, 0x700
	s_cselect_b32 s9, s3, s9
	s_cselect_b32 s8, s2, s8
	s_cselect_b32 s11, s26, s11
	s_cselect_b32 s10, s25, s10
	s_add_i32 s50, 0, 0x10000
	v_add_u32_e32 v0, s50, v169
	s_add_i32 s51, 0, 0x14000
	ds_read_b128 v[172:175], v0
	ds_read_b128 v[176:179], v0 offset:1024
	ds_read_b128 v[180:183], v0 offset:2048
	ds_read_b128 v[184:187], v0 offset:3072
	v_add_u32_e32 v0, s51, v169
	ds_read_b128 v[188:191], v0
	ds_read_b128 v[192:195], v0 offset:1024
	ds_read_b128 v[196:199], v0 offset:2048
	ds_read_b128 v[200:203], v0 offset:3072
	ds_read_b128 v[204:207], v170
	ds_read_b128 v[208:211], v170 offset:1024
	ds_read_b128 v[212:215], v170 offset:2048
	ds_read_b128 v[216:219], v170 offset:3072
	ds_read_b128 v[220:223], v170 offset:4096
	ds_read_b128 v[224:227], v170 offset:5120
	ds_read_b128 v[232:235], v170 offset:6144
	ds_read_b128 v[242:245], v170 offset:7168
	s_mov_b64 s[58:59], 0x9840080
	s_add_u32 s100, s48, s58
	s_addc_u32 s101, s49, s59
	s_add_i32 m0, s17, 0xc000
	s_nop 0
	global_load_lds_dwordx4 v164, s[100:101]
	s_add_i32 m0, s17, 0xe000
	s_nop 0
	global_load_lds_dwordx4 v166, s[100:101]
	s_waitcnt vmcnt(8)
	s_waitcnt lgkmcnt(0)
	s_barrier
	s_setprio 1
	s_waitcnt lgkmcnt(0)
	v_mfma_f32_16x16x32_bf16 v[160:163], v[172:175], v[204:207], v[160:163]
	v_mfma_f32_16x16x32_bf16 v[156:159], v[180:183], v[204:207], v[156:159]
	v_mfma_f32_16x16x32_bf16 v[112:115], v[172:175], v[212:215], v[112:115]
	v_mfma_f32_16x16x32_bf16 v[108:111], v[180:183], v[212:215], v[108:111]
	v_mfma_f32_16x16x32_bf16 v[96:99], v[172:175], v[220:223], v[96:99]
	v_mfma_f32_16x16x32_bf16 v[92:95], v[180:183], v[220:223], v[92:95]
	v_mfma_f32_16x16x32_bf16 v[80:83], v[172:175], v[232:235], v[80:83]
	v_mfma_f32_16x16x32_bf16 v[76:79], v[180:183], v[232:235], v[76:79]
	v_mfma_f32_16x16x32_bf16 v[160:163], v[176:179], v[208:211], v[160:163]
	v_mfma_f32_16x16x32_bf16 v[156:159], v[184:187], v[208:211], v[156:159]
	v_mfma_f32_16x16x32_bf16 v[112:115], v[176:179], v[216:219], v[112:115]
	v_mfma_f32_16x16x32_bf16 v[108:111], v[184:187], v[216:219], v[108:111]
	v_mfma_f32_16x16x32_bf16 v[96:99], v[176:179], v[224:227], v[96:99]
	v_mfma_f32_16x16x32_bf16 v[92:95], v[184:187], v[224:227], v[92:95]
	v_mfma_f32_16x16x32_bf16 v[80:83], v[176:179], v[242:245], v[80:83]
	v_mfma_f32_16x16x32_bf16 v[76:79], v[184:187], v[242:245], v[76:79]
	s_setprio 0
	s_setprio 1
	v_mfma_f32_16x16x32_bf16 v[128:131], v[188:191], v[204:207], v[128:131]
	v_mfma_f32_16x16x32_bf16 v[120:123], v[196:199], v[204:207], v[120:123]
	v_mfma_f32_16x16x32_bf16 v[104:107], v[188:191], v[212:215], v[104:107]
	v_mfma_f32_16x16x32_bf16 v[100:103], v[196:199], v[212:215], v[100:103]
	v_mfma_f32_16x16x32_bf16 v[88:91], v[188:191], v[220:223], v[88:91]
	v_mfma_f32_16x16x32_bf16 v[84:87], v[196:199], v[220:223], v[84:87]
	v_mfma_f32_16x16x32_bf16 v[72:75], v[188:191], v[232:235], v[72:75]
	v_mfma_f32_16x16x32_bf16 v[68:71], v[196:199], v[232:235], v[68:71]
	v_mfma_f32_16x16x32_bf16 v[128:131], v[192:195], v[208:211], v[128:131]
	v_mfma_f32_16x16x32_bf16 v[120:123], v[200:203], v[208:211], v[120:123]
	v_mfma_f32_16x16x32_bf16 v[104:107], v[192:195], v[216:219], v[104:107]
	v_mfma_f32_16x16x32_bf16 v[100:103], v[200:203], v[216:219], v[100:103]
	v_mfma_f32_16x16x32_bf16 v[88:91], v[192:195], v[224:227], v[88:91]
	v_mfma_f32_16x16x32_bf16 v[84:87], v[200:203], v[224:227], v[84:87]
	v_mfma_f32_16x16x32_bf16 v[72:75], v[192:195], v[242:245], v[72:75]
	v_mfma_f32_16x16x32_bf16 v[68:71], v[200:203], v[242:245], v[68:71]
	s_setprio 0
	s_barrier
	s_add_i32 s48, s50, s16
	ds_read_b128 v[204:207], v170 offset:16384
	ds_read_b128 v[208:211], v170 offset:17408
	ds_read_b128 v[212:215], v170 offset:18432
	ds_read_b128 v[216:219], v170 offset:19456
	ds_read_b128 v[220:223], v170 offset:20480
	ds_read_b128 v[224:227], v170 offset:21504
	ds_read_b128 v[232:235], v170 offset:22528
	ds_read_b128 v[242:245], v170 offset:23552
	s_mov_b32 m0, s48
	s_nop 0
	global_load_lds_dwordx4 v167, s[10:11]
	s_add_i32 m0, s48, 0x2000
	s_add_u32 s48, s10, 0x40000
	global_load_lds_dwordx4 v168, s[10:11]
	s_addc_u32 s49, s11, 0
	s_add_i32 s50, s51, s16
	s_mov_b32 m0, s50
	s_nop 0
	global_load_lds_dwordx4 v167, s[48:49]
	s_add_i32 m0, s50, 0x2000
	s_nop 0
	global_load_lds_dwordx4 v168, s[48:49]
	s_mov_b32 m0, s17
	s_nop 0
	global_load_lds_dwordx4 v164, s[8:9]
	s_mov_b32 m0, s22
	s_nop 0
	global_load_lds_dwordx4 v166, s[8:9]
	s_waitcnt vmcnt(8)
	s_waitcnt lgkmcnt(0)
	s_barrier
	s_setprio 1
	s_waitcnt lgkmcnt(0)
	v_mfma_f32_16x16x32_bf16 v[64:67], v[172:175], v[204:207], v[64:67]
	v_mfma_f32_16x16x32_bf16 v[60:63], v[180:183], v[204:207], v[60:63]
	v_mfma_f32_16x16x32_bf16 v[48:51], v[172:175], v[212:215], v[48:51]
	v_mfma_f32_16x16x32_bf16 v[44:47], v[180:183], v[212:215], v[44:47]
	v_mfma_f32_16x16x32_bf16 v[32:35], v[172:175], v[220:223], v[32:35]
	v_mfma_f32_16x16x32_bf16 v[28:31], v[180:183], v[220:223], v[28:31]
	v_mfma_f32_16x16x32_bf16 v[16:19], v[172:175], v[232:235], v[16:19]
	v_mfma_f32_16x16x32_bf16 v[12:15], v[180:183], v[232:235], v[12:15]
	v_mfma_f32_16x16x32_bf16 v[64:67], v[176:179], v[208:211], v[64:67]
	v_mfma_f32_16x16x32_bf16 v[60:63], v[184:187], v[208:211], v[60:63]
	v_mfma_f32_16x16x32_bf16 v[48:51], v[176:179], v[216:219], v[48:51]
	v_mfma_f32_16x16x32_bf16 v[44:47], v[184:187], v[216:219], v[44:47]
	v_mfma_f32_16x16x32_bf16 v[32:35], v[176:179], v[224:227], v[32:35]
	v_mfma_f32_16x16x32_bf16 v[28:31], v[184:187], v[224:227], v[28:31]
	v_mfma_f32_16x16x32_bf16 v[16:19], v[176:179], v[242:245], v[16:19]
	v_mfma_f32_16x16x32_bf16 v[12:15], v[184:187], v[242:245], v[12:15]
	s_setprio 0
	s_setprio 1
	v_mfma_f32_16x16x32_bf16 v[56:59], v[188:191], v[204:207], v[56:59]
	v_mfma_f32_16x16x32_bf16 v[52:55], v[196:199], v[204:207], v[52:55]
	v_mfma_f32_16x16x32_bf16 v[40:43], v[188:191], v[212:215], v[40:43]
	v_mfma_f32_16x16x32_bf16 v[36:39], v[196:199], v[212:215], v[36:39]
	v_mfma_f32_16x16x32_bf16 v[24:27], v[188:191], v[220:223], v[24:27]
	v_mfma_f32_16x16x32_bf16 v[20:23], v[196:199], v[220:223], v[20:23]
	v_mfma_f32_16x16x32_bf16 v[8:11], v[188:191], v[232:235], v[8:11]
	v_mfma_f32_16x16x32_bf16 v[2:5], v[196:199], v[232:235], v[4:7]
	v_mfma_f32_16x16x32_bf16 v[56:59], v[192:195], v[208:211], v[56:59]
	v_mfma_f32_16x16x32_bf16 v[52:55], v[200:203], v[208:211], v[52:55]
	v_mfma_f32_16x16x32_bf16 v[40:43], v[192:195], v[216:219], v[40:43]
	v_mfma_f32_16x16x32_bf16 v[36:39], v[200:203], v[216:219], v[36:39]
	v_mfma_f32_16x16x32_bf16 v[24:27], v[192:195], v[224:227], v[24:27]
	v_mfma_f32_16x16x32_bf16 v[20:23], v[200:203], v[224:227], v[20:23]
	v_mfma_f32_16x16x32_bf16 v[8:11], v[192:195], v[242:245], v[8:11]
	v_mfma_f32_16x16x32_bf16 v[2:5], v[200:203], v[242:245], v[2:5]
	s_setprio 0
	s_barrier
	s_add_i32 s50, 0, 0x18000
	v_add_u32_e32 v0, s50, v169
	s_add_i32 s51, 0, 0x1c000
	ds_read_b128 v[172:175], v0
	ds_read_b128 v[176:179], v0 offset:1024
	ds_read_b128 v[180:183], v0 offset:2048
	ds_read_b128 v[184:187], v0 offset:3072
	v_add_u32_e32 v0, s51, v169
	ds_read_b128 v[188:191], v0
	ds_read_b128 v[192:195], v0 offset:1024
	ds_read_b128 v[196:199], v0 offset:2048
	ds_read_b128 v[200:203], v0 offset:3072
	s_add_u32 s48, s8, 0x40000
	s_mov_b32 m0, s23
	ds_read_b128 v[204:207], v170 offset:32768
	ds_read_b128 v[208:211], v170 offset:33792
	ds_read_b128 v[212:215], v170 offset:34816
	ds_read_b128 v[216:219], v170 offset:35840
	ds_read_b128 v[220:223], v170 offset:36864
	ds_read_b128 v[224:227], v170 offset:37888
	ds_read_b128 v[232:235], v170 offset:38912
	ds_read_b128 v[242:245], v170 offset:39936
	s_addc_u32 s49, s9, 0
	s_nop 0
	global_load_lds_dwordx4 v164, s[48:49]
	s_mov_b32 m0, s24
	s_nop 0
	global_load_lds_dwordx4 v166, s[48:49]
	s_waitcnt vmcnt(8)
	s_waitcnt lgkmcnt(0)
	s_barrier
	s_setprio 1
	s_waitcnt lgkmcnt(0)
	v_mfma_f32_16x16x32_bf16 v[160:163], v[172:175], v[204:207], v[160:163]
	v_mfma_f32_16x16x32_bf16 v[156:159], v[180:183], v[204:207], v[156:159]
	v_mfma_f32_16x16x32_bf16 v[112:115], v[172:175], v[212:215], v[112:115]
	v_mfma_f32_16x16x32_bf16 v[108:111], v[180:183], v[212:215], v[108:111]
	v_mfma_f32_16x16x32_bf16 v[96:99], v[172:175], v[220:223], v[96:99]
	v_mfma_f32_16x16x32_bf16 v[92:95], v[180:183], v[220:223], v[92:95]
	v_mfma_f32_16x16x32_bf16 v[80:83], v[172:175], v[232:235], v[80:83]
	v_mfma_f32_16x16x32_bf16 v[76:79], v[180:183], v[232:235], v[76:79]
	v_mfma_f32_16x16x32_bf16 v[160:163], v[176:179], v[208:211], v[160:163]
	v_mfma_f32_16x16x32_bf16 v[156:159], v[184:187], v[208:211], v[156:159]
	v_mfma_f32_16x16x32_bf16 v[112:115], v[176:179], v[216:219], v[112:115]
	v_mfma_f32_16x16x32_bf16 v[108:111], v[184:187], v[216:219], v[108:111]
	v_mfma_f32_16x16x32_bf16 v[96:99], v[176:179], v[224:227], v[96:99]
	v_mfma_f32_16x16x32_bf16 v[92:95], v[184:187], v[224:227], v[92:95]
	v_mfma_f32_16x16x32_bf16 v[80:83], v[176:179], v[242:245], v[80:83]
	v_mfma_f32_16x16x32_bf16 v[76:79], v[184:187], v[242:245], v[76:79]
	s_setprio 0
	s_setprio 1
	v_mfma_f32_16x16x32_bf16 v[128:131], v[188:191], v[204:207], v[128:131]
	v_mfma_f32_16x16x32_bf16 v[120:123], v[196:199], v[204:207], v[120:123]
	v_mfma_f32_16x16x32_bf16 v[104:107], v[188:191], v[212:215], v[104:107]
	v_mfma_f32_16x16x32_bf16 v[100:103], v[196:199], v[212:215], v[100:103]
	v_mfma_f32_16x16x32_bf16 v[88:91], v[188:191], v[220:223], v[88:91]
	v_mfma_f32_16x16x32_bf16 v[84:87], v[196:199], v[220:223], v[84:87]
	v_mfma_f32_16x16x32_bf16 v[72:75], v[188:191], v[232:235], v[72:75]
	v_mfma_f32_16x16x32_bf16 v[68:71], v[196:199], v[232:235], v[68:71]
	v_mfma_f32_16x16x32_bf16 v[128:131], v[192:195], v[208:211], v[128:131]
	v_mfma_f32_16x16x32_bf16 v[120:123], v[200:203], v[208:211], v[120:123]
	v_mfma_f32_16x16x32_bf16 v[104:107], v[192:195], v[216:219], v[104:107]
	v_mfma_f32_16x16x32_bf16 v[100:103], v[200:203], v[216:219], v[100:103]
	v_mfma_f32_16x16x32_bf16 v[88:91], v[192:195], v[224:227], v[88:91]
	v_mfma_f32_16x16x32_bf16 v[84:87], v[200:203], v[224:227], v[84:87]
	v_mfma_f32_16x16x32_bf16 v[72:75], v[192:195], v[242:245], v[72:75]
	v_mfma_f32_16x16x32_bf16 v[68:71], v[200:203], v[242:245], v[68:71]
	s_setprio 0
	s_barrier
	ds_read_b128 v[204:207], v170 offset:49152
	ds_read_b128 v[208:211], v170 offset:50176
	ds_read_b128 v[212:215], v170 offset:51200
	ds_read_b128 v[216:219], v170 offset:52224
	ds_read_b128 v[220:223], v170 offset:53248
	ds_read_b128 v[224:227], v170 offset:54272
	ds_read_b128 v[232:235], v170 offset:55296
	ds_read_b128 v[242:245], v170 offset:56320
	s_add_i32 s48, s50, s16
	s_add_u32 s100, s10, s38
	s_addc_u32 s101, s11, s39
	s_mov_b32 m0, s48
	s_nop 0
	global_load_lds_dwordx4 v167, s[100:101]
	s_add_i32 m0, s48, 0x2000
	s_nop 0
	s_add_u32 s10, s10, 0x40080
	s_addc_u32 s11, s11, 0
	s_add_i32 s48, s51, s16
	global_load_lds_dwordx4 v168, s[100:101]
	s_mov_b32 m0, s48
	s_nop 0
	global_load_lds_dwordx4 v167, s[10:11]
	s_add_i32 m0, s48, 0x2000
	s_nop 0
	global_load_lds_dwordx4 v168, s[10:11]
	s_mov_b32 m0, s37
	s_add_u32 s100, s8, s38
	s_addc_u32 s101, s9, s39
	v_mov_b32_e32 v0, v166
	global_load_lds_dwordx4 v164, s[100:101]
	s_mov_b32 m0, s40
	s_nop 0
	global_load_lds_dwordx4 v166, s[100:101]
	s_waitcnt vmcnt(8)
	s_waitcnt lgkmcnt(0)
	s_barrier
	s_setprio 1
	s_waitcnt lgkmcnt(0)
	v_mfma_f32_16x16x32_bf16 v[64:67], v[172:175], v[204:207], v[64:67]
	v_mfma_f32_16x16x32_bf16 v[60:63], v[180:183], v[204:207], v[60:63]
	v_mfma_f32_16x16x32_bf16 v[48:51], v[172:175], v[212:215], v[48:51]
	v_mfma_f32_16x16x32_bf16 v[44:47], v[180:183], v[212:215], v[44:47]
	v_mfma_f32_16x16x32_bf16 v[32:35], v[172:175], v[220:223], v[32:35]
	v_mfma_f32_16x16x32_bf16 v[28:31], v[180:183], v[220:223], v[28:31]
	v_mfma_f32_16x16x32_bf16 v[16:19], v[172:175], v[232:235], v[16:19]
	v_mfma_f32_16x16x32_bf16 v[12:15], v[180:183], v[232:235], v[12:15]
	v_mfma_f32_16x16x32_bf16 v[64:67], v[176:179], v[208:211], v[64:67]
	v_mfma_f32_16x16x32_bf16 v[60:63], v[184:187], v[208:211], v[60:63]
	v_mfma_f32_16x16x32_bf16 v[48:51], v[176:179], v[216:219], v[48:51]
	v_mfma_f32_16x16x32_bf16 v[44:47], v[184:187], v[216:219], v[44:47]
	v_mfma_f32_16x16x32_bf16 v[32:35], v[176:179], v[224:227], v[32:35]
	v_mfma_f32_16x16x32_bf16 v[28:31], v[184:187], v[224:227], v[28:31]
	v_mfma_f32_16x16x32_bf16 v[16:19], v[176:179], v[242:245], v[16:19]
	v_mfma_f32_16x16x32_bf16 v[12:15], v[184:187], v[242:245], v[12:15]
	s_setprio 0
	s_setprio 1
	v_mfma_f32_16x16x32_bf16 v[56:59], v[188:191], v[204:207], v[56:59]
	v_mfma_f32_16x16x32_bf16 v[52:55], v[196:199], v[204:207], v[52:55]
	v_mfma_f32_16x16x32_bf16 v[40:43], v[188:191], v[212:215], v[40:43]
	v_mfma_f32_16x16x32_bf16 v[36:39], v[196:199], v[212:215], v[36:39]
	v_mfma_f32_16x16x32_bf16 v[24:27], v[188:191], v[220:223], v[24:27]
	v_mfma_f32_16x16x32_bf16 v[20:23], v[196:199], v[220:223], v[20:23]
	v_mfma_f32_16x16x32_bf16 v[6:9], v[188:191], v[232:235], v[8:11]
	v_mfma_f32_16x16x32_bf16 v[2:5], v[196:199], v[232:235], v[2:5]
	v_mfma_f32_16x16x32_bf16 v[56:59], v[192:195], v[208:211], v[56:59]
	v_mfma_f32_16x16x32_bf16 v[52:55], v[200:203], v[208:211], v[52:55]
	v_mfma_f32_16x16x32_bf16 v[40:43], v[192:195], v[216:219], v[40:43]
	v_mfma_f32_16x16x32_bf16 v[36:39], v[200:203], v[216:219], v[36:39]
	v_mfma_f32_16x16x32_bf16 v[24:27], v[192:195], v[224:227], v[24:27]
	v_mfma_f32_16x16x32_bf16 v[20:23], v[200:203], v[224:227], v[20:23]
	v_mfma_f32_16x16x32_bf16 v[8:11], v[192:195], v[242:245], v[6:9]
	v_mfma_f32_16x16x32_bf16 v[4:7], v[200:203], v[242:245], v[2:5]
	s_setprio 0
	s_barrier
	s_add_i32 s47, s47, 2
	s_add_u32 s6, s6, 0x100
	s_addc_u32 s7, s7, 0
	s_cmp_gt_u32 s47, 13
	s_cbranch_scc1 .LBB0_1573

.LBB0_1681:
	s_add_u32 s48, s6, s2
	s_addc_u32 s49, s7, s3
	s_add_u32 s10, s48, 0x100
	s_addc_u32 s11, s49, 0
	s_add_u32 s12, s37, s2
	s_addc_u32 s13, s40, s3
	s_add_i32 s47, 0, 0x10000
	s_cmp_eq_u32 s46, 12
	s_cselect_b32 s11, s7, s11
	s_cselect_b32 s10, s6, s10
	v_add_u32_e32 v0, s47, v136
	s_cselect_b32 s13, s9, s13
	s_cselect_b32 s12, s8, s12
	s_add_i32 s50, 0, 0x14000
	ds_read_b128 v[138:141], v0
	ds_read_b128 v[142:145], v0 offset:1024
	ds_read_b128 v[146:149], v0 offset:2048
	ds_read_b128 v[150:153], v0 offset:3072
	v_add_u32_e32 v0, s50, v136
	ds_read_b128 v[154:157], v0
	ds_read_b128 v[158:161], v0 offset:1024
	ds_read_b128 v[162:165], v0 offset:2048
	ds_read_b128 v[166:169], v0 offset:3072
	ds_read_b128 v[170:173], v137
	ds_read_b128 v[174:177], v137 offset:1024
	ds_read_b128 v[178:181], v137 offset:2048
	ds_read_b128 v[182:185], v137 offset:3072
	ds_read_b128 v[186:189], v137 offset:4096
	ds_read_b128 v[190:193], v137 offset:5120
	ds_read_b128 v[194:197], v137 offset:6144
	ds_read_b128 v[198:201], v137 offset:7168
	s_add_i32 m0, s23, 0xc000
	s_add_u32 s100, s48, s56
	s_addc_u32 s101, s49, s57
	global_load_lds_dwordx4 v130, s[100:101]
	s_add_i32 m0, s23, 0xe000
	s_nop 0
	global_load_lds_dwordx4 v132, s[100:101]
	s_waitcnt vmcnt(8)
	s_waitcnt lgkmcnt(0)
	s_barrier
	s_setprio 1
	s_waitcnt lgkmcnt(0)
	v_mfma_f32_16x16x32_bf16 v[126:129], v[138:141], v[170:173], v[126:129]
	v_mfma_f32_16x16x32_bf16 v[122:125], v[146:149], v[170:173], v[122:125]
	v_mfma_f32_16x16x32_bf16 v[110:113], v[138:141], v[178:181], v[110:113]
	v_mfma_f32_16x16x32_bf16 v[106:109], v[146:149], v[178:181], v[106:109]
	v_mfma_f32_16x16x32_bf16 v[94:97], v[138:141], v[186:189], v[94:97]
	v_mfma_f32_16x16x32_bf16 v[90:93], v[146:149], v[186:189], v[90:93]
	v_mfma_f32_16x16x32_bf16 v[78:81], v[138:141], v[194:197], v[78:81]
	v_mfma_f32_16x16x32_bf16 v[74:77], v[146:149], v[194:197], v[74:77]
	v_mfma_f32_16x16x32_bf16 v[126:129], v[142:145], v[174:177], v[126:129]
	v_mfma_f32_16x16x32_bf16 v[122:125], v[150:153], v[174:177], v[122:125]
	v_mfma_f32_16x16x32_bf16 v[110:113], v[142:145], v[182:185], v[110:113]
	v_mfma_f32_16x16x32_bf16 v[106:109], v[150:153], v[182:185], v[106:109]
	v_mfma_f32_16x16x32_bf16 v[94:97], v[142:145], v[190:193], v[94:97]
	v_mfma_f32_16x16x32_bf16 v[90:93], v[150:153], v[190:193], v[90:93]
	v_mfma_f32_16x16x32_bf16 v[78:81], v[142:145], v[198:201], v[78:81]
	v_mfma_f32_16x16x32_bf16 v[74:77], v[150:153], v[198:201], v[74:77]
	s_setprio 0
	s_setprio 1
	v_mfma_f32_16x16x32_bf16 v[118:121], v[154:157], v[170:173], v[118:121]
	v_mfma_f32_16x16x32_bf16 v[114:117], v[162:165], v[170:173], v[114:117]
	v_mfma_f32_16x16x32_bf16 v[102:105], v[154:157], v[178:181], v[102:105]
	v_mfma_f32_16x16x32_bf16 v[98:101], v[162:165], v[178:181], v[98:101]
	v_mfma_f32_16x16x32_bf16 v[86:89], v[154:157], v[186:189], v[86:89]
	v_mfma_f32_16x16x32_bf16 v[82:85], v[162:165], v[186:189], v[82:85]
	v_mfma_f32_16x16x32_bf16 v[70:73], v[154:157], v[194:197], v[70:73]
	v_mfma_f32_16x16x32_bf16 v[66:69], v[162:165], v[194:197], v[66:69]
	v_mfma_f32_16x16x32_bf16 v[118:121], v[158:161], v[174:177], v[118:121]
	v_mfma_f32_16x16x32_bf16 v[114:117], v[166:169], v[174:177], v[114:117]
	v_mfma_f32_16x16x32_bf16 v[102:105], v[158:161], v[182:185], v[102:105]
	v_mfma_f32_16x16x32_bf16 v[98:101], v[166:169], v[182:185], v[98:101]
	v_mfma_f32_16x16x32_bf16 v[86:89], v[158:161], v[190:193], v[86:89]
	v_mfma_f32_16x16x32_bf16 v[82:85], v[166:169], v[190:193], v[82:85]
	v_mfma_f32_16x16x32_bf16 v[70:73], v[158:161], v[198:201], v[70:73]
	v_mfma_f32_16x16x32_bf16 v[66:69], v[166:169], v[198:201], v[66:69]
	s_setprio 0
	s_barrier
	s_add_i32 s47, s47, s22
	ds_read_b128 v[170:173], v137 offset:16384
	ds_read_b128 v[174:177], v137 offset:17408
	ds_read_b128 v[178:181], v137 offset:18432
	ds_read_b128 v[182:185], v137 offset:19456
	ds_read_b128 v[186:189], v137 offset:20480
	ds_read_b128 v[190:193], v137 offset:21504
	ds_read_b128 v[194:197], v137 offset:22528
	ds_read_b128 v[198:201], v137 offset:23552
	s_mov_b32 m0, s47
	s_nop 0
	global_load_lds_dwordx4 v134, s[12:13]
	s_add_i32 m0, s47, 0x2000
	s_add_u32 s48, s12, 0x40000
	global_load_lds_dwordx4 v135, s[12:13]
	s_addc_u32 s49, s13, 0
	s_add_i32 s47, s50, s22
	s_mov_b32 m0, s47
	s_nop 0
	global_load_lds_dwordx4 v134, s[48:49]
	s_add_i32 m0, s47, 0x2000
	s_nop 0
	global_load_lds_dwordx4 v135, s[48:49]
	s_mov_b32 m0, s23
	s_nop 0
	global_load_lds_dwordx4 v130, s[10:11]
	s_mov_b32 m0, s24
	s_nop 0
	global_load_lds_dwordx4 v132, s[10:11]
	s_waitcnt vmcnt(8)
	s_waitcnt lgkmcnt(0)
	s_barrier
	s_setprio 1
	s_waitcnt lgkmcnt(0)
	v_mfma_f32_16x16x32_bf16 v[62:65], v[138:141], v[170:173], v[62:65]
	v_mfma_f32_16x16x32_bf16 v[58:61], v[146:149], v[170:173], v[58:61]
	v_mfma_f32_16x16x32_bf16 v[46:49], v[138:141], v[178:181], v[46:49]
	v_mfma_f32_16x16x32_bf16 v[42:45], v[146:149], v[178:181], v[42:45]
	v_mfma_f32_16x16x32_bf16 v[30:33], v[138:141], v[186:189], v[30:33]
	v_mfma_f32_16x16x32_bf16 v[26:29], v[146:149], v[186:189], v[26:29]
	v_mfma_f32_16x16x32_bf16 v[14:17], v[138:141], v[194:197], v[14:17]
	v_mfma_f32_16x16x32_bf16 v[10:13], v[146:149], v[194:197], v[10:13]
	v_mfma_f32_16x16x32_bf16 v[62:65], v[142:145], v[174:177], v[62:65]
	v_mfma_f32_16x16x32_bf16 v[58:61], v[150:153], v[174:177], v[58:61]
	v_mfma_f32_16x16x32_bf16 v[46:49], v[142:145], v[182:185], v[46:49]
	v_mfma_f32_16x16x32_bf16 v[42:45], v[150:153], v[182:185], v[42:45]
	v_mfma_f32_16x16x32_bf16 v[30:33], v[142:145], v[190:193], v[30:33]
	v_mfma_f32_16x16x32_bf16 v[26:29], v[150:153], v[190:193], v[26:29]
	v_mfma_f32_16x16x32_bf16 v[14:17], v[142:145], v[198:201], v[14:17]
	v_mfma_f32_16x16x32_bf16 v[10:13], v[150:153], v[198:201], v[10:13]
	s_setprio 0
	s_setprio 1
	v_mfma_f32_16x16x32_bf16 v[54:57], v[154:157], v[170:173], v[54:57]
	v_mfma_f32_16x16x32_bf16 v[50:53], v[162:165], v[170:173], v[50:53]
	v_mfma_f32_16x16x32_bf16 v[38:41], v[154:157], v[178:181], v[38:41]
	v_mfma_f32_16x16x32_bf16 v[34:37], v[162:165], v[178:181], v[34:37]
	v_mfma_f32_16x16x32_bf16 v[22:25], v[154:157], v[186:189], v[22:25]
	v_mfma_f32_16x16x32_bf16 v[18:21], v[162:165], v[186:189], v[18:21]
	v_mfma_f32_16x16x32_bf16 v[6:9], v[154:157], v[194:197], v[6:9]
	v_mfma_f32_16x16x32_bf16 v[2:5], v[162:165], v[194:197], v[2:5]
	v_mfma_f32_16x16x32_bf16 v[54:57], v[158:161], v[174:177], v[54:57]
	v_mfma_f32_16x16x32_bf16 v[50:53], v[166:169], v[174:177], v[50:53]
	v_mfma_f32_16x16x32_bf16 v[38:41], v[158:161], v[182:185], v[38:41]
	v_mfma_f32_16x16x32_bf16 v[34:37], v[166:169], v[182:185], v[34:37]
	v_mfma_f32_16x16x32_bf16 v[22:25], v[158:161], v[190:193], v[22:25]
	v_mfma_f32_16x16x32_bf16 v[18:21], v[166:169], v[190:193], v[18:21]
	v_mfma_f32_16x16x32_bf16 v[6:9], v[158:161], v[198:201], v[6:9]
	v_mfma_f32_16x16x32_bf16 v[2:5], v[166:169], v[198:201], v[2:5]
	s_setprio 0
	s_barrier
	s_add_i32 s47, 0, 0x18000
	v_add_u32_e32 v0, s47, v136
	s_add_i32 s50, 0, 0x1c000
	ds_read_b128 v[138:141], v0
	ds_read_b128 v[142:145], v0 offset:1024
	ds_read_b128 v[146:149], v0 offset:2048
	ds_read_b128 v[150:153], v0 offset:3072
	v_add_u32_e32 v0, s50, v136
	ds_read_b128 v[154:157], v0
	ds_read_b128 v[158:161], v0 offset:1024
	ds_read_b128 v[162:165], v0 offset:2048
	ds_read_b128 v[166:169], v0 offset:3072
	s_add_u32 s48, s10, 0x40000
	s_mov_b32 m0, s25
	ds_read_b128 v[170:173], v137 offset:32768
	ds_read_b128 v[174:177], v137 offset:33792
	ds_read_b128 v[178:181], v137 offset:34816
	ds_read_b128 v[182:185], v137 offset:35840
	ds_read_b128 v[186:189], v137 offset:36864
	ds_read_b128 v[190:193], v137 offset:37888
	ds_read_b128 v[194:197], v137 offset:38912
	ds_read_b128 v[198:201], v137 offset:39936
	s_addc_u32 s49, s11, 0
	s_nop 0
	global_load_lds_dwordx4 v130, s[48:49]
	s_mov_b32 m0, s26
	s_nop 0
	global_load_lds_dwordx4 v132, s[48:49]
	s_waitcnt vmcnt(8)
	s_waitcnt lgkmcnt(0)
	s_barrier
	s_setprio 1
	s_waitcnt lgkmcnt(0)
	v_mfma_f32_16x16x32_bf16 v[126:129], v[138:141], v[170:173], v[126:129]
	v_mfma_f32_16x16x32_bf16 v[122:125], v[146:149], v[170:173], v[122:125]
	v_mfma_f32_16x16x32_bf16 v[110:113], v[138:141], v[178:181], v[110:113]
	v_mfma_f32_16x16x32_bf16 v[106:109], v[146:149], v[178:181], v[106:109]
	v_mfma_f32_16x16x32_bf16 v[94:97], v[138:141], v[186:189], v[94:97]
	v_mfma_f32_16x16x32_bf16 v[90:93], v[146:149], v[186:189], v[90:93]
	v_mfma_f32_16x16x32_bf16 v[78:81], v[138:141], v[194:197], v[78:81]
	v_mfma_f32_16x16x32_bf16 v[74:77], v[146:149], v[194:197], v[74:77]
	v_mfma_f32_16x16x32_bf16 v[126:129], v[142:145], v[174:177], v[126:129]
	v_mfma_f32_16x16x32_bf16 v[122:125], v[150:153], v[174:177], v[122:125]
	v_mfma_f32_16x16x32_bf16 v[110:113], v[142:145], v[182:185], v[110:113]
	v_mfma_f32_16x16x32_bf16 v[106:109], v[150:153], v[182:185], v[106:109]
	v_mfma_f32_16x16x32_bf16 v[94:97], v[142:145], v[190:193], v[94:97]
	v_mfma_f32_16x16x32_bf16 v[90:93], v[150:153], v[190:193], v[90:93]
	v_mfma_f32_16x16x32_bf16 v[78:81], v[142:145], v[198:201], v[78:81]
	v_mfma_f32_16x16x32_bf16 v[74:77], v[150:153], v[198:201], v[74:77]
	s_setprio 0
	s_setprio 1
	v_mfma_f32_16x16x32_bf16 v[118:121], v[154:157], v[170:173], v[118:121]
	v_mfma_f32_16x16x32_bf16 v[114:117], v[162:165], v[170:173], v[114:117]
	v_mfma_f32_16x16x32_bf16 v[102:105], v[154:157], v[178:181], v[102:105]
	v_mfma_f32_16x16x32_bf16 v[98:101], v[162:165], v[178:181], v[98:101]
	v_mfma_f32_16x16x32_bf16 v[86:89], v[154:157], v[186:189], v[86:89]
	v_mfma_f32_16x16x32_bf16 v[82:85], v[162:165], v[186:189], v[82:85]
	v_mfma_f32_16x16x32_bf16 v[70:73], v[154:157], v[194:197], v[70:73]
	v_mfma_f32_16x16x32_bf16 v[66:69], v[162:165], v[194:197], v[66:69]
	v_mfma_f32_16x16x32_bf16 v[118:121], v[158:161], v[174:177], v[118:121]
	v_mfma_f32_16x16x32_bf16 v[114:117], v[166:169], v[174:177], v[114:117]
	v_mfma_f32_16x16x32_bf16 v[102:105], v[158:161], v[182:185], v[102:105]
	v_mfma_f32_16x16x32_bf16 v[98:101], v[166:169], v[182:185], v[98:101]
	v_mfma_f32_16x16x32_bf16 v[86:89], v[158:161], v[190:193], v[86:89]
	v_mfma_f32_16x16x32_bf16 v[82:85], v[166:169], v[190:193], v[82:85]
	v_mfma_f32_16x16x32_bf16 v[70:73], v[158:161], v[198:201], v[70:73]
	v_mfma_f32_16x16x32_bf16 v[66:69], v[166:169], v[198:201], v[66:69]
	s_setprio 0
	s_barrier
	ds_read_b128 v[170:173], v137 offset:49152
	ds_read_b128 v[174:177], v137 offset:50176
	ds_read_b128 v[178:181], v137 offset:51200
	ds_read_b128 v[182:185], v137 offset:52224
	ds_read_b128 v[186:189], v137 offset:53248
	ds_read_b128 v[190:193], v137 offset:54272
	ds_read_b128 v[194:197], v137 offset:55296
	ds_read_b128 v[198:201], v137 offset:56320
	s_add_i32 s47, s47, s22
	s_add_u32 s100, s12, s38
	s_addc_u32 s101, s13, s39
	s_mov_b32 m0, s47
	s_nop 0
	global_load_lds_dwordx4 v134, s[100:101]
	s_add_i32 m0, s47, 0x2000
	s_nop 0
	s_add_u32 s12, s12, 0x40080
	s_addc_u32 s13, s13, 0
	s_add_i32 s47, s50, s22
	global_load_lds_dwordx4 v135, s[100:101]
	s_mov_b32 m0, s47
	s_nop 0
	global_load_lds_dwordx4 v134, s[12:13]
	s_add_i32 m0, s47, 0x2000
	s_nop 0
	global_load_lds_dwordx4 v135, s[12:13]
	s_mov_b32 m0, s42
	s_add_u32 s100, s10, s38
	s_addc_u32 s101, s11, s39
	v_mov_b32_e32 v0, v132
	global_load_lds_dwordx4 v130, s[100:101]
	s_mov_b32 m0, s43
	s_nop 0
	global_load_lds_dwordx4 v132, s[100:101]
	s_waitcnt vmcnt(8)
	s_waitcnt lgkmcnt(0)
	s_barrier
	s_setprio 1
	s_waitcnt lgkmcnt(0)
	v_mfma_f32_16x16x32_bf16 v[62:65], v[138:141], v[170:173], v[62:65]
	v_mfma_f32_16x16x32_bf16 v[58:61], v[146:149], v[170:173], v[58:61]
	v_mfma_f32_16x16x32_bf16 v[46:49], v[138:141], v[178:181], v[46:49]
	v_mfma_f32_16x16x32_bf16 v[42:45], v[146:149], v[178:181], v[42:45]
	v_mfma_f32_16x16x32_bf16 v[30:33], v[138:141], v[186:189], v[30:33]
	v_mfma_f32_16x16x32_bf16 v[26:29], v[146:149], v[186:189], v[26:29]
	v_mfma_f32_16x16x32_bf16 v[14:17], v[138:141], v[194:197], v[14:17]
	v_mfma_f32_16x16x32_bf16 v[10:13], v[146:149], v[194:197], v[10:13]
	v_mfma_f32_16x16x32_bf16 v[62:65], v[142:145], v[174:177], v[62:65]
	v_mfma_f32_16x16x32_bf16 v[58:61], v[150:153], v[174:177], v[58:61]
	v_mfma_f32_16x16x32_bf16 v[46:49], v[142:145], v[182:185], v[46:49]
	v_mfma_f32_16x16x32_bf16 v[42:45], v[150:153], v[182:185], v[42:45]
	v_mfma_f32_16x16x32_bf16 v[30:33], v[142:145], v[190:193], v[30:33]
	v_mfma_f32_16x16x32_bf16 v[26:29], v[150:153], v[190:193], v[26:29]
	v_mfma_f32_16x16x32_bf16 v[14:17], v[142:145], v[198:201], v[14:17]
	v_mfma_f32_16x16x32_bf16 v[10:13], v[150:153], v[198:201], v[10:13]
	s_setprio 0
	s_setprio 1
	v_mfma_f32_16x16x32_bf16 v[54:57], v[154:157], v[170:173], v[54:57]
	v_mfma_f32_16x16x32_bf16 v[50:53], v[162:165], v[170:173], v[50:53]
	v_mfma_f32_16x16x32_bf16 v[38:41], v[154:157], v[178:181], v[38:41]
	v_mfma_f32_16x16x32_bf16 v[34:37], v[162:165], v[178:181], v[34:37]
	v_mfma_f32_16x16x32_bf16 v[22:25], v[154:157], v[186:189], v[22:25]
	v_mfma_f32_16x16x32_bf16 v[18:21], v[162:165], v[186:189], v[18:21]
	v_mfma_f32_16x16x32_bf16 v[6:9], v[154:157], v[194:197], v[6:9]
	v_mfma_f32_16x16x32_bf16 v[2:5], v[162:165], v[194:197], v[2:5]
	v_mfma_f32_16x16x32_bf16 v[54:57], v[158:161], v[174:177], v[54:57]
	v_mfma_f32_16x16x32_bf16 v[50:53], v[166:169], v[174:177], v[50:53]
	v_mfma_f32_16x16x32_bf16 v[38:41], v[158:161], v[182:185], v[38:41]
	v_mfma_f32_16x16x32_bf16 v[34:37], v[166:169], v[182:185], v[34:37]
	v_mfma_f32_16x16x32_bf16 v[22:25], v[158:161], v[190:193], v[22:25]
	v_mfma_f32_16x16x32_bf16 v[18:21], v[166:169], v[190:193], v[18:21]
	v_mfma_f32_16x16x32_bf16 v[6:9], v[158:161], v[198:201], v[6:9]
	v_mfma_f32_16x16x32_bf16 v[2:5], v[166:169], v[198:201], v[2:5]
	s_setprio 0
	s_barrier
	s_add_i32 s46, s46, 2
	s_add_u32 s2, s2, 0x100
	s_addc_u32 s3, s3, 0
	s_cmp_gt_u32 s46, 13
	s_cbranch_scc0 .LBB0_1681
	s_cmpk_lt_u32 s17, 0x100
	s_cbranch_scc0 .LBB0_1684
	s_barrier

.LBB0_1807:
	s_add_u32 s68, s4, s14
	s_addc_u32 s69, s5, s15
	s_add_u32 s16, s68, 0x100
	s_addc_u32 s17, s69, 0
	s_add_u32 s22, s50, s14
	s_addc_u32 s23, s51, s15
	s_add_i32 s67, 0, 0x10000
	s_cmp_eq_u32 s66, 12
	s_cselect_b32 s17, s5, s17
	s_cselect_b32 s16, s4, s16
	v_add_u32_e32 v0, s67, v126
	s_cselect_b32 s23, s13, s23
	s_cselect_b32 s22, s12, s22
	s_add_i32 s70, 0, 0x14000
	ds_read_b128 v[128:131], v0
	ds_read_b128 v[142:145], v0 offset:1024
	ds_read_b128 v[146:149], v0 offset:2048
	ds_read_b128 v[150:153], v0 offset:3072
	v_add_u32_e32 v0, s70, v126
	ds_read_b128 v[154:157], v0
	ds_read_b128 v[160:163], v0 offset:1024
	ds_read_b128 v[164:167], v0 offset:2048
	ds_read_b128 v[168:171], v0 offset:3072
	ds_read_b128 v[172:175], v127
	ds_read_b128 v[176:179], v127 offset:1024
	ds_read_b128 v[180:183], v127 offset:2048
	ds_read_b128 v[184:187], v127 offset:3072
	ds_read_b128 v[188:191], v127 offset:4096
	ds_read_b128 v[192:195], v127 offset:5120
	ds_read_b128 v[196:199], v127 offset:6144
	ds_read_b128 v[200:203], v127 offset:7168
	s_add_i32 m0, s43, 0xc000
	s_add_u32 s100, s68, s56
	s_addc_u32 s101, s69, s57
	global_load_lds_dwordx4 v122, s[100:101]
	s_add_i32 m0, s43, 0xe000
	s_nop 0
	global_load_lds_dwordx4 v123, s[100:101]
	s_waitcnt vmcnt(8)
	s_waitcnt lgkmcnt(0)
	s_barrier
	s_setprio 1
	s_waitcnt lgkmcnt(0)
	v_mfma_f32_16x16x32_bf16 v[138:141], v[128:131], v[172:175], v[138:141]
	v_mfma_f32_16x16x32_bf16 v[132:135], v[146:149], v[172:175], v[134:137]
	v_mfma_f32_16x16x32_bf16 v[110:113], v[128:131], v[180:183], v[110:113]
	v_mfma_f32_16x16x32_bf16 v[106:109], v[146:149], v[180:183], v[106:109]
	v_mfma_f32_16x16x32_bf16 v[94:97], v[128:131], v[188:191], v[94:97]
	v_mfma_f32_16x16x32_bf16 v[90:93], v[146:149], v[188:191], v[90:93]
	v_mfma_f32_16x16x32_bf16 v[78:81], v[128:131], v[196:199], v[78:81]
	v_mfma_f32_16x16x32_bf16 v[74:77], v[146:149], v[196:199], v[74:77]
	v_mfma_f32_16x16x32_bf16 v[138:141], v[142:145], v[176:179], v[138:141]
	v_mfma_f32_16x16x32_bf16 v[132:135], v[150:153], v[176:179], v[132:135]
	v_mfma_f32_16x16x32_bf16 v[110:113], v[142:145], v[184:187], v[110:113]
	v_mfma_f32_16x16x32_bf16 v[106:109], v[150:153], v[184:187], v[106:109]
	v_mfma_f32_16x16x32_bf16 v[94:97], v[142:145], v[192:195], v[94:97]
	v_mfma_f32_16x16x32_bf16 v[90:93], v[150:153], v[192:195], v[90:93]
	v_mfma_f32_16x16x32_bf16 v[78:81], v[142:145], v[200:203], v[78:81]
	v_mfma_f32_16x16x32_bf16 v[74:77], v[150:153], v[200:203], v[74:77]
	s_setprio 0
	s_setprio 1
	v_mfma_f32_16x16x32_bf16 v[118:121], v[154:157], v[172:175], v[118:121]
	v_mfma_f32_16x16x32_bf16 v[114:117], v[164:167], v[172:175], v[114:117]
	v_mfma_f32_16x16x32_bf16 v[102:105], v[154:157], v[180:183], v[102:105]
	v_mfma_f32_16x16x32_bf16 v[98:101], v[164:167], v[180:183], v[98:101]
	v_mfma_f32_16x16x32_bf16 v[86:89], v[154:157], v[188:191], v[86:89]
	v_mfma_f32_16x16x32_bf16 v[82:85], v[164:167], v[188:191], v[82:85]
	v_mfma_f32_16x16x32_bf16 v[70:73], v[154:157], v[196:199], v[70:73]
	v_mfma_f32_16x16x32_bf16 v[66:69], v[164:167], v[196:199], v[66:69]
	v_mfma_f32_16x16x32_bf16 v[118:121], v[160:163], v[176:179], v[118:121]
	v_mfma_f32_16x16x32_bf16 v[114:117], v[168:171], v[176:179], v[114:117]
	v_mfma_f32_16x16x32_bf16 v[102:105], v[160:163], v[184:187], v[102:105]
	v_mfma_f32_16x16x32_bf16 v[98:101], v[168:171], v[184:187], v[98:101]
	v_mfma_f32_16x16x32_bf16 v[86:89], v[160:163], v[192:195], v[86:89]
	v_mfma_f32_16x16x32_bf16 v[82:85], v[168:171], v[192:195], v[82:85]
	v_mfma_f32_16x16x32_bf16 v[70:73], v[160:163], v[200:203], v[70:73]
	v_mfma_f32_16x16x32_bf16 v[66:69], v[168:171], v[200:203], v[66:69]
	s_setprio 0
	s_barrier
	s_add_i32 s67, s67, s42
	ds_read_b128 v[172:175], v127 offset:16384
	ds_read_b128 v[176:179], v127 offset:17408
	ds_read_b128 v[180:183], v127 offset:18432
	ds_read_b128 v[184:187], v127 offset:19456
	ds_read_b128 v[188:191], v127 offset:20480
	ds_read_b128 v[192:195], v127 offset:21504
	ds_read_b128 v[196:199], v127 offset:22528
	ds_read_b128 v[200:203], v127 offset:23552
	s_mov_b32 m0, s67
	s_nop 0
	global_load_lds_dwordx4 v124, s[22:23]
	s_add_i32 m0, s67, 0x2000
	s_add_u32 s68, s22, 0x40000
	global_load_lds_dwordx4 v125, s[22:23]
	s_addc_u32 s69, s23, 0
	s_add_i32 s67, s70, s42
	s_mov_b32 m0, s67
	s_nop 0
	global_load_lds_dwordx4 v124, s[68:69]
	s_add_i32 m0, s67, 0x2000
	s_nop 0
	global_load_lds_dwordx4 v125, s[68:69]
	s_mov_b32 m0, s43
	s_nop 0
	global_load_lds_dwordx4 v122, s[16:17]
	s_mov_b32 m0, s46
	s_nop 0
	global_load_lds_dwordx4 v123, s[16:17]
	s_waitcnt vmcnt(8)
	s_waitcnt lgkmcnt(0)
	s_barrier
	s_setprio 1
	s_waitcnt lgkmcnt(0)
	v_mfma_f32_16x16x32_bf16 v[62:65], v[128:131], v[172:175], v[62:65]
	v_mfma_f32_16x16x32_bf16 v[58:61], v[146:149], v[172:175], v[58:61]
	v_mfma_f32_16x16x32_bf16 v[46:49], v[128:131], v[180:183], v[46:49]
	v_mfma_f32_16x16x32_bf16 v[42:45], v[146:149], v[180:183], v[42:45]
	v_mfma_f32_16x16x32_bf16 v[30:33], v[128:131], v[188:191], v[30:33]
	v_mfma_f32_16x16x32_bf16 v[26:29], v[146:149], v[188:191], v[26:29]
	v_mfma_f32_16x16x32_bf16 v[14:17], v[128:131], v[196:199], v[14:17]
	v_mfma_f32_16x16x32_bf16 v[10:13], v[146:149], v[196:199], v[10:13]
	v_mfma_f32_16x16x32_bf16 v[62:65], v[142:145], v[176:179], v[62:65]
	v_mfma_f32_16x16x32_bf16 v[58:61], v[150:153], v[176:179], v[58:61]
	v_mfma_f32_16x16x32_bf16 v[46:49], v[142:145], v[184:187], v[46:49]
	v_mfma_f32_16x16x32_bf16 v[42:45], v[150:153], v[184:187], v[42:45]
	v_mfma_f32_16x16x32_bf16 v[30:33], v[142:145], v[192:195], v[30:33]
	v_mfma_f32_16x16x32_bf16 v[26:29], v[150:153], v[192:195], v[26:29]
	v_mfma_f32_16x16x32_bf16 v[14:17], v[142:145], v[200:203], v[14:17]
	v_mfma_f32_16x16x32_bf16 v[10:13], v[150:153], v[200:203], v[10:13]
	s_setprio 0
	s_setprio 1
	v_mfma_f32_16x16x32_bf16 v[54:57], v[154:157], v[172:175], v[54:57]
	v_mfma_f32_16x16x32_bf16 v[50:53], v[164:167], v[172:175], v[50:53]
	v_mfma_f32_16x16x32_bf16 v[38:41], v[154:157], v[180:183], v[38:41]
	v_mfma_f32_16x16x32_bf16 v[34:37], v[164:167], v[180:183], v[34:37]
	v_mfma_f32_16x16x32_bf16 v[22:25], v[154:157], v[188:191], v[22:25]
	v_mfma_f32_16x16x32_bf16 v[18:21], v[164:167], v[188:191], v[18:21]
	v_mfma_f32_16x16x32_bf16 v[6:9], v[154:157], v[196:199], v[6:9]
	v_mfma_f32_16x16x32_bf16 v[2:5], v[164:167], v[196:199], v[2:5]
	v_mfma_f32_16x16x32_bf16 v[54:57], v[160:163], v[176:179], v[54:57]
	v_mfma_f32_16x16x32_bf16 v[50:53], v[168:171], v[176:179], v[50:53]
	v_mfma_f32_16x16x32_bf16 v[38:41], v[160:163], v[184:187], v[38:41]
	v_mfma_f32_16x16x32_bf16 v[34:37], v[168:171], v[184:187], v[34:37]
	v_mfma_f32_16x16x32_bf16 v[22:25], v[160:163], v[192:195], v[22:25]
	v_mfma_f32_16x16x32_bf16 v[18:21], v[168:171], v[192:195], v[18:21]
	v_mfma_f32_16x16x32_bf16 v[6:9], v[160:163], v[200:203], v[6:9]
	v_mfma_f32_16x16x32_bf16 v[2:5], v[168:171], v[200:203], v[2:5]
	s_setprio 0
	s_barrier
	s_add_i32 s67, 0, 0x18000
	v_add_u32_e32 v0, s67, v126
	s_add_i32 s70, 0, 0x1c000
	ds_read_b128 v[128:131], v0
	ds_read_b128 v[142:145], v0 offset:1024
	ds_read_b128 v[146:149], v0 offset:2048
	ds_read_b128 v[150:153], v0 offset:3072
	v_add_u32_e32 v0, s70, v126
	ds_read_b128 v[154:157], v0
	ds_read_b128 v[160:163], v0 offset:1024
	ds_read_b128 v[164:167], v0 offset:2048
	ds_read_b128 v[168:171], v0 offset:3072
	s_add_u32 s68, s16, 0x40000
	s_mov_b32 m0, s47
	ds_read_b128 v[172:175], v127 offset:32768
	ds_read_b128 v[176:179], v127 offset:33792
	ds_read_b128 v[180:183], v127 offset:34816
	ds_read_b128 v[184:187], v127 offset:35840
	ds_read_b128 v[188:191], v127 offset:36864
	ds_read_b128 v[192:195], v127 offset:37888
	ds_read_b128 v[196:199], v127 offset:38912
	ds_read_b128 v[200:203], v127 offset:39936
	s_addc_u32 s69, s17, 0
	s_nop 0
	global_load_lds_dwordx4 v122, s[68:69]
	s_mov_b32 m0, s48
	s_nop 0
	global_load_lds_dwordx4 v123, s[68:69]
	s_waitcnt vmcnt(8)
	s_waitcnt lgkmcnt(0)
	s_barrier
	s_setprio 1
	s_waitcnt lgkmcnt(0)
	v_mfma_f32_16x16x32_bf16 v[136:139], v[128:131], v[172:175], v[138:141]
	v_mfma_f32_16x16x32_bf16 v[132:135], v[146:149], v[172:175], v[132:135]
	v_mfma_f32_16x16x32_bf16 v[110:113], v[128:131], v[180:183], v[110:113]
	v_mfma_f32_16x16x32_bf16 v[106:109], v[146:149], v[180:183], v[106:109]
	v_mfma_f32_16x16x32_bf16 v[94:97], v[128:131], v[188:191], v[94:97]
	v_mfma_f32_16x16x32_bf16 v[90:93], v[146:149], v[188:191], v[90:93]
	v_mfma_f32_16x16x32_bf16 v[78:81], v[128:131], v[196:199], v[78:81]
	v_mfma_f32_16x16x32_bf16 v[74:77], v[146:149], v[196:199], v[74:77]
	v_mfma_f32_16x16x32_bf16 v[138:141], v[142:145], v[176:179], v[136:139]
	v_mfma_f32_16x16x32_bf16 v[134:137], v[150:153], v[176:179], v[132:135]
	v_mfma_f32_16x16x32_bf16 v[110:113], v[142:145], v[184:187], v[110:113]
	v_mfma_f32_16x16x32_bf16 v[106:109], v[150:153], v[184:187], v[106:109]
	v_mfma_f32_16x16x32_bf16 v[94:97], v[142:145], v[192:195], v[94:97]
	v_mfma_f32_16x16x32_bf16 v[90:93], v[150:153], v[192:195], v[90:93]
	v_mfma_f32_16x16x32_bf16 v[78:81], v[142:145], v[200:203], v[78:81]
	v_mfma_f32_16x16x32_bf16 v[74:77], v[150:153], v[200:203], v[74:77]
	s_setprio 0
	s_setprio 1
	v_mfma_f32_16x16x32_bf16 v[118:121], v[154:157], v[172:175], v[118:121]
	v_mfma_f32_16x16x32_bf16 v[114:117], v[164:167], v[172:175], v[114:117]
	v_mfma_f32_16x16x32_bf16 v[102:105], v[154:157], v[180:183], v[102:105]
	v_mfma_f32_16x16x32_bf16 v[98:101], v[164:167], v[180:183], v[98:101]
	v_mfma_f32_16x16x32_bf16 v[86:89], v[154:157], v[188:191], v[86:89]
	v_mfma_f32_16x16x32_bf16 v[82:85], v[164:167], v[188:191], v[82:85]
	v_mfma_f32_16x16x32_bf16 v[70:73], v[154:157], v[196:199], v[70:73]
	v_mfma_f32_16x16x32_bf16 v[66:69], v[164:167], v[196:199], v[66:69]
	v_mfma_f32_16x16x32_bf16 v[118:121], v[160:163], v[176:179], v[118:121]
	v_mfma_f32_16x16x32_bf16 v[114:117], v[168:171], v[176:179], v[114:117]
	v_mfma_f32_16x16x32_bf16 v[102:105], v[160:163], v[184:187], v[102:105]
	v_mfma_f32_16x16x32_bf16 v[98:101], v[168:171], v[184:187], v[98:101]
	v_mfma_f32_16x16x32_bf16 v[86:89], v[160:163], v[192:195], v[86:89]
	v_mfma_f32_16x16x32_bf16 v[82:85], v[168:171], v[192:195], v[82:85]
	v_mfma_f32_16x16x32_bf16 v[70:73], v[160:163], v[200:203], v[70:73]
	v_mfma_f32_16x16x32_bf16 v[66:69], v[168:171], v[200:203], v[66:69]
	s_setprio 0
	s_barrier
	ds_read_b128 v[172:175], v127 offset:49152
	ds_read_b128 v[176:179], v127 offset:50176
	ds_read_b128 v[180:183], v127 offset:51200
	ds_read_b128 v[184:187], v127 offset:52224
	ds_read_b128 v[188:191], v127 offset:53248
	ds_read_b128 v[192:195], v127 offset:54272
	ds_read_b128 v[196:199], v127 offset:55296
	ds_read_b128 v[200:203], v127 offset:56320
	s_add_i32 s67, s67, s42
	s_add_u32 s100, s22, s38
	s_addc_u32 s101, s23, s39
	s_mov_b32 m0, s67
	s_nop 0
	global_load_lds_dwordx4 v124, s[100:101]
	s_add_i32 m0, s67, 0x2000
	s_nop 0
	s_add_u32 s22, s22, 0x40080
	s_addc_u32 s23, s23, 0
	s_add_i32 s67, s70, s42
	global_load_lds_dwordx4 v125, s[100:101]
	s_mov_b32 m0, s67
	s_nop 0
	global_load_lds_dwordx4 v124, s[22:23]
	s_add_i32 m0, s67, 0x2000
	s_nop 0
	global_load_lds_dwordx4 v125, s[22:23]
	s_mov_b32 m0, s64
	s_add_u32 s100, s16, s38
	s_addc_u32 s101, s17, s39
	v_mov_b32_e32 v0, v123
	global_load_lds_dwordx4 v122, s[100:101]
	s_mov_b32 m0, s65
	s_nop 0
	global_load_lds_dwordx4 v123, s[100:101]
	s_waitcnt vmcnt(8)
	s_waitcnt lgkmcnt(0)
	s_barrier
	s_setprio 1
	s_waitcnt lgkmcnt(0)
	v_mfma_f32_16x16x32_bf16 v[62:65], v[128:131], v[172:175], v[62:65]
	v_mfma_f32_16x16x32_bf16 v[58:61], v[146:149], v[172:175], v[58:61]
	v_mfma_f32_16x16x32_bf16 v[46:49], v[128:131], v[180:183], v[46:49]
	v_mfma_f32_16x16x32_bf16 v[42:45], v[146:149], v[180:183], v[42:45]
	v_mfma_f32_16x16x32_bf16 v[30:33], v[128:131], v[188:191], v[30:33]
	v_mfma_f32_16x16x32_bf16 v[26:29], v[146:149], v[188:191], v[26:29]
	v_mfma_f32_16x16x32_bf16 v[14:17], v[128:131], v[196:199], v[14:17]
	v_mfma_f32_16x16x32_bf16 v[10:13], v[146:149], v[196:199], v[10:13]
	v_mfma_f32_16x16x32_bf16 v[62:65], v[142:145], v[176:179], v[62:65]
	v_mfma_f32_16x16x32_bf16 v[58:61], v[150:153], v[176:179], v[58:61]
	v_mfma_f32_16x16x32_bf16 v[46:49], v[142:145], v[184:187], v[46:49]
	v_mfma_f32_16x16x32_bf16 v[42:45], v[150:153], v[184:187], v[42:45]
	v_mfma_f32_16x16x32_bf16 v[30:33], v[142:145], v[192:195], v[30:33]
	v_mfma_f32_16x16x32_bf16 v[26:29], v[150:153], v[192:195], v[26:29]
	v_mfma_f32_16x16x32_bf16 v[14:17], v[142:145], v[200:203], v[14:17]
	v_mfma_f32_16x16x32_bf16 v[10:13], v[150:153], v[200:203], v[10:13]
	s_setprio 0
	s_setprio 1
	v_mfma_f32_16x16x32_bf16 v[54:57], v[154:157], v[172:175], v[54:57]
	v_mfma_f32_16x16x32_bf16 v[50:53], v[164:167], v[172:175], v[50:53]
	v_mfma_f32_16x16x32_bf16 v[38:41], v[154:157], v[180:183], v[38:41]
	v_mfma_f32_16x16x32_bf16 v[34:37], v[164:167], v[180:183], v[34:37]
	v_mfma_f32_16x16x32_bf16 v[22:25], v[154:157], v[188:191], v[22:25]
	v_mfma_f32_16x16x32_bf16 v[18:21], v[164:167], v[188:191], v[18:21]
	v_mfma_f32_16x16x32_bf16 v[6:9], v[154:157], v[196:199], v[6:9]
	v_mfma_f32_16x16x32_bf16 v[2:5], v[164:167], v[196:199], v[2:5]
	v_mfma_f32_16x16x32_bf16 v[54:57], v[160:163], v[176:179], v[54:57]
	v_mfma_f32_16x16x32_bf16 v[50:53], v[168:171], v[176:179], v[50:53]
	v_mfma_f32_16x16x32_bf16 v[38:41], v[160:163], v[184:187], v[38:41]
	v_mfma_f32_16x16x32_bf16 v[34:37], v[168:171], v[184:187], v[34:37]
	v_mfma_f32_16x16x32_bf16 v[22:25], v[160:163], v[192:195], v[22:25]
	v_mfma_f32_16x16x32_bf16 v[18:21], v[168:171], v[192:195], v[18:21]
	v_mfma_f32_16x16x32_bf16 v[6:9], v[160:163], v[200:203], v[6:9]
	v_mfma_f32_16x16x32_bf16 v[2:5], v[168:171], v[200:203], v[2:5]
	s_setprio 0
	s_barrier
	s_add_i32 s66, s66, 2
	s_add_u32 s14, s14, 0x100
	s_addc_u32 s15, s15, 0
	s_cmp_gt_u32 s66, 13
	s_cbranch_scc0 .LBB0_1807
	s_cmpk_lt_u32 s26, 0x100
	s_cbranch_scc0 .LBB0_1810
	s_barrier

.LBB0_1886:
	s_add_u32 s6, s4, 0xfffc0080
	s_addc_u32 s7, s5, -1
	s_add_i32 s47, 0, 0x10000
	s_cmp_eq_u32 s46, 12
	s_cselect_b32 s7, s3, s7
	s_cselect_b32 s6, s2, s6
	v_add_u32_e32 v0, s47, v127
	s_cselect_b32 s11, s40, s43
	s_cselect_b32 s10, s26, s37
	s_add_i32 s50, 0, 0x14000
	ds_read_b128 v[130:133], v0
	ds_read_b128 v[134:137], v0 offset:1024
	ds_read_b128 v[138:141], v0 offset:2048
	ds_read_b128 v[142:145], v0 offset:3072
	v_add_u32_e32 v0, s50, v127
	ds_read_b128 v[146:149], v0
	ds_read_b128 v[158:161], v0 offset:1024
	ds_read_b128 v[162:165], v0 offset:2048
	ds_read_b128 v[166:169], v0 offset:3072
	ds_read_b128 v[170:173], v128
	ds_read_b128 v[174:177], v128 offset:1024
	ds_read_b128 v[178:181], v128 offset:2048
	ds_read_b128 v[182:185], v128 offset:3072
	ds_read_b128 v[186:189], v128 offset:4096
	ds_read_b128 v[190:193], v128 offset:5120
	ds_read_b128 v[194:197], v128 offset:6144
	ds_read_b128 v[198:201], v128 offset:7168
	s_add_i32 m0, s17, 0xc000
	s_nop 0
	global_load_lds_dwordx4 v122, s[4:5]
	s_add_i32 m0, s17, 0xe000
	s_nop 0
	global_load_lds_dwordx4 v123, s[4:5]
	s_waitcnt vmcnt(8)
	s_waitcnt lgkmcnt(0)
	s_barrier
	s_setprio 1
	s_waitcnt lgkmcnt(0)
	v_mfma_f32_16x16x32_bf16 v[154:157], v[130:133], v[170:173], v[154:157]
	v_mfma_f32_16x16x32_bf16 v[150:153], v[138:141], v[170:173], v[150:153]
	v_mfma_f32_16x16x32_bf16 v[110:113], v[130:133], v[178:181], v[110:113]
	v_mfma_f32_16x16x32_bf16 v[106:109], v[138:141], v[178:181], v[106:109]
	v_mfma_f32_16x16x32_bf16 v[94:97], v[130:133], v[186:189], v[94:97]
	v_mfma_f32_16x16x32_bf16 v[90:93], v[138:141], v[186:189], v[90:93]
	v_mfma_f32_16x16x32_bf16 v[78:81], v[130:133], v[194:197], v[78:81]
	v_mfma_f32_16x16x32_bf16 v[74:77], v[138:141], v[194:197], v[74:77]
	v_mfma_f32_16x16x32_bf16 v[154:157], v[134:137], v[174:177], v[154:157]
	v_mfma_f32_16x16x32_bf16 v[150:153], v[142:145], v[174:177], v[150:153]
	v_mfma_f32_16x16x32_bf16 v[110:113], v[134:137], v[182:185], v[110:113]
	v_mfma_f32_16x16x32_bf16 v[106:109], v[142:145], v[182:185], v[106:109]
	v_mfma_f32_16x16x32_bf16 v[94:97], v[134:137], v[190:193], v[94:97]
	v_mfma_f32_16x16x32_bf16 v[90:93], v[142:145], v[190:193], v[90:93]
	v_mfma_f32_16x16x32_bf16 v[78:81], v[134:137], v[198:201], v[78:81]
	v_mfma_f32_16x16x32_bf16 v[74:77], v[142:145], v[198:201], v[74:77]
	s_setprio 0
	s_setprio 1
	v_mfma_f32_16x16x32_bf16 v[118:121], v[146:149], v[170:173], v[118:121]
	v_mfma_f32_16x16x32_bf16 v[114:117], v[162:165], v[170:173], v[114:117]
	v_mfma_f32_16x16x32_bf16 v[102:105], v[146:149], v[178:181], v[102:105]
	v_mfma_f32_16x16x32_bf16 v[98:101], v[162:165], v[178:181], v[98:101]
	v_mfma_f32_16x16x32_bf16 v[86:89], v[146:149], v[186:189], v[86:89]
	v_mfma_f32_16x16x32_bf16 v[82:85], v[162:165], v[186:189], v[82:85]
	v_mfma_f32_16x16x32_bf16 v[70:73], v[146:149], v[194:197], v[70:73]
	v_mfma_f32_16x16x32_bf16 v[66:69], v[162:165], v[194:197], v[66:69]
	v_mfma_f32_16x16x32_bf16 v[118:121], v[158:161], v[174:177], v[118:121]
	v_mfma_f32_16x16x32_bf16 v[114:117], v[166:169], v[174:177], v[114:117]
	v_mfma_f32_16x16x32_bf16 v[102:105], v[158:161], v[182:185], v[102:105]
	v_mfma_f32_16x16x32_bf16 v[98:101], v[166:169], v[182:185], v[98:101]
	v_mfma_f32_16x16x32_bf16 v[86:89], v[158:161], v[190:193], v[86:89]
	v_mfma_f32_16x16x32_bf16 v[82:85], v[166:169], v[190:193], v[82:85]
	v_mfma_f32_16x16x32_bf16 v[70:73], v[158:161], v[198:201], v[70:73]
	v_mfma_f32_16x16x32_bf16 v[66:69], v[166:169], v[198:201], v[66:69]
	s_setprio 0
	s_barrier
	s_add_i32 s47, s47, s16
	ds_read_b128 v[170:173], v128 offset:16384
	ds_read_b128 v[174:177], v128 offset:17408
	ds_read_b128 v[178:181], v128 offset:18432
	ds_read_b128 v[182:185], v128 offset:19456
	ds_read_b128 v[186:189], v128 offset:20480
	ds_read_b128 v[190:193], v128 offset:21504
	ds_read_b128 v[194:197], v128 offset:22528
	ds_read_b128 v[198:201], v128 offset:23552
	s_mov_b32 m0, s47
	s_nop 0
	global_load_lds_dwordx4 v125, s[10:11]
	s_add_i32 m0, s47, 0x2000
	s_add_u32 s48, s10, 0x40000
	global_load_lds_dwordx4 v126, s[10:11]
	s_addc_u32 s49, s11, 0
	s_add_i32 s47, s50, s16
	s_mov_b32 m0, s47
	s_nop 0
	global_load_lds_dwordx4 v125, s[48:49]
	s_add_i32 m0, s47, 0x2000
	s_nop 0
	global_load_lds_dwordx4 v126, s[48:49]
	s_mov_b32 m0, s17
	s_nop 0
	global_load_lds_dwordx4 v122, s[6:7]
	s_mov_b32 m0, s22
	s_nop 0
	global_load_lds_dwordx4 v123, s[6:7]
	s_waitcnt vmcnt(8)
	s_waitcnt lgkmcnt(0)
	s_barrier
	s_setprio 1
	s_waitcnt lgkmcnt(0)
	v_mfma_f32_16x16x32_bf16 v[62:65], v[130:133], v[170:173], v[62:65]
	v_mfma_f32_16x16x32_bf16 v[58:61], v[138:141], v[170:173], v[58:61]
	v_mfma_f32_16x16x32_bf16 v[46:49], v[130:133], v[178:181], v[46:49]
	v_mfma_f32_16x16x32_bf16 v[42:45], v[138:141], v[178:181], v[42:45]
	v_mfma_f32_16x16x32_bf16 v[30:33], v[130:133], v[186:189], v[30:33]
	v_mfma_f32_16x16x32_bf16 v[26:29], v[138:141], v[186:189], v[26:29]
	v_mfma_f32_16x16x32_bf16 v[14:17], v[130:133], v[194:197], v[14:17]
	v_mfma_f32_16x16x32_bf16 v[10:13], v[138:141], v[194:197], v[10:13]
	v_mfma_f32_16x16x32_bf16 v[62:65], v[134:137], v[174:177], v[62:65]
	v_mfma_f32_16x16x32_bf16 v[58:61], v[142:145], v[174:177], v[58:61]
	v_mfma_f32_16x16x32_bf16 v[46:49], v[134:137], v[182:185], v[46:49]
	v_mfma_f32_16x16x32_bf16 v[42:45], v[142:145], v[182:185], v[42:45]
	v_mfma_f32_16x16x32_bf16 v[30:33], v[134:137], v[190:193], v[30:33]
	v_mfma_f32_16x16x32_bf16 v[26:29], v[142:145], v[190:193], v[26:29]
	v_mfma_f32_16x16x32_bf16 v[14:17], v[134:137], v[198:201], v[14:17]
	v_mfma_f32_16x16x32_bf16 v[10:13], v[142:145], v[198:201], v[10:13]
	s_setprio 0
	s_setprio 1
	v_mfma_f32_16x16x32_bf16 v[54:57], v[146:149], v[170:173], v[54:57]
	v_mfma_f32_16x16x32_bf16 v[50:53], v[162:165], v[170:173], v[50:53]
	v_mfma_f32_16x16x32_bf16 v[38:41], v[146:149], v[178:181], v[38:41]
	v_mfma_f32_16x16x32_bf16 v[34:37], v[162:165], v[178:181], v[34:37]
	v_mfma_f32_16x16x32_bf16 v[22:25], v[146:149], v[186:189], v[22:25]
	v_mfma_f32_16x16x32_bf16 v[18:21], v[162:165], v[186:189], v[18:21]
	v_mfma_f32_16x16x32_bf16 v[6:9], v[146:149], v[194:197], v[6:9]
	v_mfma_f32_16x16x32_bf16 v[2:5], v[162:165], v[194:197], v[2:5]
	v_mfma_f32_16x16x32_bf16 v[54:57], v[158:161], v[174:177], v[54:57]
	v_mfma_f32_16x16x32_bf16 v[50:53], v[166:169], v[174:177], v[50:53]
	v_mfma_f32_16x16x32_bf16 v[38:41], v[158:161], v[182:185], v[38:41]
	v_mfma_f32_16x16x32_bf16 v[34:37], v[166:169], v[182:185], v[34:37]
	v_mfma_f32_16x16x32_bf16 v[22:25], v[158:161], v[190:193], v[22:25]
	v_mfma_f32_16x16x32_bf16 v[18:21], v[166:169], v[190:193], v[18:21]
	v_mfma_f32_16x16x32_bf16 v[6:9], v[158:161], v[198:201], v[6:9]
	v_mfma_f32_16x16x32_bf16 v[2:5], v[166:169], v[198:201], v[2:5]
	s_setprio 0
	s_barrier
	s_add_i32 s47, 0, 0x18000
	v_add_u32_e32 v0, s47, v127
	s_add_i32 s50, 0, 0x1c000
	ds_read_b128 v[130:133], v0
	ds_read_b128 v[134:137], v0 offset:1024
	ds_read_b128 v[138:141], v0 offset:2048
	ds_read_b128 v[142:145], v0 offset:3072
	v_add_u32_e32 v0, s50, v127
	ds_read_b128 v[146:149], v0
	ds_read_b128 v[158:161], v0 offset:1024
	ds_read_b128 v[162:165], v0 offset:2048
	ds_read_b128 v[166:169], v0 offset:3072
	s_add_u32 s48, s6, 0x40000
	s_mov_b32 m0, s23
	ds_read_b128 v[170:173], v128 offset:32768
	ds_read_b128 v[174:177], v128 offset:33792
	ds_read_b128 v[178:181], v128 offset:34816
	ds_read_b128 v[182:185], v128 offset:35840
	ds_read_b128 v[186:189], v128 offset:36864
	ds_read_b128 v[190:193], v128 offset:37888
	ds_read_b128 v[194:197], v128 offset:38912
	ds_read_b128 v[198:201], v128 offset:39936
	s_addc_u32 s49, s7, 0
	s_nop 0
	global_load_lds_dwordx4 v122, s[48:49]
	s_mov_b32 m0, s24
	s_nop 0
	global_load_lds_dwordx4 v123, s[48:49]
	s_waitcnt vmcnt(8)
	s_waitcnt lgkmcnt(0)
	s_barrier
	s_setprio 1
	s_waitcnt lgkmcnt(0)
	v_mfma_f32_16x16x32_bf16 v[154:157], v[130:133], v[170:173], v[154:157]
	v_mfma_f32_16x16x32_bf16 v[150:153], v[138:141], v[170:173], v[150:153]
	v_mfma_f32_16x16x32_bf16 v[110:113], v[130:133], v[178:181], v[110:113]
	v_mfma_f32_16x16x32_bf16 v[106:109], v[138:141], v[178:181], v[106:109]
	v_mfma_f32_16x16x32_bf16 v[94:97], v[130:133], v[186:189], v[94:97]
	v_mfma_f32_16x16x32_bf16 v[90:93], v[138:141], v[186:189], v[90:93]
	v_mfma_f32_16x16x32_bf16 v[78:81], v[130:133], v[194:197], v[78:81]
	v_mfma_f32_16x16x32_bf16 v[74:77], v[138:141], v[194:197], v[74:77]
	v_mfma_f32_16x16x32_bf16 v[154:157], v[134:137], v[174:177], v[154:157]
	v_mfma_f32_16x16x32_bf16 v[150:153], v[142:145], v[174:177], v[150:153]
	v_mfma_f32_16x16x32_bf16 v[110:113], v[134:137], v[182:185], v[110:113]
	v_mfma_f32_16x16x32_bf16 v[106:109], v[142:145], v[182:185], v[106:109]
	v_mfma_f32_16x16x32_bf16 v[94:97], v[134:137], v[190:193], v[94:97]
	v_mfma_f32_16x16x32_bf16 v[90:93], v[142:145], v[190:193], v[90:93]
	v_mfma_f32_16x16x32_bf16 v[78:81], v[134:137], v[198:201], v[78:81]
	v_mfma_f32_16x16x32_bf16 v[74:77], v[142:145], v[198:201], v[74:77]
	s_setprio 0
	s_setprio 1
	v_mfma_f32_16x16x32_bf16 v[118:121], v[146:149], v[170:173], v[118:121]
	v_mfma_f32_16x16x32_bf16 v[114:117], v[162:165], v[170:173], v[114:117]
	v_mfma_f32_16x16x32_bf16 v[102:105], v[146:149], v[178:181], v[102:105]
	v_mfma_f32_16x16x32_bf16 v[98:101], v[162:165], v[178:181], v[98:101]
	v_mfma_f32_16x16x32_bf16 v[86:89], v[146:149], v[186:189], v[86:89]
	v_mfma_f32_16x16x32_bf16 v[82:85], v[162:165], v[186:189], v[82:85]
	v_mfma_f32_16x16x32_bf16 v[70:73], v[146:149], v[194:197], v[70:73]
	v_mfma_f32_16x16x32_bf16 v[66:69], v[162:165], v[194:197], v[66:69]
	v_mfma_f32_16x16x32_bf16 v[118:121], v[158:161], v[174:177], v[118:121]
	v_mfma_f32_16x16x32_bf16 v[114:117], v[166:169], v[174:177], v[114:117]
	v_mfma_f32_16x16x32_bf16 v[102:105], v[158:161], v[182:185], v[102:105]
	v_mfma_f32_16x16x32_bf16 v[98:101], v[166:169], v[182:185], v[98:101]
	v_mfma_f32_16x16x32_bf16 v[86:89], v[158:161], v[190:193], v[86:89]
	v_mfma_f32_16x16x32_bf16 v[82:85], v[166:169], v[190:193], v[82:85]
	v_mfma_f32_16x16x32_bf16 v[70:73], v[158:161], v[198:201], v[70:73]
	v_mfma_f32_16x16x32_bf16 v[66:69], v[166:169], v[198:201], v[66:69]
	s_setprio 0
	s_barrier
	ds_read_b128 v[170:173], v128 offset:49152
	ds_read_b128 v[174:177], v128 offset:50176
	ds_read_b128 v[178:181], v128 offset:51200
	ds_read_b128 v[182:185], v128 offset:52224
	ds_read_b128 v[186:189], v128 offset:53248
	ds_read_b128 v[190:193], v128 offset:54272
	ds_read_b128 v[194:197], v128 offset:55296
	ds_read_b128 v[198:201], v128 offset:56320
	s_add_i32 s47, s47, s16
	s_add_u32 s100, s10, s38
	s_addc_u32 s101, s11, s39
	s_mov_b32 m0, s47
	s_nop 0
	global_load_lds_dwordx4 v125, s[100:101]
	s_add_i32 m0, s47, 0x2000
	s_nop 0
	s_add_u32 s10, s10, 0x40080
	s_addc_u32 s11, s11, 0
	s_add_i32 s47, s50, s16
	global_load_lds_dwordx4 v126, s[100:101]
	s_mov_b32 m0, s47
	s_nop 0
	global_load_lds_dwordx4 v125, s[10:11]
	s_add_i32 m0, s47, 0x2000
	s_nop 0
	global_load_lds_dwordx4 v126, s[10:11]
	s_mov_b32 m0, s41
	s_add_u32 s100, s6, s38
	s_addc_u32 s101, s7, s39
	v_mov_b32_e32 v0, v123
	global_load_lds_dwordx4 v122, s[100:101]
	s_mov_b32 m0, s42
	s_nop 0
	global_load_lds_dwordx4 v123, s[100:101]
	s_waitcnt vmcnt(8)
	s_waitcnt lgkmcnt(0)
	s_barrier
	s_setprio 1
	s_waitcnt lgkmcnt(0)
	v_mfma_f32_16x16x32_bf16 v[62:65], v[130:133], v[170:173], v[62:65]
	v_mfma_f32_16x16x32_bf16 v[58:61], v[138:141], v[170:173], v[58:61]
	v_mfma_f32_16x16x32_bf16 v[46:49], v[130:133], v[178:181], v[46:49]
	v_mfma_f32_16x16x32_bf16 v[42:45], v[138:141], v[178:181], v[42:45]
	v_mfma_f32_16x16x32_bf16 v[30:33], v[130:133], v[186:189], v[30:33]
	v_mfma_f32_16x16x32_bf16 v[26:29], v[138:141], v[186:189], v[26:29]
	v_mfma_f32_16x16x32_bf16 v[14:17], v[130:133], v[194:197], v[14:17]
	v_mfma_f32_16x16x32_bf16 v[10:13], v[138:141], v[194:197], v[10:13]
	v_mfma_f32_16x16x32_bf16 v[62:65], v[134:137], v[174:177], v[62:65]
	v_mfma_f32_16x16x32_bf16 v[58:61], v[142:145], v[174:177], v[58:61]
	v_mfma_f32_16x16x32_bf16 v[46:49], v[134:137], v[182:185], v[46:49]
	v_mfma_f32_16x16x32_bf16 v[42:45], v[142:145], v[182:185], v[42:45]
	v_mfma_f32_16x16x32_bf16 v[30:33], v[134:137], v[190:193], v[30:33]
	v_mfma_f32_16x16x32_bf16 v[26:29], v[142:145], v[190:193], v[26:29]
	v_mfma_f32_16x16x32_bf16 v[14:17], v[134:137], v[198:201], v[14:17]
	v_mfma_f32_16x16x32_bf16 v[10:13], v[142:145], v[198:201], v[10:13]
	s_setprio 0
	s_setprio 1
	v_mfma_f32_16x16x32_bf16 v[54:57], v[146:149], v[170:173], v[54:57]
	v_mfma_f32_16x16x32_bf16 v[50:53], v[162:165], v[170:173], v[50:53]
	v_mfma_f32_16x16x32_bf16 v[38:41], v[146:149], v[178:181], v[38:41]
	v_mfma_f32_16x16x32_bf16 v[34:37], v[162:165], v[178:181], v[34:37]
	v_mfma_f32_16x16x32_bf16 v[22:25], v[146:149], v[186:189], v[22:25]
	v_mfma_f32_16x16x32_bf16 v[18:21], v[162:165], v[186:189], v[18:21]
	v_mfma_f32_16x16x32_bf16 v[6:9], v[146:149], v[194:197], v[6:9]
	v_mfma_f32_16x16x32_bf16 v[2:5], v[162:165], v[194:197], v[2:5]
	v_mfma_f32_16x16x32_bf16 v[54:57], v[158:161], v[174:177], v[54:57]
	v_mfma_f32_16x16x32_bf16 v[50:53], v[166:169], v[174:177], v[50:53]
	v_mfma_f32_16x16x32_bf16 v[38:41], v[158:161], v[182:185], v[38:41]
	v_mfma_f32_16x16x32_bf16 v[34:37], v[166:169], v[182:185], v[34:37]
	v_mfma_f32_16x16x32_bf16 v[22:25], v[158:161], v[190:193], v[22:25]
	v_mfma_f32_16x16x32_bf16 v[18:21], v[166:169], v[190:193], v[18:21]
	v_mfma_f32_16x16x32_bf16 v[6:9], v[158:161], v[198:201], v[6:9]
	v_mfma_f32_16x16x32_bf16 v[2:5], v[166:169], v[198:201], v[2:5]
	s_setprio 0
	s_barrier
	s_add_i32 s46, s46, 2
	s_add_u32 s4, s4, 0x100
	s_addc_u32 s5, s5, 0
	s_add_u32 s37, s37, 0x100
	s_addc_u32 s43, s43, 0
	s_cmp_gt_u32 s46, 13
	s_cbranch_scc0 .LBB0_1886
	s_cmpk_lt_u32 s14, 0x100
	s_cbranch_scc0 .LBB0_1889
	s_barrier
